# GEMM unit end: leading half issues its epilogue loads before taking the ALIGN barrier (barrier moved to just before vmcnt wait)
# speedup vs baseline: 1.0105x; 1.0012x over previous
.LBB0_208:
	v_lshl_or_b32 v132, s51, 8, v228
	v_ashrrev_i32_e32 v133, 31, v132
	v_readlane_b32 s16, v255, 6
	v_lshlrev_b64 v[136:137], 2, v[132:133]
	v_readlane_b32 s17, v255, 7
	v_lshl_add_u32 v246, s72, 8, v226
	v_lshl_add_u64 v[150:151], s[12:13], 0, v[136:137]
	v_lshl_add_u64 v[148:149], s[16:17], 0, v[136:137]
	v_ashrrev_i32_e32 v247, 31, v246
	global_load_dwordx4 v[132:135], v[148:149], off
	global_load_dwordx4 v[136:139], v[150:151], off
	global_load_dwordx4 v[140:143], v[148:149], off offset:16
	global_load_dwordx4 v[144:147], v[150:151], off offset:16
	global_load_dwordx4 v[166:169], v[148:149], off offset:512
	global_load_dwordx4 v[170:173], v[150:151], off offset:512
	global_load_dwordx4 v[184:187], v[148:149], off offset:528
	global_load_dwordx4 v[188:191], v[150:151], off offset:528
	v_lshl_add_u64 v[148:149], v[246:247], 4, s[14:15]
	global_load_dwordx4 v[210:213], v[148:149], off
	v_or_b32_e32 v224, 16, v246
	v_or_b32_e32 v222, 32, v246
	v_or_b32_e32 v220, 48, v246
	v_ashrrev_i32_e32 v225, 31, v224
	v_ashrrev_i32_e32 v223, 31, v222
	v_ashrrev_i32_e32 v221, 31, v220
	v_lshl_add_u64 v[148:149], v[224:225], 4, s[14:15]
	v_lshl_add_u64 v[150:151], v[222:223], 4, s[14:15]
	v_lshl_add_u64 v[192:193], v[220:221], 4, s[14:15]
	global_load_dwordx4 v[242:245], v[148:149], off
	global_load_dwordx4 v[152:155], v[150:151], off
	s_nop 0
	global_load_dwordx4 v[148:151], v[192:193], off
	s_brev_b32 s16, 44
	v_add_u32_e32 v218, 0x80, v246
	v_add_u32_e32 v216, 0x90, v246
	v_ashrrev_i32_e32 v219, 31, v218
	v_ashrrev_i32_e32 v217, 31, v216
	v_lshl_add_u64 v[208:209], v[218:219], 4, s[14:15]
	v_add_u32_e32 v214, 0xa0, v246
	v_ashrrev_i32_e32 v215, 31, v214
	s_movk_i32 s23, 0x2c00
	s_andn2_b64 vcc, exec, s[36:37]
	s_mov_b64 s[28:29], -1
	s_movk_i32 s74, 0x6000
	s_and_b64 s[100:101], exec, s[18:19]
	s_cbranch_scc0 .Lalign_205
	s_barrier
.Lalign_205:
	s_waitcnt vmcnt(0)
	v_cvt_f32_i32_e32 v137, v137
	v_cvt_f32_i32_e32 v136, v136
	v_cvt_f32_i32_e32 v139, v139
	v_cvt_f32_i32_e32 v138, v138
	v_cvt_f32_i32_e32 v141, v141
	v_cvt_f32_i32_e32 v133, v133
	v_cvt_f32_i32_e32 v132, v132
	v_cvt_f32_i32_e32 v135, v135
	v_cvt_f32_i32_e32 v183, v211
	v_cvt_f32_i32_e32 v182, v213
	v_cvt_f32_u32_e32 v211, v210
	v_cvt_f32_u32_e32 v210, v212
	v_cvt_f32_i32_e32 v134, v134
	v_cvt_f32_i32_e32 v140, v140
	v_cvt_f32_i32_e32 v143, v143
	v_pk_fma_f32 v[182:183], v[182:183], s[30:31], v[210:211] op_sel_hi:[1,0,1]
	v_cvt_f32_i32_e32 v142, v142
	v_pk_mul_f32 v[182:183], v[182:183], s[90:91] op_sel_hi:[1,0]
	v_cvt_f32_i32_e32 v145, v145
	v_pk_mul_f32 v[182:183], v[182:183], s[92:93] op_sel_hi:[1,0]
	v_cvt_f32_i32_e32 v144, v144
	v_fma_f32 v174, -v183, v183, v182
	v_max_f32_e32 v174, 0, v174
	v_cvt_f32_i32_e32 v147, v147
	v_cvt_f32_i32_e32 v146, v146
	v_cvt_f32_i32_e32 v167, v167
	v_cvt_f32_i32_e32 v166, v166
	v_cvt_f32_i32_e32 v169, v169
	v_cvt_f32_i32_e32 v168, v168
	v_cvt_f32_i32_e32 v171, v171
	v_cvt_f32_i32_e32 v170, v170
	v_cvt_f32_i32_e32 v193, v173
	v_cvt_f32_i32_e32 v192, v172
	v_cvt_f32_i32_e32 v197, v185
	v_cvt_f32_i32_e32 v196, v184
	v_cvt_f32_i32_e32 v199, v187
	v_cvt_f32_i32_e32 v198, v186
	v_cvt_f32_i32_e32 v189, v189
	v_cvt_f32_i32_e32 v188, v188
	v_cvt_f32_i32_e32 v201, v191
	v_cvt_f32_i32_e32 v200, v190
	v_add_f32_e32 v174, 0x3727c5ac, v174
	v_rsq_f32_e32 v174, v174
	v_pk_mul_f32 v[186:187], v[134:135], s[16:17] op_sel_hi:[1,0]
	v_pk_mul_f32 v[194:195], v[132:133], s[16:17] op_sel_hi:[1,0]
	v_pk_mul_f32 v[132:133], v[138:139], s[16:17] op_sel_hi:[1,0]
	v_pk_mul_f32 v[134:135], v[136:137], s[16:17] op_sel_hi:[1,0]
	v_pk_mul_f32 v[172:173], v[142:143], s[16:17] op_sel_hi:[1,0]
	v_pk_mul_f32 v[190:191], v[140:141], s[16:17] op_sel_hi:[1,0]
	v_pk_mul_f32 v[136:137], v[146:147], s[16:17] op_sel_hi:[1,0]
	v_pk_mul_f32 v[138:139], v[144:145], s[16:17] op_sel_hi:[1,0]
	v_pk_mul_f32 v[168:169], v[168:169], s[16:17] op_sel_hi:[1,0]
	v_pk_mul_f32 v[184:185], v[166:167], s[16:17] op_sel_hi:[1,0]
	v_pk_mul_f32 v[140:141], v[192:193], s[16:17] op_sel_hi:[1,0]
	v_pk_mul_f32 v[142:143], v[170:171], s[16:17] op_sel_hi:[1,0]
	v_pk_mul_f32 v[166:167], v[198:199], s[16:17] op_sel_hi:[1,0]
	v_pk_mul_f32 v[170:171], v[196:197], s[16:17] op_sel_hi:[1,0]
	v_pk_mul_f32 v[144:145], v[200:201], s[16:17] op_sel_hi:[1,0]
	v_pk_mul_f32 v[146:147], v[188:189], s[16:17] op_sel_hi:[1,0]
	s_mov_b32 s16, 0xbfb8aa3b
	v_pk_mul_f32 v[204:205], v[134:135], s[16:17] op_sel_hi:[1,0]
	v_pk_mul_f32 v[206:207], v[132:133], s[16:17] op_sel_hi:[1,0]
	v_pk_mul_f32 v[200:201], v[138:139], s[16:17] op_sel_hi:[1,0]
	v_pk_mul_f32 v[202:203], v[136:137], s[16:17] op_sel_hi:[1,0]
	s_mov_b32 s16, 0xbf317218
	v_mul_f32_e32 v248, 0xbfb8aa3b, v174
	v_pk_fma_f32 v[128:129], v[194:195], v[182:183], v[128:129] op_sel:[0,1,0] neg_lo:[1,0,0] neg_hi:[1,0,0]
	v_pk_mul_f32 v[196:197], v[142:143], s[16:17] op_sel_hi:[1,0]
	v_pk_mul_f32 v[198:199], v[140:141], s[16:17] op_sel_hi:[1,0]
	v_mul_f32_e32 v174, 0xbf317218, v174
	v_pk_fma_f32 v[128:129], v[128:129], v[248:249], v[204:205] op_sel_hi:[1,0,1]
	v_pk_fma_f32 v[120:121], v[184:185], v[182:183], v[120:121] op_sel:[0,1,0] neg_lo:[1,0,0] neg_hi:[1,0,0]
	v_pk_fma_f32 v[122:123], v[168:169], v[182:183], v[122:123] op_sel:[0,1,0] neg_lo:[1,0,0] neg_hi:[1,0,0]
	v_pk_fma_f32 v[120:121], v[120:121], v[174:175], v[196:197] op_sel_hi:[1,0,1]
	v_pk_fma_f32 v[122:123], v[122:123], v[174:175], v[198:199] op_sel_hi:[1,0,1]
	v_exp_f32_e32 v175, v128
	v_pk_mul_f32 v[188:189], v[146:147], s[16:17] op_sel_hi:[1,0]
	v_pk_mul_f32 v[192:193], v[144:145], s[16:17] op_sel_hi:[1,0]
	v_pk_fma_f32 v[116:117], v[170:171], v[182:183], v[116:117] op_sel:[0,1,0] neg_lo:[1,0,0] neg_hi:[1,0,0]
	v_pk_fma_f32 v[118:119], v[166:167], v[182:183], v[118:119] op_sel:[0,1,0] neg_lo:[1,0,0] neg_hi:[1,0,0]
	v_pk_fma_f32 v[130:131], v[186:187], v[182:183], v[130:131] op_sel:[0,1,0] neg_lo:[1,0,0] neg_hi:[1,0,0]
	v_pk_fma_f32 v[124:125], v[190:191], v[182:183], v[124:125] op_sel:[0,1,0] neg_lo:[1,0,0] neg_hi:[1,0,0]
	v_pk_fma_f32 v[126:127], v[172:173], v[182:183], v[126:127] op_sel:[0,1,0] neg_lo:[1,0,0] neg_hi:[1,0,0]
	v_pk_fma_f32 v[182:183], v[118:119], v[174:175], v[192:193] op_sel_hi:[1,0,1]
	v_pk_fma_f32 v[118:119], v[116:117], v[174:175], v[188:189] op_sel_hi:[1,0,1]
	v_exp_f32_e32 v116, v129
	v_add_f32_e32 v117, 1.0, v175
	v_rcp_f32_e32 v117, v117
	v_pk_fma_f32 v[130:131], v[130:131], v[248:249], v[206:207] op_sel_hi:[1,0,1]
	v_add_f32_e32 v116, 1.0, v116
	v_rcp_f32_e32 v116, v116
	v_mul_f32_e32 v120, v128, v120
	v_mul_f32_e32 v117, v120, v117
	v_mul_f32_e32 v120, v129, v121
	v_exp_f32_e32 v121, v130
	v_lshl_add_u64 v[132:133], v[216:217], 4, s[14:15]
	global_load_dwordx4 v[144:147], v[208:209], off
	global_load_dwordx4 v[140:143], v[132:133], off
	v_add_u32_e32 v208, 0xb0, v246
	v_mul_f32_e32 v116, v120, v116
	v_exp_f32_e32 v120, v131
	v_ashrrev_i32_e32 v209, 31, v208
	v_lshl_add_u64 v[132:133], v[214:215], 4, s[14:15]
	v_lshl_add_u64 v[134:135], v[208:209], 4, s[14:15]
	global_load_dwordx4 v[136:139], v[132:133], off
	s_nop 0
	global_load_dwordx4 v[132:135], v[134:135], off
	v_cvt_pk_bf16_f32 v116, v117, v116
	v_add_f32_e32 v117, 1.0, v121
	v_rcp_f32_e32 v117, v117
	v_add_f32_e32 v120, 1.0, v120
	v_rcp_f32_e32 v120, v120
	v_mul_f32_e32 v121, v130, v122
	v_mul_f32_e32 v117, v121, v117
	v_mul_f32_e32 v121, v131, v123
	v_pk_fma_f32 v[124:125], v[124:125], v[248:249], v[200:201] op_sel_hi:[1,0,1]
	v_mul_f32_e32 v120, v121, v120
	v_exp_f32_e32 v121, v124
	v_cvt_pk_bf16_f32 v117, v117, v120
	v_exp_f32_e32 v120, v125
	v_pk_fma_f32 v[126:127], v[126:127], v[248:249], v[202:203] op_sel_hi:[1,0,1]
	v_add_f32_e32 v121, 1.0, v121
	v_rcp_f32_e32 v121, v121
	v_add_f32_e32 v120, 1.0, v120
	v_rcp_f32_e32 v120, v120
	v_exp_f32_e32 v122, v126
	v_mul_f32_e32 v118, v124, v118
	v_mul_f32_e32 v119, v125, v119
	v_mul_f32_e32 v118, v118, v121
	v_mul_f32_e32 v119, v119, v120
	v_cvt_pk_bf16_f32 v118, v118, v119
	v_exp_f32_e32 v119, v127
	v_add_f32_e32 v120, 1.0, v122
	v_rcp_f32_e32 v120, v120
	v_mul_f32_e32 v121, v126, v182
	v_add_f32_e32 v119, 1.0, v119
	v_rcp_f32_e32 v119, v119
	v_lshl_or_b32 v212, s51, 7, v228
	v_mul_f32_e32 v124, v121, v120
	v_cvt_f32_i32_e32 v121, v243
	v_cvt_f32_i32_e32 v120, v245
	v_cvt_f32_u32_e32 v123, v242
	v_cvt_f32_u32_e32 v122, v244
	v_ashrrev_i32_e32 v213, 31, v212
	v_mov_b64_e32 v[210:211], s[70:71]
	v_mad_i64_i32 v[246:247], s[16:17], v246, s23, v[210:211]
	v_lshlrev_b64 v[212:213], 1, v[212:213]
	v_mul_f32_e32 v125, v127, v183
	v_lshl_add_u64 v[246:247], v[246:247], 0, v[212:213]
	v_mul_f32_e32 v119, v125, v119
	v_cvt_pk_bf16_f32 v119, v124, v119
	global_store_dwordx4 v[246:247], v[116:119], off
	v_mov_b32_e32 v247, v176
	s_nop 0
	v_pk_fma_f32 v[116:117], v[120:121], s[30:31], v[122:123] op_sel_hi:[1,0,1]
	s_nop 0
	v_pk_mul_f32 v[116:117], v[116:117], s[90:91] op_sel_hi:[1,0]
	s_nop 0
	v_pk_mul_f32 v[116:117], v[116:117], s[92:93] op_sel_hi:[1,0]
	s_nop 0
	v_fma_f32 v118, -v117, v117, v116
	v_max_f32_e32 v118, 0, v118
	v_add_f32_e32 v118, 0x3727c5ac, v118
	v_rsq_f32_e32 v121, v118
	v_pk_fma_f32 v[112:113], v[194:195], v[116:117], v[112:113] op_sel:[0,1,0] neg_lo:[1,0,0] neg_hi:[1,0,0]
	v_pk_fma_f32 v[114:115], v[186:187], v[116:117], v[114:115] op_sel:[0,1,0] neg_lo:[1,0,0] neg_hi:[1,0,0]
	v_pk_fma_f32 v[108:109], v[190:191], v[116:117], v[108:109] op_sel:[0,1,0] neg_lo:[1,0,0] neg_hi:[1,0,0]
	v_mul_f32_e32 v120, 0xbfb8aa3b, v121
	v_pk_fma_f32 v[112:113], v[112:113], v[120:121], v[204:205] op_sel_hi:[1,0,1]
	v_pk_fma_f32 v[110:111], v[172:173], v[116:117], v[110:111] op_sel:[0,1,0] neg_lo:[1,0,0] neg_hi:[1,0,0]
	v_mul_f32_e32 v122, 0xbf317218, v121
	v_pk_fma_f32 v[114:115], v[114:115], v[120:121], v[206:207] op_sel_hi:[1,0,1]
	v_pk_fma_f32 v[110:111], v[110:111], v[120:121], v[202:203] op_sel_hi:[1,0,1]
	v_pk_fma_f32 v[108:109], v[108:109], v[120:121], v[200:201] op_sel_hi:[1,0,1]
	v_pk_fma_f32 v[100:101], v[170:171], v[116:117], v[100:101] op_sel:[0,1,0] neg_lo:[1,0,0] neg_hi:[1,0,0]
	v_pk_fma_f32 v[102:103], v[166:167], v[116:117], v[102:103] op_sel:[0,1,0] neg_lo:[1,0,0] neg_hi:[1,0,0]
	v_exp_f32_e32 v120, v112
	v_pk_fma_f32 v[104:105], v[184:185], v[116:117], v[104:105] op_sel:[0,1,0] neg_lo:[1,0,0] neg_hi:[1,0,0]
	v_pk_fma_f32 v[106:107], v[168:169], v[116:117], v[106:107] op_sel:[0,1,0] neg_lo:[1,0,0] neg_hi:[1,0,0]
	v_pk_fma_f32 v[116:117], v[102:103], v[122:123], v[192:193] op_sel_hi:[1,0,1]
	v_pk_fma_f32 v[102:103], v[100:101], v[122:123], v[188:189] op_sel_hi:[1,0,1]
	v_exp_f32_e32 v100, v113
	v_add_f32_e32 v101, 1.0, v120
	v_rcp_f32_e32 v101, v101
	v_pk_fma_f32 v[104:105], v[104:105], v[122:123], v[196:197] op_sel_hi:[1,0,1]
	v_add_f32_e32 v100, 1.0, v100
	v_rcp_f32_e32 v100, v100
	v_mul_f32_e32 v104, v112, v104
	v_mul_f32_e32 v101, v104, v101
	v_mul_f32_e32 v104, v113, v105
	v_exp_f32_e32 v105, v114
	v_mul_f32_e32 v100, v104, v100
	v_exp_f32_e32 v104, v115
	v_cvt_pk_bf16_f32 v100, v101, v100
	v_add_f32_e32 v101, 1.0, v105
	v_rcp_f32_e32 v101, v101
	v_add_f32_e32 v104, 1.0, v104
	v_rcp_f32_e32 v104, v104
	v_pk_fma_f32 v[106:107], v[106:107], v[122:123], v[198:199] op_sel_hi:[1,0,1]
	v_mul_f32_e32 v102, v108, v102
	v_mul_f32_e32 v105, v114, v106
	v_mul_f32_e32 v101, v105, v101
	v_mul_f32_e32 v105, v115, v107
	v_mul_f32_e32 v104, v105, v104
	v_exp_f32_e32 v105, v108
	v_cvt_pk_bf16_f32 v101, v101, v104
	v_exp_f32_e32 v104, v109
	v_exp_f32_e32 v106, v110
	v_add_f32_e32 v105, 1.0, v105
	v_rcp_f32_e32 v105, v105
	v_add_f32_e32 v104, 1.0, v104
	v_rcp_f32_e32 v104, v104
	v_mul_f32_e32 v103, v109, v103
	v_mul_f32_e32 v102, v102, v105
	v_mul_f32_e32 v105, v110, v116
	v_mul_f32_e32 v103, v103, v104
	v_cvt_pk_bf16_f32 v102, v102, v103
	v_exp_f32_e32 v103, v111
	v_add_f32_e32 v104, 1.0, v106
	v_rcp_f32_e32 v104, v104
	v_cvt_f32_u32_e32 v107, v152
	v_add_f32_e32 v103, 1.0, v103
	v_rcp_f32_e32 v103, v103
	v_mul_f32_e32 v108, v105, v104
	v_cvt_f32_i32_e32 v105, v153
	v_cvt_f32_i32_e32 v104, v155
	v_cvt_f32_u32_e32 v106, v154
	v_mad_i64_i32 v[118:119], s[16:17], v224, s23, v[210:211]
	v_mul_f32_e32 v109, v111, v117
	v_lshl_add_u64 v[118:119], v[118:119], 0, v[212:213]
	v_mul_f32_e32 v103, v109, v103
	v_cvt_pk_bf16_f32 v103, v108, v103
	global_store_dwordx4 v[118:119], v[100:103], off
	s_nop 1
	v_pk_fma_f32 v[100:101], v[104:105], s[30:31], v[106:107] op_sel_hi:[1,0,1]
	s_nop 0
	v_pk_mul_f32 v[100:101], v[100:101], s[90:91] op_sel_hi:[1,0]
	s_nop 0
	v_pk_mul_f32 v[100:101], v[100:101], s[92:93] op_sel_hi:[1,0]
	s_nop 0
	v_fma_f32 v102, -v101, v101, v100
	v_max_f32_e32 v102, 0, v102
	v_add_f32_e32 v102, 0x3727c5ac, v102
	v_rsq_f32_e32 v105, v102
	v_pk_fma_f32 v[96:97], v[194:195], v[100:101], v[96:97] op_sel:[0,1,0] neg_lo:[1,0,0] neg_hi:[1,0,0]
	v_pk_fma_f32 v[98:99], v[186:187], v[100:101], v[98:99] op_sel:[0,1,0] neg_lo:[1,0,0] neg_hi:[1,0,0]
	v_pk_fma_f32 v[92:93], v[190:191], v[100:101], v[92:93] op_sel:[0,1,0] neg_lo:[1,0,0] neg_hi:[1,0,0]
	v_mul_f32_e32 v104, 0xbfb8aa3b, v105
	v_pk_fma_f32 v[96:97], v[96:97], v[104:105], v[204:205] op_sel_hi:[1,0,1]
	v_pk_fma_f32 v[94:95], v[172:173], v[100:101], v[94:95] op_sel:[0,1,0] neg_lo:[1,0,0] neg_hi:[1,0,0]
	v_mul_f32_e32 v106, 0xbf317218, v105
	v_pk_fma_f32 v[98:99], v[98:99], v[104:105], v[206:207] op_sel_hi:[1,0,1]
	v_pk_fma_f32 v[94:95], v[94:95], v[104:105], v[202:203] op_sel_hi:[1,0,1]
	v_pk_fma_f32 v[92:93], v[92:93], v[104:105], v[200:201] op_sel_hi:[1,0,1]
	v_pk_fma_f32 v[84:85], v[170:171], v[100:101], v[84:85] op_sel:[0,1,0] neg_lo:[1,0,0] neg_hi:[1,0,0]
	v_pk_fma_f32 v[86:87], v[166:167], v[100:101], v[86:87] op_sel:[0,1,0] neg_lo:[1,0,0] neg_hi:[1,0,0]
	v_exp_f32_e32 v104, v96
	v_pk_fma_f32 v[88:89], v[184:185], v[100:101], v[88:89] op_sel:[0,1,0] neg_lo:[1,0,0] neg_hi:[1,0,0]
	v_pk_fma_f32 v[90:91], v[168:169], v[100:101], v[90:91] op_sel:[0,1,0] neg_lo:[1,0,0] neg_hi:[1,0,0]
	v_pk_fma_f32 v[100:101], v[86:87], v[106:107], v[192:193] op_sel_hi:[1,0,1]
	v_pk_fma_f32 v[86:87], v[84:85], v[106:107], v[188:189] op_sel_hi:[1,0,1]
	v_exp_f32_e32 v84, v97
	v_add_f32_e32 v85, 1.0, v104
	v_rcp_f32_e32 v85, v85
	v_pk_fma_f32 v[88:89], v[88:89], v[106:107], v[196:197] op_sel_hi:[1,0,1]
	v_add_f32_e32 v84, 1.0, v84
	v_rcp_f32_e32 v84, v84
	v_mul_f32_e32 v88, v96, v88
	v_mul_f32_e32 v85, v88, v85
	v_mul_f32_e32 v88, v97, v89
	v_exp_f32_e32 v89, v98
	v_mul_f32_e32 v84, v88, v84
	v_exp_f32_e32 v88, v99
	v_cvt_pk_bf16_f32 v84, v85, v84
	v_add_f32_e32 v85, 1.0, v89
	v_rcp_f32_e32 v85, v85
	v_add_f32_e32 v88, 1.0, v88
	v_rcp_f32_e32 v88, v88
	v_pk_fma_f32 v[90:91], v[90:91], v[106:107], v[198:199] op_sel_hi:[1,0,1]
	v_mul_f32_e32 v86, v92, v86
	v_mul_f32_e32 v89, v98, v90
	v_mul_f32_e32 v85, v89, v85
	v_mul_f32_e32 v89, v99, v91
	v_mul_f32_e32 v88, v89, v88
	v_exp_f32_e32 v89, v92
	v_cvt_pk_bf16_f32 v85, v85, v88
	v_exp_f32_e32 v88, v93
	v_exp_f32_e32 v90, v94
	v_add_f32_e32 v89, 1.0, v89
	v_rcp_f32_e32 v89, v89
	v_add_f32_e32 v88, 1.0, v88
	v_rcp_f32_e32 v88, v88
	v_mul_f32_e32 v87, v93, v87
	v_mul_f32_e32 v86, v86, v89
	v_mul_f32_e32 v89, v94, v100
	v_mul_f32_e32 v87, v87, v88
	v_cvt_pk_bf16_f32 v86, v86, v87
	v_exp_f32_e32 v87, v95
	v_add_f32_e32 v88, 1.0, v90
	v_rcp_f32_e32 v88, v88
	v_cvt_f32_u32_e32 v91, v148
	v_add_f32_e32 v87, 1.0, v87
	v_rcp_f32_e32 v87, v87
	v_mul_f32_e32 v92, v89, v88
	v_cvt_f32_i32_e32 v89, v149
	v_cvt_f32_i32_e32 v88, v151
	v_cvt_f32_u32_e32 v90, v150
	v_mad_i64_i32 v[102:103], s[16:17], v222, s23, v[210:211]
	v_mul_f32_e32 v93, v95, v101
	v_lshl_add_u64 v[102:103], v[102:103], 0, v[212:213]
	v_mul_f32_e32 v87, v93, v87
	v_cvt_pk_bf16_f32 v87, v92, v87
	global_store_dwordx4 v[102:103], v[84:87], off
	s_nop 1
	v_pk_fma_f32 v[84:85], v[88:89], s[30:31], v[90:91] op_sel_hi:[1,0,1]
	s_nop 0
	v_pk_mul_f32 v[84:85], v[84:85], s[90:91] op_sel_hi:[1,0]
	s_nop 0
	v_pk_mul_f32 v[84:85], v[84:85], s[92:93] op_sel_hi:[1,0]
	s_nop 0
	v_fma_f32 v86, -v85, v85, v84
	v_max_f32_e32 v86, 0, v86
	v_add_f32_e32 v86, 0x3727c5ac, v86
	v_rsq_f32_e32 v89, v86
	v_pk_fma_f32 v[80:81], v[194:195], v[84:85], v[80:81] op_sel:[0,1,0] neg_lo:[1,0,0] neg_hi:[1,0,0]
	v_pk_fma_f32 v[82:83], v[186:187], v[84:85], v[82:83] op_sel:[0,1,0] neg_lo:[1,0,0] neg_hi:[1,0,0]
	v_pk_fma_f32 v[76:77], v[190:191], v[84:85], v[76:77] op_sel:[0,1,0] neg_lo:[1,0,0] neg_hi:[1,0,0]
	v_mul_f32_e32 v88, 0xbfb8aa3b, v89
	v_pk_fma_f32 v[80:81], v[80:81], v[88:89], v[204:205] op_sel_hi:[1,0,1]
	v_pk_fma_f32 v[78:79], v[172:173], v[84:85], v[78:79] op_sel:[0,1,0] neg_lo:[1,0,0] neg_hi:[1,0,0]
	v_mul_f32_e32 v90, 0xbf317218, v89
	v_pk_fma_f32 v[82:83], v[82:83], v[88:89], v[206:207] op_sel_hi:[1,0,1]
	v_pk_fma_f32 v[78:79], v[78:79], v[88:89], v[202:203] op_sel_hi:[1,0,1]
	v_pk_fma_f32 v[76:77], v[76:77], v[88:89], v[200:201] op_sel_hi:[1,0,1]
	v_pk_fma_f32 v[68:69], v[170:171], v[84:85], v[68:69] op_sel:[0,1,0] neg_lo:[1,0,0] neg_hi:[1,0,0]
	v_pk_fma_f32 v[70:71], v[166:167], v[84:85], v[70:71] op_sel:[0,1,0] neg_lo:[1,0,0] neg_hi:[1,0,0]
	v_exp_f32_e32 v88, v80
	v_pk_fma_f32 v[72:73], v[184:185], v[84:85], v[72:73] op_sel:[0,1,0] neg_lo:[1,0,0] neg_hi:[1,0,0]
	v_pk_fma_f32 v[74:75], v[168:169], v[84:85], v[74:75] op_sel:[0,1,0] neg_lo:[1,0,0] neg_hi:[1,0,0]
	v_pk_fma_f32 v[84:85], v[70:71], v[90:91], v[192:193] op_sel_hi:[1,0,1]
	v_pk_fma_f32 v[70:71], v[68:69], v[90:91], v[188:189] op_sel_hi:[1,0,1]
	v_exp_f32_e32 v68, v81
	v_add_f32_e32 v69, 1.0, v88
	v_rcp_f32_e32 v69, v69
	v_pk_fma_f32 v[72:73], v[72:73], v[90:91], v[196:197] op_sel_hi:[1,0,1]
	v_add_f32_e32 v68, 1.0, v68
	v_rcp_f32_e32 v68, v68
	v_mul_f32_e32 v72, v80, v72
	v_mul_f32_e32 v69, v72, v69
	v_mul_f32_e32 v72, v81, v73
	v_exp_f32_e32 v73, v82
	v_mul_f32_e32 v68, v72, v68
	v_exp_f32_e32 v72, v83
	v_cvt_pk_bf16_f32 v68, v69, v68
	v_add_f32_e32 v69, 1.0, v73
	v_rcp_f32_e32 v69, v69
	v_add_f32_e32 v72, 1.0, v72
	v_rcp_f32_e32 v72, v72
	v_pk_fma_f32 v[74:75], v[74:75], v[90:91], v[198:199] op_sel_hi:[1,0,1]
	v_mul_f32_e32 v70, v76, v70
	v_mul_f32_e32 v73, v82, v74
	v_mul_f32_e32 v69, v73, v69
	v_mul_f32_e32 v73, v83, v75
	v_mul_f32_e32 v72, v73, v72
	v_exp_f32_e32 v73, v76
	v_cvt_pk_bf16_f32 v69, v69, v72
	v_exp_f32_e32 v72, v77
	v_exp_f32_e32 v74, v78
	v_add_f32_e32 v73, 1.0, v73
	v_rcp_f32_e32 v73, v73
	v_add_f32_e32 v72, 1.0, v72
	v_rcp_f32_e32 v72, v72
	v_mul_f32_e32 v71, v77, v71
	v_mul_f32_e32 v70, v70, v73
	v_mul_f32_e32 v73, v78, v84
	v_mul_f32_e32 v71, v71, v72
	v_cvt_pk_bf16_f32 v70, v70, v71
	v_exp_f32_e32 v71, v79
	v_add_f32_e32 v72, 1.0, v74
	v_rcp_f32_e32 v72, v72
	s_waitcnt vmcnt(6)
	v_cvt_f32_u32_e32 v75, v144
	v_add_f32_e32 v71, 1.0, v71
	v_rcp_f32_e32 v71, v71
	v_mul_f32_e32 v76, v73, v72
	v_cvt_f32_i32_e32 v73, v145
	v_cvt_f32_i32_e32 v72, v147
	v_cvt_f32_u32_e32 v74, v146
	v_mad_i64_i32 v[86:87], s[16:17], v220, s23, v[210:211]
	v_mul_f32_e32 v77, v79, v85
	v_lshl_add_u64 v[86:87], v[86:87], 0, v[212:213]
	v_mul_f32_e32 v71, v77, v71
	v_cvt_pk_bf16_f32 v71, v76, v71
	global_store_dwordx4 v[86:87], v[68:71], off
	s_nop 1
	v_pk_fma_f32 v[68:69], v[72:73], s[30:31], v[74:75] op_sel_hi:[1,0,1]
	s_nop 0
	v_pk_mul_f32 v[68:69], v[68:69], s[90:91] op_sel_hi:[1,0]
	s_nop 0
	v_pk_mul_f32 v[68:69], v[68:69], s[92:93] op_sel_hi:[1,0]
	s_nop 0
	v_fma_f32 v70, -v69, v69, v68
	v_max_f32_e32 v70, 0, v70
	v_add_f32_e32 v70, 0x3727c5ac, v70
	v_rsq_f32_e32 v73, v70
	v_pk_fma_f32 v[64:65], v[194:195], v[68:69], v[64:65] op_sel:[0,1,0] neg_lo:[1,0,0] neg_hi:[1,0,0]
	v_pk_fma_f32 v[66:67], v[186:187], v[68:69], v[66:67] op_sel:[0,1,0] neg_lo:[1,0,0] neg_hi:[1,0,0]
	v_pk_fma_f32 v[60:61], v[190:191], v[68:69], v[60:61] op_sel:[0,1,0] neg_lo:[1,0,0] neg_hi:[1,0,0]
	v_mul_f32_e32 v72, 0xbfb8aa3b, v73
	v_pk_fma_f32 v[64:65], v[64:65], v[72:73], v[204:205] op_sel_hi:[1,0,1]
	v_pk_fma_f32 v[62:63], v[172:173], v[68:69], v[62:63] op_sel:[0,1,0] neg_lo:[1,0,0] neg_hi:[1,0,0]
	v_mul_f32_e32 v74, 0xbf317218, v73
	v_pk_fma_f32 v[66:67], v[66:67], v[72:73], v[206:207] op_sel_hi:[1,0,1]
	v_pk_fma_f32 v[62:63], v[62:63], v[72:73], v[202:203] op_sel_hi:[1,0,1]
	v_pk_fma_f32 v[60:61], v[60:61], v[72:73], v[200:201] op_sel_hi:[1,0,1]
	v_pk_fma_f32 v[52:53], v[170:171], v[68:69], v[52:53] op_sel:[0,1,0] neg_lo:[1,0,0] neg_hi:[1,0,0]
	v_pk_fma_f32 v[54:55], v[166:167], v[68:69], v[54:55] op_sel:[0,1,0] neg_lo:[1,0,0] neg_hi:[1,0,0]
	v_exp_f32_e32 v72, v64
	v_pk_fma_f32 v[56:57], v[184:185], v[68:69], v[56:57] op_sel:[0,1,0] neg_lo:[1,0,0] neg_hi:[1,0,0]
	v_pk_fma_f32 v[58:59], v[168:169], v[68:69], v[58:59] op_sel:[0,1,0] neg_lo:[1,0,0] neg_hi:[1,0,0]
	v_pk_fma_f32 v[68:69], v[54:55], v[74:75], v[192:193] op_sel_hi:[1,0,1]
	v_pk_fma_f32 v[54:55], v[52:53], v[74:75], v[188:189] op_sel_hi:[1,0,1]
	v_exp_f32_e32 v52, v65
	v_add_f32_e32 v53, 1.0, v72
	v_rcp_f32_e32 v53, v53
	v_pk_fma_f32 v[56:57], v[56:57], v[74:75], v[196:197] op_sel_hi:[1,0,1]
	v_add_f32_e32 v52, 1.0, v52
	v_rcp_f32_e32 v52, v52
	v_mul_f32_e32 v56, v64, v56
	v_mul_f32_e32 v53, v56, v53
	v_mul_f32_e32 v56, v65, v57
	v_exp_f32_e32 v57, v66
	v_mul_f32_e32 v52, v56, v52
	v_exp_f32_e32 v56, v67
	v_cvt_pk_bf16_f32 v52, v53, v52
	v_add_f32_e32 v53, 1.0, v57
	v_rcp_f32_e32 v53, v53
	v_add_f32_e32 v56, 1.0, v56
	v_rcp_f32_e32 v56, v56
	v_pk_fma_f32 v[58:59], v[58:59], v[74:75], v[198:199] op_sel_hi:[1,0,1]
	v_mul_f32_e32 v54, v60, v54
	v_mul_f32_e32 v57, v66, v58
	v_mul_f32_e32 v53, v57, v53
	v_mul_f32_e32 v57, v67, v59
	v_mul_f32_e32 v56, v57, v56
	v_exp_f32_e32 v57, v60
	v_cvt_pk_bf16_f32 v53, v53, v56
	v_exp_f32_e32 v56, v61
	v_exp_f32_e32 v58, v62
	v_add_f32_e32 v57, 1.0, v57
	v_rcp_f32_e32 v57, v57
	v_add_f32_e32 v56, 1.0, v56
	v_rcp_f32_e32 v56, v56
	v_mul_f32_e32 v55, v61, v55
	v_mul_f32_e32 v54, v54, v57
	v_mul_f32_e32 v57, v62, v68
	v_mul_f32_e32 v55, v55, v56
	v_cvt_pk_bf16_f32 v54, v54, v55
	v_exp_f32_e32 v55, v63
	v_add_f32_e32 v56, 1.0, v58
	v_rcp_f32_e32 v56, v56
	s_waitcnt vmcnt(6)
	v_cvt_f32_u32_e32 v59, v140
	v_add_f32_e32 v55, 1.0, v55
	v_rcp_f32_e32 v55, v55
	v_mul_f32_e32 v60, v57, v56
	v_cvt_f32_i32_e32 v57, v141
	v_cvt_f32_i32_e32 v56, v143
	v_cvt_f32_u32_e32 v58, v142
	v_mad_i64_i32 v[70:71], s[16:17], v218, s23, v[210:211]
	v_mul_f32_e32 v61, v63, v69
	v_lshl_add_u64 v[70:71], v[70:71], 0, v[212:213]
	v_mul_f32_e32 v55, v61, v55
	v_cvt_pk_bf16_f32 v55, v60, v55
	global_store_dwordx4 v[70:71], v[52:55], off
	s_nop 1
	v_pk_fma_f32 v[52:53], v[56:57], s[30:31], v[58:59] op_sel_hi:[1,0,1]
	s_nop 0
	v_pk_mul_f32 v[52:53], v[52:53], s[90:91] op_sel_hi:[1,0]
	s_nop 0
	v_pk_mul_f32 v[52:53], v[52:53], s[92:93] op_sel_hi:[1,0]
	s_nop 0
	v_fma_f32 v54, -v53, v53, v52
	v_max_f32_e32 v54, 0, v54
	v_add_f32_e32 v54, 0x3727c5ac, v54
	v_rsq_f32_e32 v57, v54
	v_pk_fma_f32 v[48:49], v[194:195], v[52:53], v[48:49] op_sel:[0,1,0] neg_lo:[1,0,0] neg_hi:[1,0,0]
	v_pk_fma_f32 v[50:51], v[186:187], v[52:53], v[50:51] op_sel:[0,1,0] neg_lo:[1,0,0] neg_hi:[1,0,0]
	v_pk_fma_f32 v[44:45], v[190:191], v[52:53], v[44:45] op_sel:[0,1,0] neg_lo:[1,0,0] neg_hi:[1,0,0]
	v_mul_f32_e32 v56, 0xbfb8aa3b, v57
	v_pk_fma_f32 v[48:49], v[48:49], v[56:57], v[204:205] op_sel_hi:[1,0,1]
	v_pk_fma_f32 v[46:47], v[172:173], v[52:53], v[46:47] op_sel:[0,1,0] neg_lo:[1,0,0] neg_hi:[1,0,0]
	v_mul_f32_e32 v58, 0xbf317218, v57
	v_pk_fma_f32 v[50:51], v[50:51], v[56:57], v[206:207] op_sel_hi:[1,0,1]
	v_pk_fma_f32 v[46:47], v[46:47], v[56:57], v[202:203] op_sel_hi:[1,0,1]
	v_pk_fma_f32 v[44:45], v[44:45], v[56:57], v[200:201] op_sel_hi:[1,0,1]
	v_pk_fma_f32 v[36:37], v[170:171], v[52:53], v[36:37] op_sel:[0,1,0] neg_lo:[1,0,0] neg_hi:[1,0,0]
	v_pk_fma_f32 v[38:39], v[166:167], v[52:53], v[38:39] op_sel:[0,1,0] neg_lo:[1,0,0] neg_hi:[1,0,0]
	v_exp_f32_e32 v56, v48
	v_pk_fma_f32 v[40:41], v[184:185], v[52:53], v[40:41] op_sel:[0,1,0] neg_lo:[1,0,0] neg_hi:[1,0,0]
	v_pk_fma_f32 v[42:43], v[168:169], v[52:53], v[42:43] op_sel:[0,1,0] neg_lo:[1,0,0] neg_hi:[1,0,0]
	v_pk_fma_f32 v[52:53], v[38:39], v[58:59], v[192:193] op_sel_hi:[1,0,1]
	v_pk_fma_f32 v[38:39], v[36:37], v[58:59], v[188:189] op_sel_hi:[1,0,1]
	v_exp_f32_e32 v36, v49
	v_add_f32_e32 v37, 1.0, v56
	v_rcp_f32_e32 v37, v37
	v_pk_fma_f32 v[40:41], v[40:41], v[58:59], v[196:197] op_sel_hi:[1,0,1]
	v_add_f32_e32 v36, 1.0, v36
	v_rcp_f32_e32 v36, v36
	v_mul_f32_e32 v40, v48, v40
	v_mul_f32_e32 v37, v40, v37
	v_mul_f32_e32 v40, v49, v41
	v_exp_f32_e32 v41, v50
	v_mul_f32_e32 v36, v40, v36
	v_exp_f32_e32 v40, v51
	v_cvt_pk_bf16_f32 v36, v37, v36
	v_add_f32_e32 v37, 1.0, v41
	v_rcp_f32_e32 v37, v37
	v_add_f32_e32 v40, 1.0, v40
	v_rcp_f32_e32 v40, v40
	v_pk_fma_f32 v[42:43], v[42:43], v[58:59], v[198:199] op_sel_hi:[1,0,1]
	v_mul_f32_e32 v38, v44, v38
	v_mul_f32_e32 v41, v50, v42
	v_mul_f32_e32 v37, v41, v37
	v_mul_f32_e32 v41, v51, v43
	v_mul_f32_e32 v40, v41, v40
	v_exp_f32_e32 v41, v44
	v_cvt_pk_bf16_f32 v37, v37, v40
	v_exp_f32_e32 v40, v45
	v_exp_f32_e32 v42, v46
	v_add_f32_e32 v41, 1.0, v41
	v_rcp_f32_e32 v41, v41
	v_add_f32_e32 v40, 1.0, v40
	v_rcp_f32_e32 v40, v40
	v_mul_f32_e32 v39, v45, v39
	v_mul_f32_e32 v38, v38, v41
	v_mul_f32_e32 v41, v46, v52
	v_mul_f32_e32 v39, v39, v40
	v_cvt_pk_bf16_f32 v38, v38, v39
	v_exp_f32_e32 v39, v47
	v_add_f32_e32 v40, 1.0, v42
	v_rcp_f32_e32 v40, v40
	s_waitcnt vmcnt(6)
	v_cvt_f32_u32_e32 v43, v136
	v_add_f32_e32 v39, 1.0, v39
	v_rcp_f32_e32 v39, v39
	v_mul_f32_e32 v44, v41, v40
	v_cvt_f32_i32_e32 v41, v137
	v_cvt_f32_i32_e32 v40, v139
	v_cvt_f32_u32_e32 v42, v138
	v_mad_i64_i32 v[54:55], s[16:17], v216, s23, v[210:211]
	v_mul_f32_e32 v45, v47, v53
	v_lshl_add_u64 v[54:55], v[54:55], 0, v[212:213]
	v_mul_f32_e32 v39, v45, v39
	v_cvt_pk_bf16_f32 v39, v44, v39
	global_store_dwordx4 v[54:55], v[36:39], off
	s_nop 1
	v_pk_fma_f32 v[36:37], v[40:41], s[30:31], v[42:43] op_sel_hi:[1,0,1]
	s_nop 0
	v_pk_mul_f32 v[36:37], v[36:37], s[90:91] op_sel_hi:[1,0]
	s_nop 0
	v_pk_mul_f32 v[36:37], v[36:37], s[92:93] op_sel_hi:[1,0]
	s_nop 0
	v_fma_f32 v38, -v37, v37, v36
	v_max_f32_e32 v38, 0, v38
	v_add_f32_e32 v38, 0x3727c5ac, v38
	v_rsq_f32_e32 v41, v38
	v_pk_fma_f32 v[32:33], v[194:195], v[36:37], v[32:33] op_sel:[0,1,0] neg_lo:[1,0,0] neg_hi:[1,0,0]
	v_pk_fma_f32 v[34:35], v[186:187], v[36:37], v[34:35] op_sel:[0,1,0] neg_lo:[1,0,0] neg_hi:[1,0,0]
	v_pk_fma_f32 v[28:29], v[190:191], v[36:37], v[28:29] op_sel:[0,1,0] neg_lo:[1,0,0] neg_hi:[1,0,0]
	v_mul_f32_e32 v40, 0xbfb8aa3b, v41
	v_pk_fma_f32 v[32:33], v[32:33], v[40:41], v[204:205] op_sel_hi:[1,0,1]
	v_pk_fma_f32 v[30:31], v[172:173], v[36:37], v[30:31] op_sel:[0,1,0] neg_lo:[1,0,0] neg_hi:[1,0,0]
	v_mul_f32_e32 v42, 0xbf317218, v41
	v_pk_fma_f32 v[34:35], v[34:35], v[40:41], v[206:207] op_sel_hi:[1,0,1]
	v_pk_fma_f32 v[30:31], v[30:31], v[40:41], v[202:203] op_sel_hi:[1,0,1]
	v_pk_fma_f32 v[28:29], v[28:29], v[40:41], v[200:201] op_sel_hi:[1,0,1]
	v_pk_fma_f32 v[20:21], v[170:171], v[36:37], v[20:21] op_sel:[0,1,0] neg_lo:[1,0,0] neg_hi:[1,0,0]
	v_pk_fma_f32 v[22:23], v[166:167], v[36:37], v[22:23] op_sel:[0,1,0] neg_lo:[1,0,0] neg_hi:[1,0,0]
	v_exp_f32_e32 v40, v32
	v_pk_fma_f32 v[24:25], v[184:185], v[36:37], v[24:25] op_sel:[0,1,0] neg_lo:[1,0,0] neg_hi:[1,0,0]
	v_pk_fma_f32 v[26:27], v[168:169], v[36:37], v[26:27] op_sel:[0,1,0] neg_lo:[1,0,0] neg_hi:[1,0,0]
	v_pk_fma_f32 v[36:37], v[22:23], v[42:43], v[192:193] op_sel_hi:[1,0,1]
	v_pk_fma_f32 v[22:23], v[20:21], v[42:43], v[188:189] op_sel_hi:[1,0,1]
	v_exp_f32_e32 v20, v33
	v_add_f32_e32 v21, 1.0, v40
	v_rcp_f32_e32 v21, v21
	v_pk_fma_f32 v[24:25], v[24:25], v[42:43], v[196:197] op_sel_hi:[1,0,1]
	v_add_f32_e32 v20, 1.0, v20
	v_rcp_f32_e32 v20, v20
	v_mul_f32_e32 v24, v32, v24
	v_mul_f32_e32 v21, v24, v21
	v_mul_f32_e32 v24, v33, v25
	v_exp_f32_e32 v25, v34
	v_mul_f32_e32 v20, v24, v20
	v_exp_f32_e32 v24, v35
	v_cvt_pk_bf16_f32 v20, v21, v20
	v_add_f32_e32 v21, 1.0, v25
	v_rcp_f32_e32 v21, v21
	v_add_f32_e32 v24, 1.0, v24
	v_rcp_f32_e32 v24, v24
	v_pk_fma_f32 v[26:27], v[26:27], v[42:43], v[198:199] op_sel_hi:[1,0,1]
	v_mul_f32_e32 v22, v28, v22
	v_mul_f32_e32 v25, v34, v26
	v_mul_f32_e32 v21, v25, v21
	v_mul_f32_e32 v25, v35, v27
	v_mul_f32_e32 v24, v25, v24
	v_exp_f32_e32 v25, v28
	v_cvt_pk_bf16_f32 v21, v21, v24
	v_exp_f32_e32 v24, v29
	v_exp_f32_e32 v26, v30
	v_add_f32_e32 v25, 1.0, v25
	v_rcp_f32_e32 v25, v25
	v_add_f32_e32 v24, 1.0, v24
	v_rcp_f32_e32 v24, v24
	v_mul_f32_e32 v23, v29, v23
	v_mul_f32_e32 v22, v22, v25
	v_mul_f32_e32 v25, v30, v36
	v_mul_f32_e32 v23, v23, v24
	v_cvt_pk_bf16_f32 v22, v22, v23
	v_exp_f32_e32 v23, v31
	v_add_f32_e32 v24, 1.0, v26
	v_rcp_f32_e32 v24, v24
	s_waitcnt vmcnt(6)
	v_cvt_f32_u32_e32 v27, v132
	v_add_f32_e32 v23, 1.0, v23
	v_rcp_f32_e32 v23, v23
	v_mul_f32_e32 v28, v25, v24
	v_cvt_f32_i32_e32 v25, v133
	v_cvt_f32_i32_e32 v24, v135
	v_cvt_f32_u32_e32 v26, v134
	v_mad_i64_i32 v[38:39], s[16:17], v214, s23, v[210:211]
	v_mul_f32_e32 v29, v31, v37
	v_lshl_add_u64 v[38:39], v[38:39], 0, v[212:213]
	v_mul_f32_e32 v23, v29, v23
	v_cvt_pk_bf16_f32 v23, v28, v23
	global_store_dwordx4 v[38:39], v[20:23], off
	s_nop 1
	v_pk_fma_f32 v[20:21], v[24:25], s[30:31], v[26:27] op_sel_hi:[1,0,1]
	s_nop 0
	v_pk_mul_f32 v[20:21], v[20:21], s[90:91] op_sel_hi:[1,0]
	s_nop 0
	v_pk_mul_f32 v[20:21], v[20:21], s[92:93] op_sel_hi:[1,0]
	s_nop 0
	v_fma_f32 v22, -v21, v21, v20
	v_max_f32_e32 v22, 0, v22
	v_add_f32_e32 v22, 0x3727c5ac, v22
	v_rsq_f32_e32 v25, v22
	v_pk_fma_f32 v[16:17], v[194:195], v[20:21], v[16:17] op_sel:[0,1,0] neg_lo:[1,0,0] neg_hi:[1,0,0]
	v_pk_fma_f32 v[18:19], v[186:187], v[20:21], v[18:19] op_sel:[0,1,0] neg_lo:[1,0,0] neg_hi:[1,0,0]
	v_pk_fma_f32 v[12:13], v[190:191], v[20:21], v[12:13] op_sel:[0,1,0] neg_lo:[1,0,0] neg_hi:[1,0,0]
	v_mul_f32_e32 v24, 0xbfb8aa3b, v25
	v_pk_fma_f32 v[16:17], v[16:17], v[24:25], v[204:205] op_sel_hi:[1,0,1]
	v_pk_fma_f32 v[14:15], v[172:173], v[20:21], v[14:15] op_sel:[0,1,0] neg_lo:[1,0,0] neg_hi:[1,0,0]
	v_mul_f32_e32 v26, 0xbf317218, v25
	v_pk_fma_f32 v[18:19], v[18:19], v[24:25], v[206:207] op_sel_hi:[1,0,1]
	v_pk_fma_f32 v[14:15], v[14:15], v[24:25], v[202:203] op_sel_hi:[1,0,1]
	v_pk_fma_f32 v[12:13], v[12:13], v[24:25], v[200:201] op_sel_hi:[1,0,1]
	v_pk_fma_f32 v[4:5], v[170:171], v[20:21], v[4:5] op_sel:[0,1,0] neg_lo:[1,0,0] neg_hi:[1,0,0]
	v_pk_fma_f32 v[6:7], v[166:167], v[20:21], v[6:7] op_sel:[0,1,0] neg_lo:[1,0,0] neg_hi:[1,0,0]
	v_exp_f32_e32 v24, v16
	v_pk_fma_f32 v[8:9], v[184:185], v[20:21], v[8:9] op_sel:[0,1,0] neg_lo:[1,0,0] neg_hi:[1,0,0]
	v_pk_fma_f32 v[10:11], v[168:169], v[20:21], v[10:11] op_sel:[0,1,0] neg_lo:[1,0,0] neg_hi:[1,0,0]
	v_pk_fma_f32 v[20:21], v[6:7], v[26:27], v[192:193] op_sel_hi:[1,0,1]
	v_pk_fma_f32 v[6:7], v[4:5], v[26:27], v[188:189] op_sel_hi:[1,0,1]
	v_exp_f32_e32 v4, v17
	v_add_f32_e32 v5, 1.0, v24
	v_rcp_f32_e32 v5, v5
	v_pk_fma_f32 v[8:9], v[8:9], v[26:27], v[196:197] op_sel_hi:[1,0,1]
	v_add_f32_e32 v4, 1.0, v4
	v_rcp_f32_e32 v4, v4
	v_mul_f32_e32 v8, v16, v8
	v_mul_f32_e32 v5, v8, v5
	v_mul_f32_e32 v8, v17, v9
	v_exp_f32_e32 v9, v18
	v_mul_f32_e32 v4, v8, v4
	v_cvt_pk_bf16_f32 v4, v5, v4
	v_exp_f32_e32 v5, v19
	v_add_f32_e32 v8, 1.0, v9
	v_rcp_f32_e32 v8, v8
	v_pk_fma_f32 v[10:11], v[10:11], v[26:27], v[198:199] op_sel_hi:[1,0,1]
	v_add_f32_e32 v5, 1.0, v5
	v_rcp_f32_e32 v5, v5
	v_mul_f32_e32 v9, v18, v10
	v_mul_f32_e32 v8, v9, v8
	v_mul_f32_e32 v9, v19, v11
	v_exp_f32_e32 v10, v12
	v_mul_f32_e32 v5, v9, v5
	v_cvt_pk_bf16_f32 v5, v8, v5
	v_exp_f32_e32 v8, v13
	v_add_f32_e32 v9, 1.0, v10
	v_rcp_f32_e32 v9, v9
	v_mul_f32_e32 v6, v12, v6
	v_add_f32_e32 v8, 1.0, v8
	v_rcp_f32_e32 v8, v8
	v_mul_f32_e32 v6, v6, v9
	v_mul_f32_e32 v7, v13, v7
	v_exp_f32_e32 v9, v14
	v_mul_f32_e32 v7, v7, v8
	v_exp_f32_e32 v8, v15
	v_cvt_pk_bf16_f32 v6, v6, v7
	v_add_f32_e32 v7, 1.0, v9
	v_rcp_f32_e32 v7, v7
	v_add_f32_e32 v8, 1.0, v8
	v_rcp_f32_e32 v8, v8
	v_mad_i64_i32 v[22:23], s[16:17], v208, s23, v[210:211]
	v_mul_f32_e32 v9, v14, v20
	v_lshl_add_u64 v[22:23], v[22:23], 0, v[212:213]
	v_mul_f32_e32 v7, v9, v7
	v_mul_f32_e32 v9, v15, v21
	v_mul_f32_e32 v8, v9, v8
	v_cvt_pk_bf16_f32 v7, v7, v8
	global_store_dwordx4 v[22:23], v[4:7], off
	s_cbranch_vccnz .LBB0_201
	s_andn2_b64 vcc, exec, s[10:11]
	s_cbranch_vccnz .LBB0_200
	s_barrier
	s_branch .LBB0_200

.LBB0_369:
	v_lshl_add_u32 v188, s91, 8, v242
	v_ashrrev_i32_e32 v189, 31, v188
	v_lshl_or_b32 v140, s89, 8, v245
	v_lshl_add_u64 v[132:133], v[188:189], 4, s[14:15]
	v_ashrrev_i32_e32 v141, 31, v140
	global_load_dwordx4 v[164:167], v[132:133], off
	v_lshlrev_b64 v[132:133], 12, v[188:189]
	v_lshl_add_u64 v[132:133], s[0:1], 0, v[132:133]
	v_lshlrev_b64 v[222:223], 1, v[140:141]
	v_lshl_add_u64 v[228:229], v[132:133], 0, v[222:223]
	v_or_b32_e32 v132, 16, v188
	v_ashrrev_i32_e32 v133, 31, v132
	v_lshl_add_u64 v[134:135], v[132:133], 4, s[14:15]
	v_lshlrev_b64 v[132:133], 12, v[132:133]
	v_lshl_add_u64 v[132:133], s[0:1], 0, v[132:133]
	v_lshlrev_b64 v[140:141], 2, v[140:141]
	v_lshl_add_u64 v[224:225], v[132:133], 0, v[222:223]
	v_lshl_add_u64 v[174:175], s[10:11], 0, v[140:141]
	global_load_dwordx4 v[160:163], v[228:229], off
	global_load_dwordx4 v[156:159], v[228:229], off offset:64
	global_load_dwordx4 v[144:147], v[134:135], off
	global_load_dwordx4 v[136:139], v[224:225], off
	s_nop 0
	global_load_dwordx4 v[132:135], v[224:225], off offset:64
	v_lshl_add_u64 v[182:183], s[12:13], 0, v[140:141]
	global_load_dwordx4 v[140:143], v[174:175], off offset:16
	global_load_dwordx4 v[148:151], v[174:175], off
	v_readlane_b32 s16, v252, 10
	v_readlane_b32 s17, v252, 11
	s_mov_b64 s[28:29], -1
	v_readlane_b32 s100, v252, 12
	v_readlane_b32 s101, v252, 13
	s_and_b64 s[100:101], exec, s[100:101]
	s_cbranch_scc0 .Lalign_366
	s_barrier
.Lalign_366:
	s_waitcnt vmcnt(0)
	v_pk_mul_f32 v[194:195], v[142:143], s[86:87] op_sel_hi:[1,0]
	v_pk_mul_f32 v[190:191], v[150:151], s[86:87] op_sel_hi:[1,0]
	v_pk_mul_f32 v[192:193], v[148:149], s[86:87] op_sel_hi:[1,0]
	global_load_dwordx4 v[148:151], v[182:183], off offset:16
	global_load_dwordx4 v[152:155], v[182:183], off
	v_pk_mul_f32 v[196:197], v[140:141], s[86:87] op_sel_hi:[1,0]
	s_waitcnt vmcnt(1)
	v_pk_mul_f32 v[198:199], v[150:151], s[86:87] op_sel_hi:[1,0]
	v_pk_mul_f32 v[200:201], v[148:149], s[86:87] op_sel_hi:[1,0]
	global_load_dwordx4 v[140:143], v[174:175], off offset:144
	global_load_dwordx4 v[148:151], v[174:175], off offset:128
	s_waitcnt vmcnt(2)
	v_pk_mul_f32 v[202:203], v[154:155], s[86:87] op_sel_hi:[1,0]
	v_pk_mul_f32 v[204:205], v[152:153], s[86:87] op_sel_hi:[1,0]
	v_cvt_f32_i32_e32 v175, v165
	v_cvt_f32_i32_e32 v174, v167
	v_cvt_f32_u32_e32 v165, v164
	v_cvt_f32_u32_e32 v164, v166
	v_lshlrev_b32_e32 v166, 16, v160
	v_and_b32_e32 v160, 0xffff0000, v160
	v_and_b32_e32 v167, 0xffff0000, v161
	v_pk_fma_f32 v[164:165], v[174:175], s[30:31], v[164:165] op_sel_hi:[1,0,1]
	v_lshlrev_b32_e32 v174, 16, v161
	v_pk_mul_f32 v[164:165], v[164:165], s[90:91] op_sel_hi:[1,0]
	s_waitcnt vmcnt(1)
	v_pk_mul_f32 v[212:213], v[140:141], s[86:87] op_sel_hi:[1,0]
	s_waitcnt vmcnt(0)
	v_pk_mul_f32 v[206:207], v[150:151], s[86:87] op_sel_hi:[1,0]
	v_pk_mul_f32 v[208:209], v[148:149], s[86:87] op_sel_hi:[1,0]
	global_load_dwordx4 v[148:151], v[182:183], off offset:144
	global_load_dwordx4 v[152:155], v[182:183], off offset:128
	v_pk_mul_f32 v[164:165], v[164:165], s[92:93] op_sel_hi:[1,0]
	v_or_b32_e32 v140, 32, v188
	v_fma_f32 v164, -v165, v165, v164
	v_max_f32_e32 v164, 0, v164
	v_add_f32_e32 v164, 0x3727c5ac, v164
	v_rsq_f32_e32 v164, v164
	v_ashrrev_i32_e32 v141, 31, v140
	v_pk_mul_f32 v[210:211], v[142:143], s[86:87] op_sel_hi:[1,0]
	v_lshl_add_u64 v[142:143], v[140:141], 4, s[14:15]
	v_sub_f32_e32 v161, v160, v165
	v_sub_f32_e32 v160, v166, v165
	v_pk_mul_f32 v[160:161], v[160:161], v[164:165] op_sel_hi:[1,0]
	v_lshlrev_b64 v[140:141], 12, v[140:141]
	v_pk_fma_f32 v[160:161], v[192:193], v[160:161], v[204:205]
	v_lshl_add_u64 v[140:141], s[0:1], 0, v[140:141]
	v_pk_fma_f32 v[128:129], v[128:129], 0.5, v[160:161] op_sel_hi:[1,0,1]
	v_lshlrev_b32_e32 v160, 16, v162
	v_and_b32_e32 v161, 0xffff0000, v162
	v_lshlrev_b32_e32 v162, 16, v163
	v_and_b32_e32 v163, 0xffff0000, v163
	v_sub_f32_e32 v161, v161, v165
	v_sub_f32_e32 v160, v160, v165
	v_sub_f32_e32 v163, v163, v165
	v_sub_f32_e32 v162, v162, v165
	v_pk_mul_f32 v[160:161], v[160:161], v[164:165] op_sel_hi:[1,0]
	v_pk_mul_f32 v[162:163], v[162:163], v[164:165] op_sel_hi:[1,0]
	v_pk_fma_f32 v[160:161], v[196:197], v[160:161], v[200:201]
	v_pk_fma_f32 v[162:163], v[194:195], v[162:163], v[198:199]
	v_pk_fma_f32 v[124:125], v[124:125], 0.5, v[160:161] op_sel_hi:[1,0,1]
	v_lshlrev_b32_e32 v160, 16, v156
	v_and_b32_e32 v156, 0xffff0000, v156
	v_pk_fma_f32 v[126:127], v[126:127], 0.5, v[162:163] op_sel_hi:[1,0,1]
	v_lshlrev_b32_e32 v162, 16, v157
	v_and_b32_e32 v161, 0xffff0000, v157
	v_sub_f32_e32 v157, v156, v165
	v_sub_f32_e32 v156, v160, v165
	v_pk_mul_f32 v[156:157], v[156:157], v[164:165] op_sel_hi:[1,0]
	v_sub_f32_e32 v167, v167, v165
	v_sub_f32_e32 v166, v174, v165
	v_lshl_add_u64 v[226:227], v[140:141], 0, v[222:223]
	v_pk_mul_f32 v[166:167], v[166:167], v[164:165] op_sel_hi:[1,0]
	v_sub_f32_e32 v161, v161, v165
	v_sub_f32_e32 v160, v162, v165
	v_pk_fma_f32 v[166:167], v[190:191], v[166:167], v[202:203]
	v_pk_mul_f32 v[160:161], v[160:161], v[164:165] op_sel_hi:[1,0]
	v_pk_fma_f32 v[130:131], v[130:131], 0.5, v[166:167] op_sel_hi:[1,0,1]
	s_waitcnt vmcnt(1)
	v_pk_mul_f32 v[214:215], v[150:151], s[86:87] op_sel_hi:[1,0]
	s_waitcnt vmcnt(0)
	v_pk_mul_f32 v[218:219], v[154:155], s[86:87] op_sel_hi:[1,0]
	v_pk_mul_f32 v[220:221], v[152:153], s[86:87] op_sel_hi:[1,0]
	global_load_dwordx4 v[152:155], v[142:143], off
	v_pk_fma_f32 v[156:157], v[208:209], v[156:157], v[220:221]
	v_pk_mul_f32 v[216:217], v[148:149], s[86:87] op_sel_hi:[1,0]
	v_pk_fma_f32 v[120:121], v[120:121], 0.5, v[156:157] op_sel_hi:[1,0,1]
	v_lshlrev_b32_e32 v156, 16, v158
	v_and_b32_e32 v157, 0xffff0000, v158
	v_lshlrev_b32_e32 v158, 16, v159
	v_and_b32_e32 v159, 0xffff0000, v159
	v_sub_f32_e32 v157, v157, v165
	v_sub_f32_e32 v156, v156, v165
	v_sub_f32_e32 v159, v159, v165
	v_sub_f32_e32 v158, v158, v165
	v_pk_mul_f32 v[158:159], v[158:159], v[164:165] op_sel_hi:[1,0]
	v_pk_mul_f32 v[156:157], v[156:157], v[164:165] op_sel_hi:[1,0]
	global_load_dwordx4 v[148:151], v[226:227], off
	global_load_dwordx4 v[140:143], v[226:227], off offset:64
	v_pk_fma_f32 v[156:157], v[156:157], v[212:213], v[216:217]
	v_pk_fma_f32 v[158:159], v[158:159], v[210:211], v[214:215]
	v_pk_fma_f32 v[160:161], v[206:207], v[160:161], v[218:219]
	v_pk_fma_f32 v[158:159], v[118:119], 0.5, v[158:159] op_sel_hi:[1,0,1]
	v_pk_fma_f32 v[156:157], v[116:117], 0.5, v[156:157] op_sel_hi:[1,0,1]
	v_cvt_pk_bf16_f32 v116, v128, v129
	v_cvt_pk_bf16_f32 v117, v130, v131
	v_cvt_pk_bf16_f32 v118, v124, v125
	v_cvt_pk_bf16_f32 v119, v126, v127
	v_pk_fma_f32 v[122:123], v[122:123], 0.5, v[160:161] op_sel_hi:[1,0,1]
	global_store_dwordx4 v[228:229], v[116:119], off
	v_pk_add_f32 v[160:161], v[120:121], v[156:157]
	v_pk_add_f32 v[162:163], v[122:123], v[158:159]
	v_cvt_pk_bf16_f32 v116, v120, v121
	v_cvt_pk_bf16_f32 v117, v122, v123
	v_cvt_pk_bf16_f32 v118, v156, v157
	v_cvt_pk_bf16_f32 v119, v158, v159
	global_store_dwordx4 v[228:229], v[116:119], off offset:64
	s_nop 1
	v_pk_add_f32 v[116:117], v[128:129], v[124:125]
	v_pk_add_f32 v[118:119], v[130:131], v[126:127]
	v_pk_mul_f32 v[126:127], v[126:127], v[126:127]
	v_pk_mul_f32 v[124:125], v[124:125], v[124:125]
	v_pk_fma_f32 v[126:127], v[130:131], v[130:131], v[126:127]
	v_pk_fma_f32 v[124:125], v[128:129], v[128:129], v[124:125]
	v_pk_mul_f32 v[128:129], v[158:159], v[158:159]
	v_pk_mul_f32 v[130:131], v[156:157], v[156:157]
	v_pk_add_f32 v[118:119], v[118:119], v[162:163]
	v_pk_add_f32 v[116:117], v[116:117], v[160:161]
	v_pk_fma_f32 v[120:121], v[120:121], v[120:121], v[130:131]
	v_pk_fma_f32 v[122:123], v[122:123], v[122:123], v[128:129]
	v_pk_add_f32 v[120:121], v[124:125], v[120:121]
	v_pk_add_f32 v[122:123], v[126:127], v[122:123]
	v_add_f32_e32 v116, v116, v117
	v_add_f32_e32 v117, v118, v119
	v_add_f32_e32 v116, v116, v117
	v_add_f32_e32 v117, v120, v121
	v_add_f32_e32 v118, v122, v123
	v_and_b32_e32 v119, 64, v230
	v_add_f32_e32 v117, v117, v118
	v_xor_b32_e32 v118, 16, v230
	v_add_u32_e32 v119, 64, v119
	v_cmp_lt_i32_e32 vcc, v118, v119
	v_cvt_f32_i32_e32 v161, v145
	v_cvt_f32_i32_e32 v160, v147
	v_cndmask_b32_e32 v118, v230, v118, vcc
	v_lshlrev_b32_e32 v156, 2, v118
	ds_bpermute_b32 v118, v156, v116
	v_cvt_f32_u32_e32 v145, v144
	v_cvt_f32_u32_e32 v144, v146
	v_lshlrev_b32_e32 v146, 16, v136
	v_and_b32_e32 v136, 0xffff0000, v136
	s_waitcnt lgkmcnt(0)
	v_add_f32_e32 v130, v116, v118
	v_xor_b32_e32 v116, 32, v230
	v_cmp_lt_i32_e32 vcc, v116, v119
	v_pk_fma_f32 v[144:145], v[160:161], s[30:31], v[144:145] op_sel_hi:[1,0,1]
	v_lshlrev_b32_e32 v160, 16, v137
	v_cndmask_b32_e32 v116, v230, v116, vcc
	v_lshlrev_b32_e32 v158, 2, v116
	ds_bpermute_b32 v116, v156, v117
	v_pk_mul_f32 v[144:145], v[144:145], s[90:91] op_sel_hi:[1,0]
	v_and_b32_e32 v147, 0xffff0000, v137
	v_pk_mul_f32 v[144:145], v[144:145], s[92:93] op_sel_hi:[1,0]
	ds_bpermute_b32 v131, v158, v130
	s_waitcnt lgkmcnt(1)
	v_add_f32_e32 v157, v117, v116
	v_or_b32_e32 v116, 48, v188
	v_ashrrev_i32_e32 v117, 31, v116
	v_lshl_add_u64 v[118:119], v[116:117], 4, s[14:15]
	global_load_dwordx4 v[124:127], v[118:119], off
	v_fma_f32 v144, -v145, v145, v144
	v_max_f32_e32 v144, 0, v144
	v_add_f32_e32 v144, 0x3727c5ac, v144
	v_rsq_f32_e32 v144, v144
	v_lshlrev_b64 v[116:117], 12, v[116:117]
	v_lshl_add_u64 v[116:117], s[0:1], 0, v[116:117]
	v_lshl_add_u64 v[128:129], v[116:117], 0, v[222:223]
	v_sub_f32_e32 v137, v136, v145
	v_sub_f32_e32 v136, v146, v145
	global_load_dwordx4 v[120:123], v[128:129], off
	global_load_dwordx4 v[116:119], v[128:129], off offset:64
	v_pk_mul_f32 v[136:137], v[136:137], v[144:145] op_sel_hi:[1,0]
	v_sub_f32_e32 v147, v147, v145
	v_pk_fma_f32 v[136:137], v[192:193], v[136:137], v[204:205]
	v_sub_f32_e32 v146, v160, v145
	v_pk_fma_f32 v[112:113], v[112:113], 0.5, v[136:137] op_sel_hi:[1,0,1]
	v_lshlrev_b32_e32 v136, 16, v138
	v_and_b32_e32 v137, 0xffff0000, v138
	v_lshlrev_b32_e32 v138, 16, v139
	v_and_b32_e32 v139, 0xffff0000, v139
	v_sub_f32_e32 v137, v137, v145
	v_sub_f32_e32 v136, v136, v145
	v_sub_f32_e32 v139, v139, v145
	v_sub_f32_e32 v138, v138, v145
	v_pk_mul_f32 v[136:137], v[136:137], v[144:145] op_sel_hi:[1,0]
	v_pk_mul_f32 v[138:139], v[138:139], v[144:145] op_sel_hi:[1,0]
	v_pk_fma_f32 v[136:137], v[196:197], v[136:137], v[200:201]
	v_pk_fma_f32 v[138:139], v[194:195], v[138:139], v[198:199]
	v_pk_fma_f32 v[108:109], v[108:109], 0.5, v[136:137] op_sel_hi:[1,0,1]
	v_lshlrev_b32_e32 v136, 16, v132
	v_and_b32_e32 v132, 0xffff0000, v132
	v_pk_fma_f32 v[110:111], v[110:111], 0.5, v[138:139] op_sel_hi:[1,0,1]
	v_lshlrev_b32_e32 v138, 16, v133
	v_and_b32_e32 v137, 0xffff0000, v133
	v_sub_f32_e32 v133, v132, v145
	v_sub_f32_e32 v132, v136, v145
	v_pk_mul_f32 v[132:133], v[132:133], v[144:145] op_sel_hi:[1,0]
	v_pk_mul_f32 v[146:147], v[146:147], v[144:145] op_sel_hi:[1,0]
	v_pk_fma_f32 v[132:133], v[208:209], v[132:133], v[220:221]
	v_sub_f32_e32 v137, v137, v145
	v_pk_fma_f32 v[104:105], v[104:105], 0.5, v[132:133] op_sel_hi:[1,0,1]
	v_lshlrev_b32_e32 v132, 16, v134
	v_and_b32_e32 v133, 0xffff0000, v134
	v_lshlrev_b32_e32 v134, 16, v135
	v_and_b32_e32 v135, 0xffff0000, v135
	v_sub_f32_e32 v133, v133, v145
	v_sub_f32_e32 v132, v132, v145
	v_sub_f32_e32 v135, v135, v145
	v_sub_f32_e32 v134, v134, v145
	v_sub_f32_e32 v136, v138, v145
	v_pk_mul_f32 v[134:135], v[134:135], v[144:145] op_sel_hi:[1,0]
	v_pk_mul_f32 v[132:133], v[132:133], v[144:145] op_sel_hi:[1,0]
	v_pk_fma_f32 v[146:147], v[190:191], v[146:147], v[202:203]
	v_pk_mul_f32 v[136:137], v[136:137], v[144:145] op_sel_hi:[1,0]
	v_pk_fma_f32 v[132:133], v[212:213], v[132:133], v[216:217]
	v_pk_fma_f32 v[134:135], v[210:211], v[134:135], v[214:215]
	v_pk_fma_f32 v[114:115], v[114:115], 0.5, v[146:147] op_sel_hi:[1,0,1]
	v_pk_fma_f32 v[136:137], v[206:207], v[136:137], v[218:219]
	v_pk_fma_f32 v[134:135], v[102:103], 0.5, v[134:135] op_sel_hi:[1,0,1]
	v_pk_fma_f32 v[132:133], v[100:101], 0.5, v[132:133] op_sel_hi:[1,0,1]
	v_cvt_pk_bf16_f32 v100, v112, v113
	v_cvt_pk_bf16_f32 v101, v114, v115
	v_cvt_pk_bf16_f32 v102, v108, v109
	v_cvt_pk_bf16_f32 v103, v110, v111
	v_pk_fma_f32 v[106:107], v[106:107], 0.5, v[136:137] op_sel_hi:[1,0,1]
	global_store_dwordx4 v[224:225], v[100:103], off
	v_pk_add_f32 v[136:137], v[104:105], v[132:133]
	v_pk_add_f32 v[138:139], v[106:107], v[134:135]
	v_cvt_pk_bf16_f32 v100, v104, v105
	v_cvt_pk_bf16_f32 v101, v106, v107
	v_cvt_pk_bf16_f32 v102, v132, v133
	v_cvt_pk_bf16_f32 v103, v134, v135
	global_store_dwordx4 v[224:225], v[100:103], off offset:64
	s_waitcnt vmcnt(8)
	v_lshlrev_b32_e32 v144, 16, v149
	v_and_b32_e32 v145, 0xffff0000, v149
	v_pk_add_f32 v[100:101], v[112:113], v[108:109]
	v_pk_add_f32 v[102:103], v[114:115], v[110:111]
	v_pk_mul_f32 v[110:111], v[110:111], v[110:111]
	v_pk_mul_f32 v[108:109], v[108:109], v[108:109]
	v_pk_fma_f32 v[110:111], v[114:115], v[114:115], v[110:111]
	v_pk_fma_f32 v[108:109], v[112:113], v[112:113], v[108:109]
	v_pk_mul_f32 v[112:113], v[134:135], v[134:135]
	v_pk_mul_f32 v[114:115], v[132:133], v[132:133]
	v_pk_add_f32 v[102:103], v[102:103], v[138:139]
	v_pk_add_f32 v[100:101], v[100:101], v[136:137]
	v_pk_fma_f32 v[104:105], v[104:105], v[104:105], v[114:115]
	v_pk_fma_f32 v[106:107], v[106:107], v[106:107], v[112:113]
	v_pk_add_f32 v[104:105], v[108:109], v[104:105]
	v_pk_add_f32 v[106:107], v[110:111], v[106:107]
	v_add_f32_e32 v100, v100, v101
	v_add_f32_e32 v101, v102, v103
	v_add_f32_e32 v100, v100, v101
	v_add_f32_e32 v101, v104, v105
	v_add_f32_e32 v102, v106, v107
	v_add_f32_e32 v101, v101, v102
	ds_bpermute_b32 v102, v156, v100
	v_cvt_f32_i32_e32 v137, v153
	v_cvt_f32_i32_e32 v136, v155
	v_cvt_f32_u32_e32 v139, v152
	v_cvt_f32_u32_e32 v138, v154
	s_waitcnt lgkmcnt(0)
	v_add_f32_e32 v132, v100, v102
	ds_bpermute_b32 v100, v156, v101
	v_add_u32_e32 v112, 0x80, v188
	v_ashrrev_i32_e32 v113, 31, v112
	v_pk_fma_f32 v[136:137], v[136:137], s[30:31], v[138:139] op_sel_hi:[1,0,1]
	v_and_b32_e32 v138, 0xffff0000, v148
	s_waitcnt lgkmcnt(0)
	v_add_f32_e32 v134, v101, v100
	v_lshl_add_u64 v[100:101], v[112:113], 4, s[14:15]
	v_pk_mul_f32 v[136:137], v[136:137], s[90:91] op_sel_hi:[1,0]
	global_load_dwordx4 v[108:111], v[100:101], off
	v_pk_mul_f32 v[136:137], v[136:137], s[92:93] op_sel_hi:[1,0]
	v_lshlrev_b64 v[100:101], 12, v[112:113]
	v_fma_f32 v113, -v137, v137, v136
	v_max_f32_e32 v113, 0, v113
	v_add_f32_e32 v113, 0x3727c5ac, v113
	v_rsq_f32_e32 v136, v113
	v_lshlrev_b32_e32 v113, 16, v148
	v_sub_f32_e32 v139, v138, v137
	v_sub_f32_e32 v138, v113, v137
	v_pk_mul_f32 v[138:139], v[138:139], v[136:137] op_sel_hi:[1,0]
	v_lshlrev_b32_e32 v113, 16, v150
	v_pk_fma_f32 v[138:139], v[192:193], v[138:139], v[204:205]
	v_lshl_add_u64 v[100:101], s[0:1], 0, v[100:101]
	v_pk_fma_f32 v[96:97], v[96:97], 0.5, v[138:139] op_sel_hi:[1,0,1]
	v_and_b32_e32 v138, 0xffff0000, v150
	v_sub_f32_e32 v139, v138, v137
	v_sub_f32_e32 v138, v113, v137
	v_lshl_add_u64 v[114:115], v[100:101], 0, v[222:223]
	v_pk_mul_f32 v[138:139], v[138:139], v[136:137] op_sel_hi:[1,0]
	global_load_dwordx4 v[104:107], v[114:115], off
	global_load_dwordx4 v[100:103], v[114:115], off offset:64
	v_pk_fma_f32 v[138:139], v[196:197], v[138:139], v[200:201]
	s_waitcnt vmcnt(10)
	v_lshlrev_b32_e32 v113, 16, v140
	v_pk_fma_f32 v[92:93], v[92:93], 0.5, v[138:139] op_sel_hi:[1,0,1]
	v_and_b32_e32 v138, 0xffff0000, v140
	v_lshlrev_b32_e32 v140, 16, v141
	v_and_b32_e32 v141, 0xffff0000, v141
	v_sub_f32_e32 v145, v145, v137
	v_sub_f32_e32 v144, v144, v137
	v_sub_f32_e32 v139, v138, v137
	v_sub_f32_e32 v138, v113, v137
	v_sub_f32_e32 v141, v141, v137
	v_sub_f32_e32 v140, v140, v137
	v_pk_mul_f32 v[144:145], v[144:145], v[136:137] op_sel_hi:[1,0]
	v_pk_mul_f32 v[140:141], v[140:141], v[136:137] op_sel_hi:[1,0]
	v_pk_mul_f32 v[138:139], v[138:139], v[136:137] op_sel_hi:[1,0]
	v_pk_fma_f32 v[144:145], v[190:191], v[144:145], v[202:203]
	v_pk_fma_f32 v[138:139], v[208:209], v[138:139], v[220:221]
	v_pk_fma_f32 v[140:141], v[206:207], v[140:141], v[218:219]
	v_pk_fma_f32 v[98:99], v[98:99], 0.5, v[144:145] op_sel_hi:[1,0,1]
	v_lshlrev_b32_e32 v144, 16, v151
	v_and_b32_e32 v145, 0xffff0000, v151
	v_pk_fma_f32 v[90:91], v[90:91], 0.5, v[140:141] op_sel_hi:[1,0,1]
	v_pk_fma_f32 v[88:89], v[88:89], 0.5, v[138:139] op_sel_hi:[1,0,1]
	v_lshlrev_b32_e32 v113, 16, v142
	v_and_b32_e32 v138, 0xffff0000, v142
	v_lshlrev_b32_e32 v140, 16, v143
	v_and_b32_e32 v141, 0xffff0000, v143
	v_sub_f32_e32 v145, v145, v137
	v_sub_f32_e32 v144, v144, v137
	v_sub_f32_e32 v139, v138, v137
	v_sub_f32_e32 v138, v113, v137
	v_sub_f32_e32 v141, v141, v137
	v_sub_f32_e32 v140, v140, v137
	v_pk_mul_f32 v[144:145], v[144:145], v[136:137] op_sel_hi:[1,0]
	v_pk_mul_f32 v[140:141], v[140:141], v[136:137] op_sel_hi:[1,0]
	v_pk_mul_f32 v[136:137], v[138:139], v[136:137] op_sel_hi:[1,0]
	v_pk_fma_f32 v[144:145], v[194:195], v[144:145], v[198:199]
	v_pk_fma_f32 v[136:137], v[212:213], v[136:137], v[216:217]
	v_pk_fma_f32 v[138:139], v[210:211], v[140:141], v[214:215]
	v_pk_fma_f32 v[94:95], v[94:95], 0.5, v[144:145] op_sel_hi:[1,0,1]
	v_pk_fma_f32 v[138:139], v[86:87], 0.5, v[138:139] op_sel_hi:[1,0,1]
	v_pk_fma_f32 v[136:137], v[84:85], 0.5, v[136:137] op_sel_hi:[1,0,1]
	v_cvt_pk_bf16_f32 v84, v96, v97
	v_cvt_pk_bf16_f32 v85, v98, v99
	v_cvt_pk_bf16_f32 v86, v92, v93
	v_cvt_pk_bf16_f32 v87, v94, v95
	global_store_dwordx4 v[226:227], v[84:87], off
	v_pk_add_f32 v[140:141], v[88:89], v[136:137]
	v_pk_add_f32 v[142:143], v[90:91], v[138:139]
	v_cvt_pk_bf16_f32 v84, v88, v89
	v_cvt_pk_bf16_f32 v85, v90, v91
	v_cvt_pk_bf16_f32 v86, v136, v137
	v_cvt_pk_bf16_f32 v87, v138, v139
	global_store_dwordx4 v[226:227], v[84:87], off offset:64
	ds_bpermute_b32 v159, v158, v157
	ds_bpermute_b32 v135, v158, v134
	v_pk_add_f32 v[84:85], v[96:97], v[92:93]
	v_pk_add_f32 v[86:87], v[98:99], v[94:95]
	v_pk_mul_f32 v[94:95], v[94:95], v[94:95]
	v_pk_mul_f32 v[92:93], v[92:93], v[92:93]
	v_pk_fma_f32 v[94:95], v[98:99], v[98:99], v[94:95]
	v_pk_fma_f32 v[92:93], v[96:97], v[96:97], v[92:93]
	v_pk_mul_f32 v[96:97], v[138:139], v[138:139]
	v_pk_mul_f32 v[98:99], v[136:137], v[136:137]
	v_pk_add_f32 v[86:87], v[86:87], v[142:143]
	v_pk_add_f32 v[84:85], v[84:85], v[140:141]
	v_pk_fma_f32 v[88:89], v[88:89], v[88:89], v[98:99]
	v_pk_fma_f32 v[90:91], v[90:91], v[90:91], v[96:97]
	v_pk_add_f32 v[88:89], v[92:93], v[88:89]
	v_pk_add_f32 v[90:91], v[94:95], v[90:91]
	v_add_f32_e32 v84, v84, v85
	v_add_f32_e32 v85, v86, v87
	v_add_f32_e32 v84, v84, v85
	v_add_f32_e32 v85, v88, v89
	v_add_f32_e32 v86, v90, v91
	v_add_f32_e32 v85, v85, v86
	ds_bpermute_b32 v86, v156, v84
	s_waitcnt vmcnt(9)
	v_cvt_f32_i32_e32 v139, v125
	v_cvt_f32_i32_e32 v138, v127
	v_cvt_f32_u32_e32 v125, v124
	v_cvt_f32_u32_e32 v124, v126
	s_waitcnt lgkmcnt(0)
	v_add_f32_e32 v98, v84, v86
	ds_bpermute_b32 v84, v156, v85
	s_waitcnt vmcnt(8)
	v_lshlrev_b32_e32 v126, 16, v120
	v_pk_fma_f32 v[124:125], v[138:139], s[30:31], v[124:125] op_sel_hi:[1,0,1]
	v_and_b32_e32 v120, 0xffff0000, v120
	v_pk_mul_f32 v[124:125], v[124:125], s[90:91] op_sel_hi:[1,0]
	s_waitcnt lgkmcnt(0)
	v_add_f32_e32 v113, v85, v84
	v_add_u32_e32 v84, 0x90, v188
	v_ashrrev_i32_e32 v85, 31, v84
	v_lshl_add_u64 v[86:87], v[84:85], 4, s[14:15]
	v_pk_mul_f32 v[124:125], v[124:125], s[92:93] op_sel_hi:[1,0]
	global_load_dwordx4 v[92:95], v[86:87], off
	v_fma_f32 v124, -v125, v125, v124
	v_max_f32_e32 v124, 0, v124
	v_add_f32_e32 v124, 0x3727c5ac, v124
	v_rsq_f32_e32 v124, v124
	v_lshlrev_b32_e32 v137, 16, v121
	v_and_b32_e32 v127, 0xffff0000, v121
	v_sub_f32_e32 v121, v120, v125
	v_sub_f32_e32 v120, v126, v125
	v_pk_mul_f32 v[120:121], v[120:121], v[124:125] op_sel_hi:[1,0]
	v_lshlrev_b64 v[84:85], 12, v[84:85]
	v_pk_fma_f32 v[120:121], v[192:193], v[120:121], v[204:205]
	v_lshl_add_u64 v[84:85], s[0:1], 0, v[84:85]
	v_pk_fma_f32 v[80:81], v[80:81], 0.5, v[120:121] op_sel_hi:[1,0,1]
	v_lshlrev_b32_e32 v120, 16, v122
	v_and_b32_e32 v121, 0xffff0000, v122
	v_lshlrev_b32_e32 v122, 16, v123
	v_and_b32_e32 v123, 0xffff0000, v123
	v_sub_f32_e32 v121, v121, v125
	v_sub_f32_e32 v120, v120, v125
	v_sub_f32_e32 v123, v123, v125
	v_sub_f32_e32 v122, v122, v125
	v_pk_mul_f32 v[120:121], v[120:121], v[124:125] op_sel_hi:[1,0]
	v_lshl_add_u64 v[96:97], v[84:85], 0, v[222:223]
	v_pk_mul_f32 v[122:123], v[122:123], v[124:125] op_sel_hi:[1,0]
	v_pk_fma_f32 v[120:121], v[196:197], v[120:121], v[200:201]
	global_load_dwordx4 v[88:91], v[96:97], off
	global_load_dwordx4 v[84:87], v[96:97], off offset:64
	v_pk_fma_f32 v[122:123], v[194:195], v[122:123], v[198:199]
	v_pk_fma_f32 v[76:77], v[76:77], 0.5, v[120:121] op_sel_hi:[1,0,1]
	s_waitcnt vmcnt(10)
	v_lshlrev_b32_e32 v120, 16, v116
	v_and_b32_e32 v116, 0xffff0000, v116
	v_pk_fma_f32 v[78:79], v[78:79], 0.5, v[122:123] op_sel_hi:[1,0,1]
	v_lshlrev_b32_e32 v122, 16, v117
	v_and_b32_e32 v121, 0xffff0000, v117
	v_sub_f32_e32 v117, v116, v125
	v_sub_f32_e32 v116, v120, v125
	v_pk_mul_f32 v[116:117], v[116:117], v[124:125] op_sel_hi:[1,0]
	v_sub_f32_e32 v127, v127, v125
	v_pk_fma_f32 v[116:117], v[208:209], v[116:117], v[220:221]
	v_sub_f32_e32 v126, v137, v125
	v_pk_fma_f32 v[72:73], v[72:73], 0.5, v[116:117] op_sel_hi:[1,0,1]
	v_lshlrev_b32_e32 v116, 16, v118
	v_and_b32_e32 v117, 0xffff0000, v118
	v_lshlrev_b32_e32 v118, 16, v119
	v_and_b32_e32 v119, 0xffff0000, v119
	v_sub_f32_e32 v117, v117, v125
	v_sub_f32_e32 v116, v116, v125
	v_sub_f32_e32 v119, v119, v125
	v_sub_f32_e32 v118, v118, v125
	v_pk_mul_f32 v[126:127], v[126:127], v[124:125] op_sel_hi:[1,0]
	v_sub_f32_e32 v121, v121, v125
	v_sub_f32_e32 v120, v122, v125
	v_pk_mul_f32 v[118:119], v[118:119], v[124:125] op_sel_hi:[1,0]
	v_pk_mul_f32 v[116:117], v[116:117], v[124:125] op_sel_hi:[1,0]
	v_pk_fma_f32 v[126:127], v[190:191], v[126:127], v[202:203]
	v_pk_mul_f32 v[120:121], v[120:121], v[124:125] op_sel_hi:[1,0]
	v_pk_fma_f32 v[116:117], v[212:213], v[116:117], v[216:217]
	v_pk_fma_f32 v[118:119], v[210:211], v[118:119], v[214:215]
	v_pk_fma_f32 v[82:83], v[82:83], 0.5, v[126:127] op_sel_hi:[1,0,1]
	v_pk_fma_f32 v[120:121], v[206:207], v[120:121], v[218:219]
	v_pk_fma_f32 v[118:119], v[70:71], 0.5, v[118:119] op_sel_hi:[1,0,1]
	v_pk_fma_f32 v[116:117], v[68:69], 0.5, v[116:117] op_sel_hi:[1,0,1]
	v_cvt_pk_bf16_f32 v68, v80, v81
	v_cvt_pk_bf16_f32 v69, v82, v83
	v_cvt_pk_bf16_f32 v70, v76, v77
	v_cvt_pk_bf16_f32 v71, v78, v79
	v_pk_fma_f32 v[74:75], v[74:75], 0.5, v[120:121] op_sel_hi:[1,0,1]
	global_store_dwordx4 v[128:129], v[68:71], off
	v_pk_add_f32 v[120:121], v[72:73], v[116:117]
	v_pk_add_f32 v[122:123], v[74:75], v[118:119]
	v_cvt_pk_bf16_f32 v68, v72, v73
	v_cvt_pk_bf16_f32 v69, v74, v75
	v_cvt_pk_bf16_f32 v70, v116, v117
	v_cvt_pk_bf16_f32 v71, v118, v119
	global_store_dwordx4 v[128:129], v[68:71], off offset:64
	ds_bpermute_b32 v136, v158, v113
	ds_bpermute_b32 v133, v158, v132
	v_pk_add_f32 v[68:69], v[80:81], v[76:77]
	v_pk_add_f32 v[70:71], v[82:83], v[78:79]
	v_pk_mul_f32 v[78:79], v[78:79], v[78:79]
	v_pk_mul_f32 v[76:77], v[76:77], v[76:77]
	v_pk_fma_f32 v[78:79], v[82:83], v[82:83], v[78:79]
	v_pk_fma_f32 v[76:77], v[80:81], v[80:81], v[76:77]
	v_pk_mul_f32 v[80:81], v[118:119], v[118:119]
	v_pk_mul_f32 v[82:83], v[116:117], v[116:117]
	v_pk_add_f32 v[70:71], v[70:71], v[122:123]
	v_pk_add_f32 v[68:69], v[68:69], v[120:121]
	v_pk_fma_f32 v[72:73], v[72:73], v[72:73], v[82:83]
	v_pk_fma_f32 v[74:75], v[74:75], v[74:75], v[80:81]
	v_pk_add_f32 v[72:73], v[76:77], v[72:73]
	v_pk_add_f32 v[74:75], v[78:79], v[74:75]
	v_add_f32_e32 v68, v68, v69
	v_add_f32_e32 v69, v70, v71
	v_add_f32_e32 v68, v68, v69
	v_add_f32_e32 v69, v72, v73
	v_add_f32_e32 v70, v74, v75
	v_add_f32_e32 v69, v69, v70
	ds_bpermute_b32 v70, v156, v68
	s_waitcnt vmcnt(9)
	v_cvt_f32_i32_e32 v119, v109
	v_cvt_f32_i32_e32 v118, v111
	v_cvt_f32_u32_e32 v109, v108
	v_cvt_f32_u32_e32 v108, v110
	s_waitcnt lgkmcnt(0)
	v_add_f32_e32 v82, v68, v70
	ds_bpermute_b32 v68, v156, v69
	s_waitcnt vmcnt(8)
	v_lshlrev_b32_e32 v110, 16, v104
	v_pk_fma_f32 v[108:109], v[118:119], s[30:31], v[108:109] op_sel_hi:[1,0,1]
	v_and_b32_e32 v104, 0xffff0000, v104
	v_pk_mul_f32 v[108:109], v[108:109], s[90:91] op_sel_hi:[1,0]
	s_waitcnt lgkmcnt(0)
	v_add_f32_e32 v116, v69, v68
	v_add_u32_e32 v68, 0xa0, v188
	v_ashrrev_i32_e32 v69, 31, v68
	v_lshl_add_u64 v[70:71], v[68:69], 4, s[14:15]
	global_load_dwordx4 v[76:79], v[70:71], off
	v_pk_mul_f32 v[108:109], v[108:109], s[92:93] op_sel_hi:[1,0]
	v_lshlrev_b64 v[68:69], 12, v[68:69]
	v_fma_f32 v108, -v109, v109, v108
	v_max_f32_e32 v108, 0, v108
	v_add_f32_e32 v108, 0x3727c5ac, v108
	v_rsq_f32_e32 v108, v108
	v_lshlrev_b32_e32 v118, 16, v105
	v_and_b32_e32 v111, 0xffff0000, v105
	v_sub_f32_e32 v105, v104, v109
	v_sub_f32_e32 v104, v110, v109
	v_lshl_add_u64 v[68:69], s[0:1], 0, v[68:69]
	v_pk_mul_f32 v[104:105], v[104:105], v[108:109] op_sel_hi:[1,0]
	v_lshl_add_u64 v[80:81], v[68:69], 0, v[222:223]
	v_pk_fma_f32 v[104:105], v[192:193], v[104:105], v[204:205]
	global_load_dwordx4 v[72:75], v[80:81], off
	global_load_dwordx4 v[68:71], v[80:81], off offset:64
	v_pk_fma_f32 v[64:65], v[64:65], 0.5, v[104:105] op_sel_hi:[1,0,1]
	v_lshlrev_b32_e32 v104, 16, v106
	v_and_b32_e32 v105, 0xffff0000, v106
	v_lshlrev_b32_e32 v106, 16, v107
	v_and_b32_e32 v107, 0xffff0000, v107
	v_sub_f32_e32 v105, v105, v109
	v_sub_f32_e32 v104, v104, v109
	v_sub_f32_e32 v107, v107, v109
	v_sub_f32_e32 v106, v106, v109
	v_pk_mul_f32 v[104:105], v[104:105], v[108:109] op_sel_hi:[1,0]
	v_pk_mul_f32 v[106:107], v[106:107], v[108:109] op_sel_hi:[1,0]
	v_pk_fma_f32 v[104:105], v[196:197], v[104:105], v[200:201]
	v_pk_fma_f32 v[106:107], v[194:195], v[106:107], v[198:199]
	v_pk_fma_f32 v[60:61], v[60:61], 0.5, v[104:105] op_sel_hi:[1,0,1]
	s_waitcnt vmcnt(10)
	v_lshlrev_b32_e32 v104, 16, v100
	v_and_b32_e32 v100, 0xffff0000, v100
	v_pk_fma_f32 v[62:63], v[62:63], 0.5, v[106:107] op_sel_hi:[1,0,1]
	v_lshlrev_b32_e32 v106, 16, v101
	v_and_b32_e32 v105, 0xffff0000, v101
	v_sub_f32_e32 v101, v100, v109
	v_sub_f32_e32 v100, v104, v109
	v_pk_mul_f32 v[100:101], v[100:101], v[108:109] op_sel_hi:[1,0]
	v_sub_f32_e32 v111, v111, v109
	v_pk_fma_f32 v[100:101], v[208:209], v[100:101], v[220:221]
	v_sub_f32_e32 v110, v118, v109
	v_pk_fma_f32 v[56:57], v[56:57], 0.5, v[100:101] op_sel_hi:[1,0,1]
	v_lshlrev_b32_e32 v100, 16, v102
	v_and_b32_e32 v101, 0xffff0000, v102
	v_lshlrev_b32_e32 v102, 16, v103
	v_and_b32_e32 v103, 0xffff0000, v103
	v_sub_f32_e32 v101, v101, v109
	v_sub_f32_e32 v100, v100, v109
	v_sub_f32_e32 v103, v103, v109
	v_sub_f32_e32 v102, v102, v109
	v_pk_mul_f32 v[110:111], v[110:111], v[108:109] op_sel_hi:[1,0]
	v_sub_f32_e32 v105, v105, v109
	v_sub_f32_e32 v104, v106, v109
	v_pk_mul_f32 v[102:103], v[102:103], v[108:109] op_sel_hi:[1,0]
	v_pk_mul_f32 v[100:101], v[100:101], v[108:109] op_sel_hi:[1,0]
	v_pk_fma_f32 v[110:111], v[190:191], v[110:111], v[202:203]
	v_pk_mul_f32 v[104:105], v[104:105], v[108:109] op_sel_hi:[1,0]
	v_pk_fma_f32 v[100:101], v[212:213], v[100:101], v[216:217]
	v_pk_fma_f32 v[102:103], v[210:211], v[102:103], v[214:215]
	v_pk_fma_f32 v[66:67], v[66:67], 0.5, v[110:111] op_sel_hi:[1,0,1]
	v_pk_fma_f32 v[104:105], v[206:207], v[104:105], v[218:219]
	v_pk_fma_f32 v[102:103], v[54:55], 0.5, v[102:103] op_sel_hi:[1,0,1]
	v_pk_fma_f32 v[100:101], v[52:53], 0.5, v[100:101] op_sel_hi:[1,0,1]
	v_cvt_pk_bf16_f32 v52, v64, v65
	v_cvt_pk_bf16_f32 v53, v66, v67
	v_cvt_pk_bf16_f32 v54, v60, v61
	v_cvt_pk_bf16_f32 v55, v62, v63
	v_pk_fma_f32 v[58:59], v[58:59], 0.5, v[104:105] op_sel_hi:[1,0,1]
	global_store_dwordx4 v[114:115], v[52:55], off
	v_pk_add_f32 v[104:105], v[56:57], v[100:101]
	v_pk_add_f32 v[106:107], v[58:59], v[102:103]
	v_cvt_pk_bf16_f32 v52, v56, v57
	v_cvt_pk_bf16_f32 v53, v58, v59
	v_cvt_pk_bf16_f32 v54, v100, v101
	v_cvt_pk_bf16_f32 v55, v102, v103
	global_store_dwordx4 v[114:115], v[52:55], off offset:64
	ds_bpermute_b32 v117, v158, v116
	ds_bpermute_b32 v99, v158, v98
	v_pk_add_f32 v[52:53], v[64:65], v[60:61]
	v_pk_add_f32 v[54:55], v[66:67], v[62:63]
	v_pk_mul_f32 v[62:63], v[62:63], v[62:63]
	v_pk_mul_f32 v[60:61], v[60:61], v[60:61]
	v_pk_fma_f32 v[62:63], v[66:67], v[66:67], v[62:63]
	v_pk_fma_f32 v[60:61], v[64:65], v[64:65], v[60:61]
	v_pk_mul_f32 v[64:65], v[102:103], v[102:103]
	v_pk_mul_f32 v[66:67], v[100:101], v[100:101]
	v_pk_add_f32 v[54:55], v[54:55], v[106:107]
	v_pk_add_f32 v[52:53], v[52:53], v[104:105]
	v_pk_fma_f32 v[56:57], v[56:57], v[56:57], v[66:67]
	v_pk_fma_f32 v[58:59], v[58:59], v[58:59], v[64:65]
	v_pk_add_f32 v[56:57], v[60:61], v[56:57]
	v_pk_add_f32 v[58:59], v[62:63], v[58:59]
	v_add_f32_e32 v52, v52, v53
	v_add_f32_e32 v53, v54, v55
	v_add_f32_e32 v52, v52, v53
	v_add_f32_e32 v53, v56, v57
	v_add_f32_e32 v54, v58, v59
	v_add_f32_e32 v53, v53, v54
	ds_bpermute_b32 v54, v156, v52
	s_waitcnt vmcnt(9)
	v_cvt_f32_i32_e32 v103, v93
	v_cvt_f32_i32_e32 v102, v95
	v_cvt_f32_u32_e32 v93, v92
	v_cvt_f32_u32_e32 v92, v94
	s_waitcnt lgkmcnt(0)
	v_add_f32_e32 v66, v52, v54
	ds_bpermute_b32 v52, v156, v53
	s_waitcnt vmcnt(8)
	v_lshlrev_b32_e32 v94, 16, v88
	v_pk_fma_f32 v[92:93], v[102:103], s[30:31], v[92:93] op_sel_hi:[1,0,1]
	v_and_b32_e32 v88, 0xffff0000, v88
	v_pk_mul_f32 v[92:93], v[92:93], s[90:91] op_sel_hi:[1,0]
	s_waitcnt lgkmcnt(0)
	v_add_f32_e32 v100, v53, v52
	v_add_u32_e32 v52, 0xb0, v188
	v_ashrrev_i32_e32 v53, 31, v52
	v_lshl_add_u64 v[54:55], v[52:53], 4, s[14:15]
	global_load_dwordx4 v[60:63], v[54:55], off
	v_pk_mul_f32 v[92:93], v[92:93], s[92:93] op_sel_hi:[1,0]
	v_lshlrev_b32_e32 v102, 16, v89
	v_fma_f32 v92, -v93, v93, v92
	v_max_f32_e32 v92, 0, v92
	v_add_f32_e32 v92, 0x3727c5ac, v92
	v_rsq_f32_e32 v92, v92
	v_and_b32_e32 v95, 0xffff0000, v89
	v_sub_f32_e32 v89, v88, v93
	v_sub_f32_e32 v88, v94, v93
	v_pk_mul_f32 v[88:89], v[88:89], v[92:93] op_sel_hi:[1,0]
	v_lshlrev_b64 v[52:53], 12, v[52:53]
	v_pk_fma_f32 v[88:89], v[192:193], v[88:89], v[204:205]
	v_lshl_add_u64 v[52:53], s[0:1], 0, v[52:53]
	v_pk_fma_f32 v[48:49], v[48:49], 0.5, v[88:89] op_sel_hi:[1,0,1]
	v_lshlrev_b32_e32 v88, 16, v90
	v_and_b32_e32 v89, 0xffff0000, v90
	v_lshlrev_b32_e32 v90, 16, v91
	v_and_b32_e32 v91, 0xffff0000, v91
	v_sub_f32_e32 v89, v89, v93
	v_sub_f32_e32 v88, v88, v93
	v_lshl_add_u64 v[64:65], v[52:53], 0, v[222:223]
	v_sub_f32_e32 v91, v91, v93
	v_sub_f32_e32 v90, v90, v93
	v_pk_mul_f32 v[88:89], v[88:89], v[92:93] op_sel_hi:[1,0]
	global_load_dwordx4 v[56:59], v[64:65], off
	global_load_dwordx4 v[52:55], v[64:65], off offset:64
	v_pk_mul_f32 v[90:91], v[90:91], v[92:93] op_sel_hi:[1,0]
	v_pk_fma_f32 v[88:89], v[196:197], v[88:89], v[200:201]
	v_pk_fma_f32 v[90:91], v[194:195], v[90:91], v[198:199]
	v_pk_fma_f32 v[44:45], v[44:45], 0.5, v[88:89] op_sel_hi:[1,0,1]
	s_waitcnt vmcnt(10)
	v_lshlrev_b32_e32 v88, 16, v84
	v_and_b32_e32 v84, 0xffff0000, v84
	v_pk_fma_f32 v[46:47], v[46:47], 0.5, v[90:91] op_sel_hi:[1,0,1]
	v_lshlrev_b32_e32 v90, 16, v85
	v_and_b32_e32 v89, 0xffff0000, v85
	v_sub_f32_e32 v85, v84, v93
	v_sub_f32_e32 v84, v88, v93
	v_pk_mul_f32 v[84:85], v[84:85], v[92:93] op_sel_hi:[1,0]
	v_sub_f32_e32 v95, v95, v93
	v_pk_fma_f32 v[84:85], v[208:209], v[84:85], v[220:221]
	v_sub_f32_e32 v94, v102, v93
	v_pk_fma_f32 v[40:41], v[40:41], 0.5, v[84:85] op_sel_hi:[1,0,1]
	v_lshlrev_b32_e32 v84, 16, v86
	v_and_b32_e32 v85, 0xffff0000, v86
	v_lshlrev_b32_e32 v86, 16, v87
	v_and_b32_e32 v87, 0xffff0000, v87
	v_sub_f32_e32 v85, v85, v93
	v_sub_f32_e32 v84, v84, v93
	v_sub_f32_e32 v87, v87, v93
	v_sub_f32_e32 v86, v86, v93
	v_pk_mul_f32 v[94:95], v[94:95], v[92:93] op_sel_hi:[1,0]
	v_sub_f32_e32 v89, v89, v93
	v_sub_f32_e32 v88, v90, v93
	v_pk_mul_f32 v[86:87], v[86:87], v[92:93] op_sel_hi:[1,0]
	v_pk_mul_f32 v[84:85], v[84:85], v[92:93] op_sel_hi:[1,0]
	v_pk_fma_f32 v[94:95], v[190:191], v[94:95], v[202:203]
	v_pk_mul_f32 v[88:89], v[88:89], v[92:93] op_sel_hi:[1,0]
	v_pk_fma_f32 v[84:85], v[212:213], v[84:85], v[216:217]
	v_pk_fma_f32 v[86:87], v[210:211], v[86:87], v[214:215]
	v_pk_fma_f32 v[50:51], v[50:51], 0.5, v[94:95] op_sel_hi:[1,0,1]
	v_pk_fma_f32 v[88:89], v[206:207], v[88:89], v[218:219]
	v_pk_fma_f32 v[86:87], v[38:39], 0.5, v[86:87] op_sel_hi:[1,0,1]
	v_pk_fma_f32 v[84:85], v[36:37], 0.5, v[84:85] op_sel_hi:[1,0,1]
	v_cvt_pk_bf16_f32 v36, v48, v49
	v_cvt_pk_bf16_f32 v37, v50, v51
	v_cvt_pk_bf16_f32 v38, v44, v45
	v_cvt_pk_bf16_f32 v39, v46, v47
	v_pk_fma_f32 v[42:43], v[42:43], 0.5, v[88:89] op_sel_hi:[1,0,1]
	global_store_dwordx4 v[96:97], v[36:39], off
	v_pk_add_f32 v[88:89], v[40:41], v[84:85]
	v_pk_add_f32 v[90:91], v[42:43], v[86:87]
	v_cvt_pk_bf16_f32 v36, v40, v41
	v_cvt_pk_bf16_f32 v37, v42, v43
	v_cvt_pk_bf16_f32 v38, v84, v85
	v_cvt_pk_bf16_f32 v39, v86, v87
	global_store_dwordx4 v[96:97], v[36:39], off offset:64
	ds_bpermute_b32 v101, v158, v100
	ds_bpermute_b32 v67, v158, v66
	v_pk_add_f32 v[36:37], v[48:49], v[44:45]
	v_pk_add_f32 v[38:39], v[50:51], v[46:47]
	v_pk_mul_f32 v[46:47], v[46:47], v[46:47]
	v_pk_mul_f32 v[44:45], v[44:45], v[44:45]
	v_pk_fma_f32 v[46:47], v[50:51], v[50:51], v[46:47]
	v_pk_fma_f32 v[44:45], v[48:49], v[48:49], v[44:45]
	v_pk_mul_f32 v[48:49], v[86:87], v[86:87]
	v_pk_mul_f32 v[50:51], v[84:85], v[84:85]
	v_pk_add_f32 v[38:39], v[38:39], v[90:91]
	v_pk_add_f32 v[36:37], v[36:37], v[88:89]
	v_pk_fma_f32 v[40:41], v[40:41], v[40:41], v[50:51]
	v_pk_fma_f32 v[42:43], v[42:43], v[42:43], v[48:49]
	v_pk_add_f32 v[40:41], v[44:45], v[40:41]
	v_pk_add_f32 v[42:43], v[46:47], v[42:43]
	v_add_f32_e32 v36, v36, v37
	v_add_f32_e32 v37, v38, v39
	v_add_f32_e32 v36, v36, v37
	v_add_f32_e32 v37, v40, v41
	v_add_f32_e32 v38, v42, v43
	v_add_f32_e32 v38, v37, v38
	ds_bpermute_b32 v39, v156, v38
	s_waitcnt vmcnt(9)
	v_cvt_f32_u32_e32 v41, v76
	v_cvt_f32_u32_e32 v40, v78
	s_waitcnt vmcnt(8)
	v_lshlrev_b32_e32 v42, 16, v73
	v_and_b32_e32 v43, 0xffff0000, v73
	s_waitcnt lgkmcnt(0)
	v_add_f32_e32 v46, v38, v39
	v_cvt_f32_i32_e32 v39, v77
	v_cvt_f32_i32_e32 v38, v79
	ds_bpermute_b32 v37, v156, v36
	ds_bpermute_b32 v47, v158, v46
	ds_bpermute_b32 v83, v158, v82
	v_pk_fma_f32 v[38:39], v[38:39], s[30:31], v[40:41] op_sel_hi:[1,0,1]
	v_lshlrev_b32_e32 v40, 16, v72
	v_pk_mul_f32 v[38:39], v[38:39], s[90:91] op_sel_hi:[1,0]
	v_and_b32_e32 v41, 0xffff0000, v72
	v_pk_mul_f32 v[38:39], v[38:39], s[92:93] op_sel_hi:[1,0]
	s_waitcnt lgkmcnt(2)
	v_add_f32_e32 v36, v36, v37
	v_fma_f32 v38, -v39, v39, v38
	v_max_f32_e32 v38, 0, v38
	v_add_f32_e32 v38, 0x3727c5ac, v38
	v_rsq_f32_e32 v38, v38
	v_sub_f32_e32 v41, v41, v39
	v_sub_f32_e32 v40, v40, v39
	v_sub_f32_e32 v43, v43, v39
	v_sub_f32_e32 v42, v42, v39
	v_pk_mul_f32 v[42:43], v[42:43], v[38:39] op_sel_hi:[1,0]
	v_pk_mul_f32 v[40:41], v[40:41], v[38:39] op_sel_hi:[1,0]
	v_pk_fma_f32 v[42:43], v[190:191], v[42:43], v[202:203]
	v_pk_fma_f32 v[40:41], v[192:193], v[40:41], v[204:205]
	v_pk_fma_f32 v[34:35], v[34:35], 0.5, v[42:43] op_sel_hi:[1,0,1]
	v_pk_fma_f32 v[32:33], v[32:33], 0.5, v[40:41] op_sel_hi:[1,0,1]
	v_lshlrev_b32_e32 v40, 16, v74
	v_and_b32_e32 v41, 0xffff0000, v74
	v_lshlrev_b32_e32 v42, 16, v75
	v_and_b32_e32 v43, 0xffff0000, v75
	v_sub_f32_e32 v41, v41, v39
	v_sub_f32_e32 v40, v40, v39
	v_sub_f32_e32 v43, v43, v39
	v_sub_f32_e32 v42, v42, v39
	v_pk_mul_f32 v[42:43], v[42:43], v[38:39] op_sel_hi:[1,0]
	v_pk_mul_f32 v[40:41], v[40:41], v[38:39] op_sel_hi:[1,0]
	v_pk_fma_f32 v[42:43], v[194:195], v[42:43], v[198:199]
	v_pk_fma_f32 v[40:41], v[196:197], v[40:41], v[200:201]
	v_pk_fma_f32 v[30:31], v[30:31], 0.5, v[42:43] op_sel_hi:[1,0,1]
	v_pk_fma_f32 v[28:29], v[28:29], 0.5, v[40:41] op_sel_hi:[1,0,1]
	s_waitcnt vmcnt(7)
	v_lshlrev_b32_e32 v40, 16, v68
	v_and_b32_e32 v41, 0xffff0000, v68
	v_lshlrev_b32_e32 v42, 16, v69
	v_and_b32_e32 v43, 0xffff0000, v69
	v_sub_f32_e32 v41, v41, v39
	v_sub_f32_e32 v40, v40, v39
	v_sub_f32_e32 v43, v43, v39
	v_sub_f32_e32 v42, v42, v39
	v_pk_mul_f32 v[42:43], v[42:43], v[38:39] op_sel_hi:[1,0]
	v_pk_mul_f32 v[40:41], v[40:41], v[38:39] op_sel_hi:[1,0]
	v_pk_fma_f32 v[42:43], v[206:207], v[42:43], v[218:219]
	v_pk_fma_f32 v[40:41], v[208:209], v[40:41], v[220:221]
	v_pk_fma_f32 v[26:27], v[26:27], 0.5, v[42:43] op_sel_hi:[1,0,1]
	v_pk_fma_f32 v[24:25], v[24:25], 0.5, v[40:41] op_sel_hi:[1,0,1]
	v_lshlrev_b32_e32 v40, 16, v70
	v_and_b32_e32 v41, 0xffff0000, v70
	v_lshlrev_b32_e32 v42, 16, v71
	v_and_b32_e32 v43, 0xffff0000, v71
	v_sub_f32_e32 v41, v41, v39
	v_sub_f32_e32 v40, v40, v39
	v_sub_f32_e32 v43, v43, v39
	v_sub_f32_e32 v42, v42, v39
	v_pk_mul_f32 v[42:43], v[42:43], v[38:39] op_sel_hi:[1,0]
	v_pk_mul_f32 v[38:39], v[40:41], v[38:39] op_sel_hi:[1,0]
	v_pk_fma_f32 v[40:41], v[210:211], v[42:43], v[214:215]
	v_pk_fma_f32 v[38:39], v[212:213], v[38:39], v[216:217]
	v_pk_fma_f32 v[40:41], v[22:23], 0.5, v[40:41] op_sel_hi:[1,0,1]
	v_pk_fma_f32 v[38:39], v[20:21], 0.5, v[38:39] op_sel_hi:[1,0,1]
	v_cvt_pk_bf16_f32 v20, v32, v33
	v_cvt_pk_bf16_f32 v21, v34, v35
	v_cvt_pk_bf16_f32 v22, v28, v29
	v_cvt_pk_bf16_f32 v23, v30, v31
	global_store_dwordx4 v[80:81], v[20:23], off
	v_pk_add_f32 v[42:43], v[24:25], v[38:39]
	v_pk_add_f32 v[44:45], v[26:27], v[40:41]
	v_cvt_pk_bf16_f32 v20, v24, v25
	v_cvt_pk_bf16_f32 v21, v26, v27
	v_cvt_pk_bf16_f32 v22, v38, v39
	v_cvt_pk_bf16_f32 v23, v40, v41
	global_store_dwordx4 v[80:81], v[20:23], off offset:64
	ds_bpermute_b32 v37, v158, v36
	s_nop 0
	v_pk_add_f32 v[20:21], v[32:33], v[28:29]
	v_pk_add_f32 v[22:23], v[34:35], v[30:31]
	v_pk_mul_f32 v[30:31], v[30:31], v[30:31]
	v_pk_mul_f32 v[28:29], v[28:29], v[28:29]
	v_pk_fma_f32 v[30:31], v[34:35], v[34:35], v[30:31]
	v_pk_fma_f32 v[28:29], v[32:33], v[32:33], v[28:29]
	v_pk_mul_f32 v[32:33], v[40:41], v[40:41]
	v_pk_mul_f32 v[34:35], v[38:39], v[38:39]
	v_pk_add_f32 v[22:23], v[22:23], v[44:45]
	v_pk_add_f32 v[20:21], v[20:21], v[42:43]
	v_pk_fma_f32 v[24:25], v[24:25], v[24:25], v[34:35]
	v_pk_fma_f32 v[26:27], v[26:27], v[26:27], v[32:33]
	v_pk_add_f32 v[24:25], v[28:29], v[24:25]
	v_pk_add_f32 v[26:27], v[30:31], v[26:27]
	v_add_f32_e32 v20, v20, v21
	v_add_f32_e32 v21, v22, v23
	v_add_f32_e32 v20, v20, v21
	v_add_f32_e32 v21, v24, v25
	v_add_f32_e32 v22, v26, v27
	v_add_f32_e32 v21, v21, v22
	ds_bpermute_b32 v22, v156, v20
	s_waitcnt vmcnt(6)
	v_cvt_f32_u32_e32 v23, v60
	s_waitcnt vmcnt(5)
	v_lshlrev_b32_e32 v24, 16, v57
	v_and_b32_e32 v25, 0xffff0000, v57
	s_waitcnt lgkmcnt(0)
	v_add_f32_e32 v28, v20, v22
	ds_bpermute_b32 v20, v156, v21
	v_cvt_f32_u32_e32 v22, v62
	ds_bpermute_b32 v29, v158, v28
	s_waitcnt lgkmcnt(1)
	v_add_f32_e32 v30, v21, v20
	v_cvt_f32_i32_e32 v21, v61
	v_cvt_f32_i32_e32 v20, v63
	ds_bpermute_b32 v31, v158, v30
	v_pk_fma_f32 v[20:21], v[20:21], s[30:31], v[22:23] op_sel_hi:[1,0,1]
	s_nop 0
	v_pk_mul_f32 v[20:21], v[20:21], s[90:91] op_sel_hi:[1,0]
	v_lshlrev_b32_e32 v22, 16, v56
	v_pk_mul_f32 v[20:21], v[20:21], s[92:93] op_sel_hi:[1,0]
	v_and_b32_e32 v23, 0xffff0000, v56
	v_fma_f32 v20, -v21, v21, v20
	v_max_f32_e32 v20, 0, v20
	v_add_f32_e32 v20, 0x3727c5ac, v20
	v_rsq_f32_e32 v20, v20
	v_sub_f32_e32 v23, v23, v21
	v_sub_f32_e32 v22, v22, v21
	v_sub_f32_e32 v25, v25, v21
	v_sub_f32_e32 v24, v24, v21
	v_pk_mul_f32 v[24:25], v[24:25], v[20:21] op_sel_hi:[1,0]
	v_pk_mul_f32 v[22:23], v[22:23], v[20:21] op_sel_hi:[1,0]
	v_pk_fma_f32 v[24:25], v[190:191], v[24:25], v[202:203]
	v_pk_fma_f32 v[22:23], v[192:193], v[22:23], v[204:205]
	v_pk_fma_f32 v[18:19], v[18:19], 0.5, v[24:25] op_sel_hi:[1,0,1]
	v_pk_fma_f32 v[16:17], v[16:17], 0.5, v[22:23] op_sel_hi:[1,0,1]
	v_lshlrev_b32_e32 v22, 16, v58
	v_and_b32_e32 v23, 0xffff0000, v58
	v_lshlrev_b32_e32 v24, 16, v59
	v_and_b32_e32 v25, 0xffff0000, v59
	v_sub_f32_e32 v23, v23, v21
	v_sub_f32_e32 v22, v22, v21
	v_sub_f32_e32 v25, v25, v21
	v_sub_f32_e32 v24, v24, v21
	v_pk_mul_f32 v[24:25], v[24:25], v[20:21] op_sel_hi:[1,0]
	v_pk_mul_f32 v[22:23], v[22:23], v[20:21] op_sel_hi:[1,0]
	v_pk_fma_f32 v[24:25], v[194:195], v[24:25], v[198:199]
	v_pk_fma_f32 v[22:23], v[196:197], v[22:23], v[200:201]
	v_pk_fma_f32 v[14:15], v[14:15], 0.5, v[24:25] op_sel_hi:[1,0,1]
	v_pk_fma_f32 v[12:13], v[12:13], 0.5, v[22:23] op_sel_hi:[1,0,1]
	s_waitcnt vmcnt(4)
	v_lshlrev_b32_e32 v22, 16, v52
	v_and_b32_e32 v23, 0xffff0000, v52
	v_lshlrev_b32_e32 v24, 16, v53
	v_and_b32_e32 v25, 0xffff0000, v53
	v_sub_f32_e32 v23, v23, v21
	v_sub_f32_e32 v22, v22, v21
	v_sub_f32_e32 v25, v25, v21
	v_sub_f32_e32 v24, v24, v21
	v_pk_mul_f32 v[24:25], v[24:25], v[20:21] op_sel_hi:[1,0]
	v_pk_mul_f32 v[22:23], v[22:23], v[20:21] op_sel_hi:[1,0]
	v_pk_fma_f32 v[24:25], v[206:207], v[24:25], v[218:219]
	v_pk_fma_f32 v[22:23], v[208:209], v[22:23], v[220:221]
	v_pk_fma_f32 v[10:11], v[10:11], 0.5, v[24:25] op_sel_hi:[1,0,1]
	v_pk_fma_f32 v[8:9], v[8:9], 0.5, v[22:23] op_sel_hi:[1,0,1]
	v_lshlrev_b32_e32 v22, 16, v54
	v_and_b32_e32 v23, 0xffff0000, v54
	v_lshlrev_b32_e32 v24, 16, v55
	v_and_b32_e32 v25, 0xffff0000, v55
	v_sub_f32_e32 v23, v23, v21
	v_sub_f32_e32 v22, v22, v21
	v_sub_f32_e32 v25, v25, v21
	v_sub_f32_e32 v24, v24, v21
	v_pk_mul_f32 v[24:25], v[24:25], v[20:21] op_sel_hi:[1,0]
	v_pk_mul_f32 v[20:21], v[22:23], v[20:21] op_sel_hi:[1,0]
	v_pk_fma_f32 v[22:23], v[210:211], v[24:25], v[214:215]
	v_pk_fma_f32 v[20:21], v[212:213], v[20:21], v[216:217]
	v_pk_fma_f32 v[22:23], v[6:7], 0.5, v[22:23] op_sel_hi:[1,0,1]
	v_pk_fma_f32 v[20:21], v[4:5], 0.5, v[20:21] op_sel_hi:[1,0,1]
	v_cvt_pk_bf16_f32 v4, v16, v17
	v_cvt_pk_bf16_f32 v5, v18, v19
	v_cvt_pk_bf16_f32 v6, v12, v13
	v_cvt_pk_bf16_f32 v7, v14, v15
	global_store_dwordx4 v[64:65], v[4:7], off
	v_pk_add_f32 v[24:25], v[8:9], v[20:21]
	v_pk_add_f32 v[26:27], v[10:11], v[22:23]
	v_cvt_pk_bf16_f32 v4, v8, v9
	v_cvt_pk_bf16_f32 v5, v10, v11
	v_cvt_pk_bf16_f32 v6, v20, v21
	v_cvt_pk_bf16_f32 v7, v22, v23
	global_store_dwordx4 v[64:65], v[4:7], off offset:64
	s_nop 1
	v_pk_add_f32 v[4:5], v[16:17], v[12:13]
	v_pk_add_f32 v[6:7], v[18:19], v[14:15]
	v_pk_mul_f32 v[14:15], v[14:15], v[14:15]
	v_pk_mul_f32 v[12:13], v[12:13], v[12:13]
	v_pk_fma_f32 v[14:15], v[18:19], v[18:19], v[14:15]
	v_pk_fma_f32 v[12:13], v[16:17], v[16:17], v[12:13]
	v_pk_mul_f32 v[16:17], v[22:23], v[22:23]
	v_pk_mul_f32 v[18:19], v[20:21], v[20:21]
	v_pk_add_f32 v[6:7], v[6:7], v[26:27]
	v_pk_add_f32 v[4:5], v[4:5], v[24:25]
	v_pk_fma_f32 v[8:9], v[8:9], v[8:9], v[18:19]
	v_pk_fma_f32 v[10:11], v[10:11], v[10:11], v[16:17]
	v_pk_add_f32 v[8:9], v[12:13], v[8:9]
	v_pk_add_f32 v[10:11], v[14:15], v[10:11]
	v_add_f32_e32 v4, v4, v5
	v_add_f32_e32 v5, v6, v7
	v_add_f32_e32 v4, v4, v5
	v_add_f32_e32 v5, v8, v9
	v_add_f32_e32 v6, v10, v11
	v_add_f32_e32 v5, v5, v6
	ds_bpermute_b32 v7, v156, v5
	ds_bpermute_b32 v6, v156, v4
	v_add_f32_e32 v9, v100, v101
	v_add_f32_e32 v8, v46, v47
	v_cndmask_b32_e64 v9, 0, v9, s[44:45]
	s_waitcnt lgkmcnt(1)
	v_add_f32_e32 v5, v5, v7
	ds_bpermute_b32 v7, v158, v5
	s_waitcnt lgkmcnt(1)
	v_add_f32_e32 v4, v4, v6
	ds_bpermute_b32 v6, v158, v4
	v_cndmask_b32_e64 v8, v9, v8, s[42:43]
	s_waitcnt lgkmcnt(1)
	v_add_f32_e32 v5, v5, v7
	v_add_f32_e32 v7, v30, v31
	v_cndmask_b32_e64 v7, v8, v7, s[40:41]
	v_cndmask_b32_e64 v10, v7, v5, s[38:39]
	v_add_f32_e32 v7, v66, v67
	s_waitcnt lgkmcnt(0)
	v_add_f32_e32 v4, v4, v6
	v_add_f32_e32 v6, v36, v37
	v_cndmask_b32_e64 v7, 0, v7, s[44:45]
	v_add_f32_e32 v5, v28, v29
	v_cndmask_b32_e64 v6, v7, v6, s[42:43]
	v_add_f32_e32 v7, v157, v159
	v_cndmask_b32_e64 v5, v6, v5, s[40:41]
	v_add_f32_e32 v6, v134, v135
	v_cndmask_b32_e64 v7, 0, v7, s[44:45]
	v_cndmask_b32_e64 v11, v5, v4, s[38:39]
	v_add_f32_e32 v5, v113, v136
	v_cndmask_b32_e64 v6, v7, v6, s[42:43]
	v_add_f32_e32 v7, v130, v131
	v_add_f32_e32 v4, v116, v117
	v_cndmask_b32_e64 v5, v6, v5, s[40:41]
	v_add_f32_e32 v6, v132, v133
	v_cndmask_b32_e64 v7, 0, v7, s[44:45]
	v_cndmask_b32_e64 v12, v5, v4, s[38:39]
	v_add_f32_e32 v5, v98, v99
	v_cndmask_b32_e64 v6, v7, v6, s[42:43]
	v_add_f32_e32 v4, v82, v83
	v_cndmask_b32_e64 v5, v6, v5, s[40:41]
	v_cndmask_b32_e64 v8, v5, v4, s[38:39]
	v_or_b32_e32 v4, v188, v243
	v_or_b32_e32 v6, v112, v243
	v_ashrrev_i32_e32 v5, 31, v4
	v_ashrrev_i32_e32 v7, 31, v6
	v_mul_f32_e32 v8, 0x4b800000, v8
	v_lshl_add_u64 v[4:5], v[4:5], 4, s[16:17]
	v_lshl_add_u64 v[6:7], v[6:7], 4, s[16:17]
	v_rndne_f32_e32 v8, v8
	s_mov_b32 s16, 0x2f800000
	v_mul_f32_e64 v9, |v8|, s16
	v_floor_f32_e32 v9, v9
	s_mov_b32 s17, 0xcf800000
	v_fma_f32 v13, v9, s17, |v8|
	v_cvt_u32_f32_e32 v13, v13
	v_cvt_u32_f32_e32 v9, v9
	v_ashrrev_i32_e32 v14, 31, v8
	v_xor_b32_e32 v8, v13, v14
	v_xor_b32_e32 v9, v9, v14
	v_sub_co_u32_e32 v8, vcc, v8, v14
	s_nop 1
	v_subb_co_u32_e32 v9, vcc, v9, v14, vcc
	global_atomic_add_x2 v[4:5], v[8:9], off
	v_mul_f32_e32 v8, 0x4b800000, v12
	v_rndne_f32_e32 v8, v8
	v_mul_f32_e64 v9, |v8|, s16
	v_floor_f32_e32 v9, v9
	v_fma_f32 v12, v9, s17, |v8|
	v_cvt_u32_f32_e32 v12, v12
	v_cvt_u32_f32_e32 v9, v9
	v_ashrrev_i32_e32 v13, 31, v8
	v_xor_b32_e32 v8, v12, v13
	v_xor_b32_e32 v9, v9, v13
	v_sub_co_u32_e32 v8, vcc, v8, v13
	s_nop 1
	v_subb_co_u32_e32 v9, vcc, v9, v13, vcc
	global_atomic_add_x2 v[4:5], v[8:9], off offset:8
	v_mul_f32_e32 v4, 0x4b800000, v11
	v_rndne_f32_e32 v4, v4
	v_mul_f32_e64 v5, |v4|, s16
	v_floor_f32_e32 v5, v5
	v_fma_f32 v8, v5, s17, |v4|
	v_cvt_u32_f32_e32 v8, v8
	v_cvt_u32_f32_e32 v5, v5
	v_ashrrev_i32_e32 v9, 31, v4
	v_xor_b32_e32 v4, v8, v9
	v_xor_b32_e32 v5, v5, v9
	v_sub_co_u32_e32 v4, vcc, v4, v9
	s_nop 1
	v_subb_co_u32_e32 v5, vcc, v5, v9, vcc
	global_atomic_add_x2 v[6:7], v[4:5], off
	v_mul_f32_e32 v4, 0x4b800000, v10
	v_rndne_f32_e32 v4, v4
	v_mul_f32_e64 v5, |v4|, s16
	v_floor_f32_e32 v5, v5
	v_fma_f32 v8, v5, s17, |v4|
	v_cvt_u32_f32_e32 v8, v8
	v_cvt_u32_f32_e32 v5, v5
	v_ashrrev_i32_e32 v9, 31, v4
	v_xor_b32_e32 v4, v8, v9
	v_xor_b32_e32 v5, v5, v9
	v_sub_co_u32_e32 v4, vcc, v4, v9
	s_nop 1
	v_subb_co_u32_e32 v5, vcc, v5, v9, vcc
	global_atomic_add_x2 v[6:7], v[4:5], off offset:8
	s_and_b64 vcc, exec, s[46:47]
	s_cbranch_vccnz .LBB0_358
	v_readlane_b32 s16, v252, 2
	v_readlane_b32 s17, v252, 3
	s_andn2_b64 vcc, exec, s[16:17]
	s_cbranch_vccnz .LBB0_357
	s_barrier
	s_branch .LBB0_357

.LBB0_449:
	v_lshl_or_b32 v132, s77, 8, v220
	v_ashrrev_i32_e32 v133, 31, v132
	v_lshlrev_b64 v[136:137], 2, v[132:133]
	v_lshl_add_u64 v[140:141], s[12:13], 0, v[136:137]
	v_lshl_add_u64 v[142:143], s[18:19], 0, v[136:137]
	global_load_dwordx4 v[132:135], v[140:141], off
	global_load_dwordx4 v[136:139], v[142:143], off
	global_load_dwordx4 v[166:169], v[140:141], off offset:16
	global_load_dwordx4 v[170:173], v[142:143], off offset:16
	global_load_dwordx4 v[184:187], v[140:141], off offset:512
	global_load_dwordx4 v[188:191], v[142:143], off offset:512
	global_load_dwordx4 v[192:195], v[140:141], off offset:528
	global_load_dwordx4 v[196:199], v[142:143], off offset:528
	v_lshl_add_u32 v174, s78, 8, v218
	v_readlane_b32 s28, v252, 10
	v_ashrrev_i32_e32 v175, 31, v174
	v_readlane_b32 s29, v252, 11
	v_or_b32_e32 v182, 16, v174
	v_or_b32_e32 v216, 32, v174
	v_lshl_add_u64 v[140:141], v[174:175], 4, s[28:29]
	global_load_dwordx4 v[222:225], v[140:141], off
	v_or_b32_e32 v214, 48, v174
	v_add_u32_e32 v212, 0x80, v174
	v_add_u32_e32 v210, 0x90, v174
	v_ashrrev_i32_e32 v183, 31, v182
	v_ashrrev_i32_e32 v217, 31, v216
	v_ashrrev_i32_e32 v215, 31, v214
	v_ashrrev_i32_e32 v213, 31, v212
	v_ashrrev_i32_e32 v211, 31, v210
	v_lshl_add_u64 v[140:141], v[182:183], 4, s[28:29]
	v_lshl_add_u64 v[142:143], v[216:217], 4, s[28:29]
	v_lshl_add_u64 v[144:145], v[214:215], 4, s[28:29]
	v_lshl_add_u64 v[146:147], v[212:213], 4, s[28:29]
	v_lshl_add_u64 v[200:201], v[210:211], 4, s[28:29]
	global_load_dwordx4 v[226:229], v[140:141], off
	global_load_dwordx4 v[242:245], v[142:143], off
	global_load_dwordx4 v[148:151], v[144:145], off
	s_nop 0
	global_load_dwordx4 v[144:147], v[146:147], off
	s_nop 0
	global_load_dwordx4 v[140:143], v[200:201], off
	s_brev_b32 s16, 44
	v_add_u32_e32 v208, 0xa0, v174
	v_add_u32_e32 v164, 0xb0, v174
	v_ashrrev_i32_e32 v209, 31, v208
	v_ashrrev_i32_e32 v165, 31, v164
	v_lshl_add_u64 v[246:247], v[208:209], 4, s[28:29]
	s_and_b64 s[100:101], exec, s[22:23]
	s_cbranch_scc0 .Lalign_446
	s_barrier
.Lalign_446:
	s_waitcnt vmcnt(0)
	v_cvt_f32_i32_e32 v139, v139
	v_cvt_f32_i32_e32 v167, v167
	v_cvt_f32_i32_e32 v166, v166
	v_cvt_f32_i32_e32 v173, v173
	v_cvt_f32_i32_e32 v172, v172
	v_cvt_f32_i32_e32 v189, v189
	v_cvt_f32_i32_e32 v188, v188
	v_cvt_f32_i32_e32 v177, v193
	v_cvt_f32_i32_e32 v176, v192
	v_cvt_f32_i32_e32 v179, v195
	v_cvt_f32_i32_e32 v178, v194
	v_cvt_f32_i32_e32 v181, v199
	v_cvt_f32_i32_e32 v180, v198
	v_pk_mul_f32 v[204:205], v[166:167], s[16:17] op_sel_hi:[1,0]
	v_pk_mul_f32 v[198:199], v[172:173], s[16:17] op_sel_hi:[1,0]
	v_pk_mul_f32 v[172:173], v[188:189], s[16:17] op_sel_hi:[1,0]
	v_pk_mul_f32 v[166:167], v[178:179], s[16:17] op_sel_hi:[1,0]
	v_pk_mul_f32 v[188:189], v[176:177], s[16:17] op_sel_hi:[1,0]
	v_cvt_f32_i32_e32 v177, v223
	v_cvt_f32_i32_e32 v176, v225
	v_cvt_f32_u32_e32 v179, v222
	v_cvt_f32_u32_e32 v178, v224
	v_cvt_f32_i32_e32 v133, v133
	v_cvt_f32_i32_e32 v132, v132
	v_cvt_f32_i32_e32 v135, v135
	v_pk_fma_f32 v[176:177], v[176:177], s[30:31], v[178:179] op_sel_hi:[1,0,1]
	v_cvt_f32_i32_e32 v134, v134
	v_pk_mul_f32 v[176:177], v[176:177], s[90:91] op_sel_hi:[1,0]
	v_cvt_f32_i32_e32 v138, v138
	v_pk_mul_f32 v[176:177], v[176:177], s[92:93] op_sel_hi:[1,0]
	v_cvt_f32_i32_e32 v137, v137
	v_cvt_f32_i32_e32 v136, v136
	v_cvt_f32_i32_e32 v169, v169
	v_cvt_f32_i32_e32 v168, v168
	v_cvt_f32_i32_e32 v171, v171
	v_cvt_f32_i32_e32 v170, v170
	v_cvt_f32_i32_e32 v185, v185
	v_cvt_f32_i32_e32 v184, v184
	v_cvt_f32_i32_e32 v187, v187
	v_cvt_f32_i32_e32 v186, v186
	v_cvt_f32_i32_e32 v249, v191
	v_cvt_f32_i32_e32 v248, v190
	v_cvt_f32_i32_e32 v237, v197
	v_cvt_f32_i32_e32 v236, v196
	v_fma_f32 v178, -v177, v177, v176
	v_max_f32_e32 v178, 0, v178
	v_add_f32_e32 v178, 0x3727c5ac, v178
	v_pk_mul_f32 v[206:207], v[132:133], s[16:17] op_sel_hi:[1,0]
	v_lshl_add_u64 v[132:133], v[164:165], 4, s[28:29]
	v_rsq_f32_e32 v178, v178
	v_pk_mul_f32 v[200:201], v[134:135], s[16:17] op_sel_hi:[1,0]
	v_pk_mul_f32 v[196:197], v[136:137], s[16:17] op_sel_hi:[1,0]
	v_pk_mul_f32 v[202:203], v[138:139], s[16:17] op_sel_hi:[1,0]
	v_pk_mul_f32 v[192:193], v[168:169], s[16:17] op_sel_hi:[1,0]
	v_pk_mul_f32 v[194:195], v[170:171], s[16:17] op_sel_hi:[1,0]
	v_pk_mul_f32 v[170:171], v[186:187], s[16:17] op_sel_hi:[1,0]
	v_pk_mul_f32 v[190:191], v[184:185], s[16:17] op_sel_hi:[1,0]
	v_pk_mul_f32 v[186:187], v[248:249], s[16:17] op_sel_hi:[1,0]
	v_pk_mul_f32 v[168:169], v[236:237], s[16:17] op_sel_hi:[1,0]
	v_pk_mul_f32 v[184:185], v[180:181], s[16:17] op_sel_hi:[1,0]
	global_load_dwordx4 v[136:139], v[246:247], off
	s_nop 0
	global_load_dwordx4 v[132:135], v[132:133], off
	s_lshl_b32 s16, s77, 1
	v_mov_b32_e32 v179, 0x6000
	v_mad_i64_i32 v[174:175], s[28:29], s16, v179, v[174:175]
	v_lshlrev_b64 v[174:175], 8, v[174:175]
	v_pk_fma_f32 v[128:129], v[206:207], v[176:177], v[128:129] op_sel:[0,1,0] neg_lo:[1,0,0] neg_hi:[1,0,0]
	v_pk_fma_f32 v[130:131], v[200:201], v[176:177], v[130:131] op_sel:[0,1,0] neg_lo:[1,0,0] neg_hi:[1,0,0]
	v_pk_fma_f32 v[124:125], v[204:205], v[176:177], v[124:125] op_sel:[0,1,0] neg_lo:[1,0,0] neg_hi:[1,0,0]
	v_pk_fma_f32 v[126:127], v[192:193], v[176:177], v[126:127] op_sel:[0,1,0] neg_lo:[1,0,0] neg_hi:[1,0,0]
	v_pk_fma_f32 v[120:121], v[190:191], v[176:177], v[120:121] op_sel:[0,1,0] neg_lo:[1,0,0] neg_hi:[1,0,0]
	v_pk_fma_f32 v[122:123], v[170:171], v[176:177], v[122:123] op_sel:[0,1,0] neg_lo:[1,0,0] neg_hi:[1,0,0]
	v_lshl_add_u64 v[174:175], v[158:159], 0, v[174:175]
	v_pk_fma_f32 v[130:131], v[130:131], v[178:179], v[202:203] op_sel_hi:[1,0,1]
	v_pk_fma_f32 v[128:129], v[128:129], v[178:179], v[196:197] op_sel_hi:[1,0,1]
	v_pk_fma_f32 v[180:181], v[126:127], v[178:179], v[198:199] op_sel_hi:[1,0,1]
	v_pk_fma_f32 v[126:127], v[124:125], v[178:179], v[194:195] op_sel_hi:[1,0,1]
	v_cvt_pk_bf16_f32 v124, v128, v129
	v_cvt_pk_bf16_f32 v125, v130, v131
	v_pk_fma_f32 v[122:123], v[122:123], v[178:179], v[186:187] op_sel_hi:[1,0,1]
	v_pk_fma_f32 v[120:121], v[120:121], v[178:179], v[172:173] op_sel_hi:[1,0,1]
	v_pk_fma_f32 v[116:117], v[188:189], v[176:177], v[116:117] op_sel:[0,1,0] neg_lo:[1,0,0] neg_hi:[1,0,0]
	v_pk_fma_f32 v[118:119], v[166:167], v[176:177], v[118:119] op_sel:[0,1,0] neg_lo:[1,0,0] neg_hi:[1,0,0]
	v_cvt_pk_bf16_f32 v126, v126, v127
	v_cvt_pk_bf16_f32 v127, v180, v181
	global_store_dwordx4 v[174:175], v[124:127], off
	s_mov_b32 s17, 0x600000
	s_nop 0
	v_pk_fma_f32 v[124:125], v[118:119], v[178:179], v[184:185] op_sel_hi:[1,0,1]
	v_pk_fma_f32 v[118:119], v[116:117], v[178:179], v[168:169] op_sel_hi:[1,0,1]
	v_cvt_pk_bf16_f32 v116, v120, v121
	v_cvt_pk_bf16_f32 v117, v122, v123
	v_cvt_f32_i32_e32 v121, v227
	v_cvt_f32_i32_e32 v120, v229
	v_cvt_f32_u32_e32 v123, v226
	v_cvt_f32_u32_e32 v122, v228
	v_cvt_pk_bf16_f32 v118, v118, v119
	v_cvt_pk_bf16_f32 v119, v124, v125
	v_add_co_u32_e32 v124, vcc, s17, v174
	s_nop 1
	v_addc_co_u32_e32 v125, vcc, 0, v175, vcc
	global_store_dwordx4 v[124:125], v[116:119], off
	s_nop 1
	v_pk_fma_f32 v[116:117], v[120:121], s[30:31], v[122:123] op_sel_hi:[1,0,1]
	v_mad_i64_i32 v[120:121], s[28:29], s16, v179, v[182:183]
	v_pk_mul_f32 v[116:117], v[116:117], s[90:91] op_sel_hi:[1,0]
	v_lshlrev_b64 v[120:121], 8, v[120:121]
	v_pk_mul_f32 v[116:117], v[116:117], s[92:93] op_sel_hi:[1,0]
	v_lshl_add_u64 v[120:121], v[158:159], 0, v[120:121]
	v_fma_f32 v118, -v117, v117, v116
	v_max_f32_e32 v118, 0, v118
	v_add_f32_e32 v118, 0x3727c5ac, v118
	v_rsq_f32_e32 v118, v118
	v_pk_fma_f32 v[112:113], v[206:207], v[116:117], v[112:113] op_sel:[0,1,0] neg_lo:[1,0,0] neg_hi:[1,0,0]
	v_pk_fma_f32 v[114:115], v[200:201], v[116:117], v[114:115] op_sel:[0,1,0] neg_lo:[1,0,0] neg_hi:[1,0,0]
	v_pk_fma_f32 v[108:109], v[204:205], v[116:117], v[108:109] op_sel:[0,1,0] neg_lo:[1,0,0] neg_hi:[1,0,0]
	v_pk_fma_f32 v[110:111], v[192:193], v[116:117], v[110:111] op_sel:[0,1,0] neg_lo:[1,0,0] neg_hi:[1,0,0]
	v_pk_fma_f32 v[104:105], v[190:191], v[116:117], v[104:105] op_sel:[0,1,0] neg_lo:[1,0,0] neg_hi:[1,0,0]
	v_pk_fma_f32 v[106:107], v[170:171], v[116:117], v[106:107] op_sel:[0,1,0] neg_lo:[1,0,0] neg_hi:[1,0,0]
	v_pk_fma_f32 v[114:115], v[114:115], v[118:119], v[202:203] op_sel_hi:[1,0,1]
	v_pk_fma_f32 v[112:113], v[112:113], v[118:119], v[196:197] op_sel_hi:[1,0,1]
	v_pk_fma_f32 v[122:123], v[110:111], v[118:119], v[198:199] op_sel_hi:[1,0,1]
	v_pk_fma_f32 v[110:111], v[108:109], v[118:119], v[194:195] op_sel_hi:[1,0,1]
	v_cvt_pk_bf16_f32 v108, v112, v113
	v_cvt_pk_bf16_f32 v109, v114, v115
	v_pk_fma_f32 v[106:107], v[106:107], v[118:119], v[186:187] op_sel_hi:[1,0,1]
	v_pk_fma_f32 v[104:105], v[104:105], v[118:119], v[172:173] op_sel_hi:[1,0,1]
	v_pk_fma_f32 v[100:101], v[188:189], v[116:117], v[100:101] op_sel:[0,1,0] neg_lo:[1,0,0] neg_hi:[1,0,0]
	v_pk_fma_f32 v[102:103], v[166:167], v[116:117], v[102:103] op_sel:[0,1,0] neg_lo:[1,0,0] neg_hi:[1,0,0]
	v_cvt_pk_bf16_f32 v110, v110, v111
	v_cvt_pk_bf16_f32 v111, v122, v123
	global_store_dwordx4 v[120:121], v[108:111], off
	s_nop 1
	v_pk_fma_f32 v[108:109], v[102:103], v[118:119], v[184:185] op_sel_hi:[1,0,1]
	v_pk_fma_f32 v[102:103], v[100:101], v[118:119], v[168:169] op_sel_hi:[1,0,1]
	v_cvt_pk_bf16_f32 v100, v104, v105
	v_cvt_pk_bf16_f32 v101, v106, v107
	v_cvt_f32_i32_e32 v105, v243
	v_cvt_f32_i32_e32 v104, v245
	v_cvt_f32_u32_e32 v107, v242
	v_cvt_f32_u32_e32 v106, v244
	v_cvt_pk_bf16_f32 v102, v102, v103
	v_cvt_pk_bf16_f32 v103, v108, v109
	v_add_co_u32_e32 v108, vcc, s17, v120
	s_nop 1
	v_addc_co_u32_e32 v109, vcc, 0, v121, vcc
	global_store_dwordx4 v[108:109], v[100:103], off
	s_nop 1
	v_pk_fma_f32 v[100:101], v[104:105], s[30:31], v[106:107] op_sel_hi:[1,0,1]
	v_mad_i64_i32 v[104:105], s[28:29], s16, v179, v[216:217]
	v_pk_mul_f32 v[100:101], v[100:101], s[90:91] op_sel_hi:[1,0]
	v_lshlrev_b64 v[104:105], 8, v[104:105]
	v_pk_mul_f32 v[100:101], v[100:101], s[92:93] op_sel_hi:[1,0]
	v_lshl_add_u64 v[104:105], v[158:159], 0, v[104:105]
	v_fma_f32 v102, -v101, v101, v100
	v_max_f32_e32 v102, 0, v102
	v_add_f32_e32 v102, 0x3727c5ac, v102
	v_rsq_f32_e32 v102, v102
	v_pk_fma_f32 v[96:97], v[206:207], v[100:101], v[96:97] op_sel:[0,1,0] neg_lo:[1,0,0] neg_hi:[1,0,0]
	v_pk_fma_f32 v[98:99], v[200:201], v[100:101], v[98:99] op_sel:[0,1,0] neg_lo:[1,0,0] neg_hi:[1,0,0]
	v_pk_fma_f32 v[92:93], v[204:205], v[100:101], v[92:93] op_sel:[0,1,0] neg_lo:[1,0,0] neg_hi:[1,0,0]
	v_pk_fma_f32 v[94:95], v[192:193], v[100:101], v[94:95] op_sel:[0,1,0] neg_lo:[1,0,0] neg_hi:[1,0,0]
	v_pk_fma_f32 v[88:89], v[190:191], v[100:101], v[88:89] op_sel:[0,1,0] neg_lo:[1,0,0] neg_hi:[1,0,0]
	v_pk_fma_f32 v[90:91], v[170:171], v[100:101], v[90:91] op_sel:[0,1,0] neg_lo:[1,0,0] neg_hi:[1,0,0]
	v_pk_fma_f32 v[98:99], v[98:99], v[102:103], v[202:203] op_sel_hi:[1,0,1]
	v_pk_fma_f32 v[96:97], v[96:97], v[102:103], v[196:197] op_sel_hi:[1,0,1]
	v_pk_fma_f32 v[106:107], v[94:95], v[102:103], v[198:199] op_sel_hi:[1,0,1]
	v_pk_fma_f32 v[94:95], v[92:93], v[102:103], v[194:195] op_sel_hi:[1,0,1]
	v_cvt_pk_bf16_f32 v92, v96, v97
	v_cvt_pk_bf16_f32 v93, v98, v99
	v_pk_fma_f32 v[90:91], v[90:91], v[102:103], v[186:187] op_sel_hi:[1,0,1]
	v_pk_fma_f32 v[88:89], v[88:89], v[102:103], v[172:173] op_sel_hi:[1,0,1]
	v_pk_fma_f32 v[84:85], v[188:189], v[100:101], v[84:85] op_sel:[0,1,0] neg_lo:[1,0,0] neg_hi:[1,0,0]
	v_pk_fma_f32 v[86:87], v[166:167], v[100:101], v[86:87] op_sel:[0,1,0] neg_lo:[1,0,0] neg_hi:[1,0,0]
	v_cvt_pk_bf16_f32 v94, v94, v95
	v_cvt_pk_bf16_f32 v95, v106, v107
	global_store_dwordx4 v[104:105], v[92:95], off
	s_nop 1
	v_pk_fma_f32 v[92:93], v[86:87], v[102:103], v[184:185] op_sel_hi:[1,0,1]
	v_pk_fma_f32 v[86:87], v[84:85], v[102:103], v[168:169] op_sel_hi:[1,0,1]
	v_cvt_pk_bf16_f32 v84, v88, v89
	v_cvt_pk_bf16_f32 v85, v90, v91
	v_cvt_f32_i32_e32 v89, v149
	v_cvt_f32_i32_e32 v88, v151
	v_cvt_f32_u32_e32 v91, v148
	v_cvt_f32_u32_e32 v90, v150
	v_cvt_pk_bf16_f32 v86, v86, v87
	v_cvt_pk_bf16_f32 v87, v92, v93
	v_add_co_u32_e32 v92, vcc, s17, v104
	s_nop 1
	v_addc_co_u32_e32 v93, vcc, 0, v105, vcc
	global_store_dwordx4 v[92:93], v[84:87], off
	s_nop 1
	v_pk_fma_f32 v[84:85], v[88:89], s[30:31], v[90:91] op_sel_hi:[1,0,1]
	v_mad_i64_i32 v[88:89], s[28:29], s16, v179, v[214:215]
	v_pk_mul_f32 v[84:85], v[84:85], s[90:91] op_sel_hi:[1,0]
	v_lshlrev_b64 v[88:89], 8, v[88:89]
	v_pk_mul_f32 v[84:85], v[84:85], s[92:93] op_sel_hi:[1,0]
	v_lshl_add_u64 v[88:89], v[158:159], 0, v[88:89]
	v_fma_f32 v86, -v85, v85, v84
	v_max_f32_e32 v86, 0, v86
	v_add_f32_e32 v86, 0x3727c5ac, v86
	v_rsq_f32_e32 v86, v86
	v_pk_fma_f32 v[80:81], v[206:207], v[84:85], v[80:81] op_sel:[0,1,0] neg_lo:[1,0,0] neg_hi:[1,0,0]
	v_pk_fma_f32 v[82:83], v[200:201], v[84:85], v[82:83] op_sel:[0,1,0] neg_lo:[1,0,0] neg_hi:[1,0,0]
	v_pk_fma_f32 v[76:77], v[204:205], v[84:85], v[76:77] op_sel:[0,1,0] neg_lo:[1,0,0] neg_hi:[1,0,0]
	v_pk_fma_f32 v[78:79], v[192:193], v[84:85], v[78:79] op_sel:[0,1,0] neg_lo:[1,0,0] neg_hi:[1,0,0]
	v_pk_fma_f32 v[72:73], v[190:191], v[84:85], v[72:73] op_sel:[0,1,0] neg_lo:[1,0,0] neg_hi:[1,0,0]
	v_pk_fma_f32 v[74:75], v[170:171], v[84:85], v[74:75] op_sel:[0,1,0] neg_lo:[1,0,0] neg_hi:[1,0,0]
	v_pk_fma_f32 v[82:83], v[82:83], v[86:87], v[202:203] op_sel_hi:[1,0,1]
	v_pk_fma_f32 v[80:81], v[80:81], v[86:87], v[196:197] op_sel_hi:[1,0,1]
	v_pk_fma_f32 v[90:91], v[78:79], v[86:87], v[198:199] op_sel_hi:[1,0,1]
	v_pk_fma_f32 v[78:79], v[76:77], v[86:87], v[194:195] op_sel_hi:[1,0,1]
	v_cvt_pk_bf16_f32 v76, v80, v81
	v_cvt_pk_bf16_f32 v77, v82, v83
	v_pk_fma_f32 v[74:75], v[74:75], v[86:87], v[186:187] op_sel_hi:[1,0,1]
	v_pk_fma_f32 v[72:73], v[72:73], v[86:87], v[172:173] op_sel_hi:[1,0,1]
	v_pk_fma_f32 v[68:69], v[188:189], v[84:85], v[68:69] op_sel:[0,1,0] neg_lo:[1,0,0] neg_hi:[1,0,0]
	v_pk_fma_f32 v[70:71], v[166:167], v[84:85], v[70:71] op_sel:[0,1,0] neg_lo:[1,0,0] neg_hi:[1,0,0]
	v_cvt_pk_bf16_f32 v78, v78, v79
	v_cvt_pk_bf16_f32 v79, v90, v91
	global_store_dwordx4 v[88:89], v[76:79], off
	s_nop 1
	v_pk_fma_f32 v[76:77], v[70:71], v[86:87], v[184:185] op_sel_hi:[1,0,1]
	v_pk_fma_f32 v[70:71], v[68:69], v[86:87], v[168:169] op_sel_hi:[1,0,1]
	v_cvt_pk_bf16_f32 v68, v72, v73
	v_cvt_pk_bf16_f32 v69, v74, v75
	v_cvt_f32_i32_e32 v73, v145
	v_cvt_f32_i32_e32 v72, v147
	v_cvt_f32_u32_e32 v75, v144
	v_cvt_f32_u32_e32 v74, v146
	v_cvt_pk_bf16_f32 v70, v70, v71
	v_cvt_pk_bf16_f32 v71, v76, v77
	v_add_co_u32_e32 v76, vcc, s17, v88
	s_nop 1
	v_addc_co_u32_e32 v77, vcc, 0, v89, vcc
	global_store_dwordx4 v[76:77], v[68:71], off
	s_nop 1
	v_pk_fma_f32 v[68:69], v[72:73], s[30:31], v[74:75] op_sel_hi:[1,0,1]
	v_mad_i64_i32 v[72:73], s[28:29], s16, v179, v[212:213]
	v_pk_mul_f32 v[68:69], v[68:69], s[90:91] op_sel_hi:[1,0]
	v_lshlrev_b64 v[72:73], 8, v[72:73]
	v_pk_mul_f32 v[68:69], v[68:69], s[92:93] op_sel_hi:[1,0]
	v_lshl_add_u64 v[72:73], v[158:159], 0, v[72:73]
	v_fma_f32 v70, -v69, v69, v68
	v_max_f32_e32 v70, 0, v70
	v_add_f32_e32 v70, 0x3727c5ac, v70
	v_rsq_f32_e32 v70, v70
	v_pk_fma_f32 v[64:65], v[206:207], v[68:69], v[64:65] op_sel:[0,1,0] neg_lo:[1,0,0] neg_hi:[1,0,0]
	v_pk_fma_f32 v[66:67], v[200:201], v[68:69], v[66:67] op_sel:[0,1,0] neg_lo:[1,0,0] neg_hi:[1,0,0]
	v_pk_fma_f32 v[60:61], v[204:205], v[68:69], v[60:61] op_sel:[0,1,0] neg_lo:[1,0,0] neg_hi:[1,0,0]
	v_pk_fma_f32 v[62:63], v[192:193], v[68:69], v[62:63] op_sel:[0,1,0] neg_lo:[1,0,0] neg_hi:[1,0,0]
	v_pk_fma_f32 v[56:57], v[190:191], v[68:69], v[56:57] op_sel:[0,1,0] neg_lo:[1,0,0] neg_hi:[1,0,0]
	v_pk_fma_f32 v[58:59], v[170:171], v[68:69], v[58:59] op_sel:[0,1,0] neg_lo:[1,0,0] neg_hi:[1,0,0]
	v_pk_fma_f32 v[66:67], v[66:67], v[70:71], v[202:203] op_sel_hi:[1,0,1]
	v_pk_fma_f32 v[64:65], v[64:65], v[70:71], v[196:197] op_sel_hi:[1,0,1]
	v_pk_fma_f32 v[74:75], v[62:63], v[70:71], v[198:199] op_sel_hi:[1,0,1]
	v_pk_fma_f32 v[62:63], v[60:61], v[70:71], v[194:195] op_sel_hi:[1,0,1]
	v_cvt_pk_bf16_f32 v60, v64, v65
	v_cvt_pk_bf16_f32 v61, v66, v67
	v_pk_fma_f32 v[58:59], v[58:59], v[70:71], v[186:187] op_sel_hi:[1,0,1]
	v_pk_fma_f32 v[56:57], v[56:57], v[70:71], v[172:173] op_sel_hi:[1,0,1]
	v_pk_fma_f32 v[52:53], v[188:189], v[68:69], v[52:53] op_sel:[0,1,0] neg_lo:[1,0,0] neg_hi:[1,0,0]
	v_pk_fma_f32 v[54:55], v[166:167], v[68:69], v[54:55] op_sel:[0,1,0] neg_lo:[1,0,0] neg_hi:[1,0,0]
	v_cvt_pk_bf16_f32 v62, v62, v63
	v_cvt_pk_bf16_f32 v63, v74, v75
	global_store_dwordx4 v[72:73], v[60:63], off
	s_nop 1
	v_pk_fma_f32 v[60:61], v[54:55], v[70:71], v[184:185] op_sel_hi:[1,0,1]
	v_pk_fma_f32 v[54:55], v[52:53], v[70:71], v[168:169] op_sel_hi:[1,0,1]
	v_cvt_pk_bf16_f32 v52, v56, v57
	v_cvt_pk_bf16_f32 v53, v58, v59
	v_cvt_f32_i32_e32 v57, v141
	v_cvt_f32_i32_e32 v56, v143
	v_cvt_f32_u32_e32 v59, v140
	v_cvt_f32_u32_e32 v58, v142
	v_cvt_pk_bf16_f32 v54, v54, v55
	v_cvt_pk_bf16_f32 v55, v60, v61
	v_add_co_u32_e32 v60, vcc, s17, v72
	s_nop 1
	v_addc_co_u32_e32 v61, vcc, 0, v73, vcc
	global_store_dwordx4 v[60:61], v[52:55], off
	s_nop 1
	v_pk_fma_f32 v[52:53], v[56:57], s[30:31], v[58:59] op_sel_hi:[1,0,1]
	v_mad_i64_i32 v[56:57], s[28:29], s16, v179, v[210:211]
	v_pk_mul_f32 v[52:53], v[52:53], s[90:91] op_sel_hi:[1,0]
	v_lshlrev_b64 v[56:57], 8, v[56:57]
	v_pk_mul_f32 v[52:53], v[52:53], s[92:93] op_sel_hi:[1,0]
	v_lshl_add_u64 v[56:57], v[158:159], 0, v[56:57]
	v_fma_f32 v54, -v53, v53, v52
	v_max_f32_e32 v54, 0, v54
	v_add_f32_e32 v54, 0x3727c5ac, v54
	v_rsq_f32_e32 v54, v54
	v_pk_fma_f32 v[48:49], v[206:207], v[52:53], v[48:49] op_sel:[0,1,0] neg_lo:[1,0,0] neg_hi:[1,0,0]
	v_pk_fma_f32 v[50:51], v[200:201], v[52:53], v[50:51] op_sel:[0,1,0] neg_lo:[1,0,0] neg_hi:[1,0,0]
	v_pk_fma_f32 v[44:45], v[204:205], v[52:53], v[44:45] op_sel:[0,1,0] neg_lo:[1,0,0] neg_hi:[1,0,0]
	v_pk_fma_f32 v[46:47], v[192:193], v[52:53], v[46:47] op_sel:[0,1,0] neg_lo:[1,0,0] neg_hi:[1,0,0]
	v_pk_fma_f32 v[40:41], v[190:191], v[52:53], v[40:41] op_sel:[0,1,0] neg_lo:[1,0,0] neg_hi:[1,0,0]
	v_pk_fma_f32 v[42:43], v[170:171], v[52:53], v[42:43] op_sel:[0,1,0] neg_lo:[1,0,0] neg_hi:[1,0,0]
	v_pk_fma_f32 v[50:51], v[50:51], v[54:55], v[202:203] op_sel_hi:[1,0,1]
	v_pk_fma_f32 v[48:49], v[48:49], v[54:55], v[196:197] op_sel_hi:[1,0,1]
	v_pk_fma_f32 v[58:59], v[46:47], v[54:55], v[198:199] op_sel_hi:[1,0,1]
	v_pk_fma_f32 v[46:47], v[44:45], v[54:55], v[194:195] op_sel_hi:[1,0,1]
	v_cvt_pk_bf16_f32 v44, v48, v49
	v_cvt_pk_bf16_f32 v45, v50, v51
	v_pk_fma_f32 v[42:43], v[42:43], v[54:55], v[186:187] op_sel_hi:[1,0,1]
	v_pk_fma_f32 v[40:41], v[40:41], v[54:55], v[172:173] op_sel_hi:[1,0,1]
	v_pk_fma_f32 v[36:37], v[188:189], v[52:53], v[36:37] op_sel:[0,1,0] neg_lo:[1,0,0] neg_hi:[1,0,0]
	v_pk_fma_f32 v[38:39], v[166:167], v[52:53], v[38:39] op_sel:[0,1,0] neg_lo:[1,0,0] neg_hi:[1,0,0]
	v_cvt_pk_bf16_f32 v46, v46, v47
	v_cvt_pk_bf16_f32 v47, v58, v59
	global_store_dwordx4 v[56:57], v[44:47], off
	s_nop 1
	v_pk_fma_f32 v[44:45], v[38:39], v[54:55], v[184:185] op_sel_hi:[1,0,1]
	v_pk_fma_f32 v[38:39], v[36:37], v[54:55], v[168:169] op_sel_hi:[1,0,1]
	v_cvt_pk_bf16_f32 v36, v40, v41
	v_cvt_pk_bf16_f32 v37, v42, v43
	s_waitcnt vmcnt(12)
	v_cvt_f32_i32_e32 v41, v137
	v_cvt_f32_i32_e32 v40, v139
	v_cvt_f32_u32_e32 v43, v136
	v_cvt_f32_u32_e32 v42, v138
	v_cvt_pk_bf16_f32 v38, v38, v39
	v_cvt_pk_bf16_f32 v39, v44, v45
	v_add_co_u32_e32 v44, vcc, s17, v56
	s_nop 1
	v_addc_co_u32_e32 v45, vcc, 0, v57, vcc
	global_store_dwordx4 v[44:45], v[36:39], off
	s_nop 1
	v_pk_fma_f32 v[36:37], v[40:41], s[30:31], v[42:43] op_sel_hi:[1,0,1]
	v_mad_i64_i32 v[40:41], s[28:29], s16, v179, v[208:209]
	v_pk_mul_f32 v[36:37], v[36:37], s[90:91] op_sel_hi:[1,0]
	v_lshlrev_b64 v[40:41], 8, v[40:41]
	v_pk_mul_f32 v[36:37], v[36:37], s[92:93] op_sel_hi:[1,0]
	v_lshl_add_u64 v[40:41], v[158:159], 0, v[40:41]
	v_fma_f32 v38, -v37, v37, v36
	v_max_f32_e32 v38, 0, v38
	v_add_f32_e32 v38, 0x3727c5ac, v38
	v_rsq_f32_e32 v38, v38
	v_pk_fma_f32 v[32:33], v[206:207], v[36:37], v[32:33] op_sel:[0,1,0] neg_lo:[1,0,0] neg_hi:[1,0,0]
	v_pk_fma_f32 v[34:35], v[200:201], v[36:37], v[34:35] op_sel:[0,1,0] neg_lo:[1,0,0] neg_hi:[1,0,0]
	v_pk_fma_f32 v[28:29], v[204:205], v[36:37], v[28:29] op_sel:[0,1,0] neg_lo:[1,0,0] neg_hi:[1,0,0]
	v_pk_fma_f32 v[30:31], v[192:193], v[36:37], v[30:31] op_sel:[0,1,0] neg_lo:[1,0,0] neg_hi:[1,0,0]
	v_pk_fma_f32 v[24:25], v[190:191], v[36:37], v[24:25] op_sel:[0,1,0] neg_lo:[1,0,0] neg_hi:[1,0,0]
	v_pk_fma_f32 v[26:27], v[170:171], v[36:37], v[26:27] op_sel:[0,1,0] neg_lo:[1,0,0] neg_hi:[1,0,0]
	v_pk_fma_f32 v[34:35], v[34:35], v[38:39], v[202:203] op_sel_hi:[1,0,1]
	v_pk_fma_f32 v[32:33], v[32:33], v[38:39], v[196:197] op_sel_hi:[1,0,1]
	v_pk_fma_f32 v[42:43], v[30:31], v[38:39], v[198:199] op_sel_hi:[1,0,1]
	v_pk_fma_f32 v[30:31], v[28:29], v[38:39], v[194:195] op_sel_hi:[1,0,1]
	v_cvt_pk_bf16_f32 v28, v32, v33
	v_cvt_pk_bf16_f32 v29, v34, v35
	v_pk_fma_f32 v[26:27], v[26:27], v[38:39], v[186:187] op_sel_hi:[1,0,1]
	v_pk_fma_f32 v[24:25], v[24:25], v[38:39], v[172:173] op_sel_hi:[1,0,1]
	v_pk_fma_f32 v[20:21], v[188:189], v[36:37], v[20:21] op_sel:[0,1,0] neg_lo:[1,0,0] neg_hi:[1,0,0]
	v_pk_fma_f32 v[22:23], v[166:167], v[36:37], v[22:23] op_sel:[0,1,0] neg_lo:[1,0,0] neg_hi:[1,0,0]
	v_cvt_pk_bf16_f32 v30, v30, v31
	v_cvt_pk_bf16_f32 v31, v42, v43
	global_store_dwordx4 v[40:41], v[28:31], off
	s_mov_b64 s[28:29], -1
	s_nop 0
	v_pk_fma_f32 v[28:29], v[22:23], v[38:39], v[184:185] op_sel_hi:[1,0,1]
	v_pk_fma_f32 v[22:23], v[20:21], v[38:39], v[168:169] op_sel_hi:[1,0,1]
	v_cvt_pk_bf16_f32 v20, v24, v25
	v_cvt_pk_bf16_f32 v21, v26, v27
	s_waitcnt vmcnt(13)
	v_cvt_f32_i32_e32 v25, v133
	v_cvt_f32_i32_e32 v24, v135
	v_cvt_f32_u32_e32 v27, v132
	v_cvt_f32_u32_e32 v26, v134
	v_cvt_pk_bf16_f32 v22, v22, v23
	v_cvt_pk_bf16_f32 v23, v28, v29
	v_add_co_u32_e32 v28, vcc, s17, v40
	s_nop 1
	v_addc_co_u32_e32 v29, vcc, 0, v41, vcc
	global_store_dwordx4 v[28:29], v[20:23], off
	s_nop 1
	v_pk_fma_f32 v[20:21], v[24:25], s[30:31], v[26:27] op_sel_hi:[1,0,1]
	v_mad_i64_i32 v[24:25], s[16:17], s16, v179, v[164:165]
	v_pk_mul_f32 v[20:21], v[20:21], s[90:91] op_sel_hi:[1,0]
	v_lshlrev_b64 v[24:25], 8, v[24:25]
	v_pk_mul_f32 v[20:21], v[20:21], s[92:93] op_sel_hi:[1,0]
	v_lshl_add_u64 v[24:25], v[158:159], 0, v[24:25]
	v_fma_f32 v22, -v21, v21, v20
	v_max_f32_e32 v22, 0, v22
	v_add_f32_e32 v22, 0x3727c5ac, v22
	v_rsq_f32_e32 v22, v22
	v_pk_fma_f32 v[16:17], v[206:207], v[20:21], v[16:17] op_sel:[0,1,0] neg_lo:[1,0,0] neg_hi:[1,0,0]
	v_pk_fma_f32 v[18:19], v[200:201], v[20:21], v[18:19] op_sel:[0,1,0] neg_lo:[1,0,0] neg_hi:[1,0,0]
	v_pk_fma_f32 v[12:13], v[204:205], v[20:21], v[12:13] op_sel:[0,1,0] neg_lo:[1,0,0] neg_hi:[1,0,0]
	v_pk_fma_f32 v[14:15], v[192:193], v[20:21], v[14:15] op_sel:[0,1,0] neg_lo:[1,0,0] neg_hi:[1,0,0]
	v_pk_fma_f32 v[8:9], v[190:191], v[20:21], v[8:9] op_sel:[0,1,0] neg_lo:[1,0,0] neg_hi:[1,0,0]
	v_pk_fma_f32 v[18:19], v[18:19], v[22:23], v[202:203] op_sel_hi:[1,0,1]
	v_pk_fma_f32 v[16:17], v[16:17], v[22:23], v[196:197] op_sel_hi:[1,0,1]
	v_pk_fma_f32 v[26:27], v[14:15], v[22:23], v[198:199] op_sel_hi:[1,0,1]
	v_pk_fma_f32 v[14:15], v[12:13], v[22:23], v[194:195] op_sel_hi:[1,0,1]
	v_cvt_pk_bf16_f32 v12, v16, v17
	v_cvt_pk_bf16_f32 v13, v18, v19
	v_pk_fma_f32 v[8:9], v[8:9], v[22:23], v[172:173] op_sel_hi:[1,0,1]
	v_pk_fma_f32 v[4:5], v[188:189], v[20:21], v[4:5] op_sel:[0,1,0] neg_lo:[1,0,0] neg_hi:[1,0,0]
	v_pk_fma_f32 v[6:7], v[166:167], v[20:21], v[6:7] op_sel:[0,1,0] neg_lo:[1,0,0] neg_hi:[1,0,0]
	v_cvt_pk_bf16_f32 v14, v14, v15
	v_cvt_pk_bf16_f32 v15, v26, v27
	global_store_dwordx4 v[24:25], v[12:15], off
	v_pk_fma_f32 v[10:11], v[170:171], v[20:21], v[10:11] op_sel:[0,1,0] neg_lo:[1,0,0] neg_hi:[1,0,0]
	s_nop 0
	v_pk_fma_f32 v[12:13], v[6:7], v[22:23], v[184:185] op_sel_hi:[1,0,1]
	v_pk_fma_f32 v[6:7], v[4:5], v[22:23], v[168:169] op_sel_hi:[1,0,1]
	v_cvt_pk_bf16_f32 v4, v8, v9
	v_add_co_u32_e32 v8, vcc, 0x600000, v24
	v_pk_fma_f32 v[10:11], v[10:11], v[22:23], v[186:187] op_sel_hi:[1,0,1]
	s_nop 0
	v_addc_co_u32_e32 v9, vcc, 0, v25, vcc
	s_andn2_b64 vcc, exec, s[38:39]
	v_cvt_pk_bf16_f32 v5, v10, v11
	v_cvt_pk_bf16_f32 v6, v6, v7
	v_cvt_pk_bf16_f32 v7, v12, v13
	global_store_dwordx4 v[8:9], v[4:7], off
	s_cbranch_vccnz .LBB0_442
	s_andn2_b64 vcc, exec, s[10:11]
	s_cbranch_vccnz .LBB0_441
	s_barrier
	s_branch .LBB0_441

.LBB0_793:
	v_lshl_add_u32 v188, s91, 8, v242
	v_readlane_b32 s10, v252, 10
	v_ashrrev_i32_e32 v189, 31, v188
	v_readlane_b32 s11, v252, 11
	v_lshl_or_b32 v140, s89, 8, v245
	v_ashrrev_i32_e32 v141, 31, v140
	v_lshl_add_u64 v[132:133], v[188:189], 4, s[10:11]
	global_load_dwordx4 v[164:167], v[132:133], off
	v_lshlrev_b64 v[132:133], 12, v[188:189]
	v_lshl_add_u64 v[132:133], s[0:1], 0, v[132:133]
	v_lshlrev_b64 v[222:223], 1, v[140:141]
	v_lshl_add_u64 v[228:229], v[132:133], 0, v[222:223]
	v_or_b32_e32 v132, 16, v188
	v_ashrrev_i32_e32 v133, 31, v132
	v_lshl_add_u64 v[134:135], v[132:133], 4, s[10:11]
	v_lshlrev_b64 v[132:133], 12, v[132:133]
	v_readlane_b32 s16, v252, 12
	v_lshl_add_u64 v[132:133], s[0:1], 0, v[132:133]
	v_lshlrev_b64 v[140:141], 2, v[140:141]
	v_readlane_b32 s17, v252, 13
	v_lshl_add_u64 v[224:225], v[132:133], 0, v[222:223]
	global_load_dwordx4 v[160:163], v[228:229], off
	global_load_dwordx4 v[156:159], v[228:229], off offset:64
	v_lshl_add_u64 v[174:175], s[16:17], 0, v[140:141]
	global_load_dwordx4 v[144:147], v[134:135], off
	global_load_dwordx4 v[136:139], v[224:225], off
	s_nop 0
	global_load_dwordx4 v[132:135], v[224:225], off offset:64
	v_lshl_add_u64 v[176:177], s[12:13], 0, v[140:141]
	global_load_dwordx4 v[140:143], v[174:175], off offset:16
	global_load_dwordx4 v[148:151], v[174:175], off
	s_mov_b64 s[28:29], -1
	v_readlane_b32 s100, v252, 2
	v_readlane_b32 s101, v252, 3
	s_and_b64 s[100:101], exec, s[100:101]
	s_cbranch_scc0 .Lalign_790
	s_barrier
.Lalign_790:
	s_waitcnt vmcnt(0)
	v_pk_mul_f32 v[194:195], v[142:143], s[86:87] op_sel_hi:[1,0]
	v_pk_mul_f32 v[190:191], v[150:151], s[86:87] op_sel_hi:[1,0]
	v_pk_mul_f32 v[192:193], v[148:149], s[86:87] op_sel_hi:[1,0]
	global_load_dwordx4 v[148:151], v[176:177], off offset:16
	global_load_dwordx4 v[152:155], v[176:177], off
	v_pk_mul_f32 v[196:197], v[140:141], s[86:87] op_sel_hi:[1,0]
	s_waitcnt vmcnt(1)
	v_pk_mul_f32 v[198:199], v[150:151], s[86:87] op_sel_hi:[1,0]
	v_pk_mul_f32 v[200:201], v[148:149], s[86:87] op_sel_hi:[1,0]
	global_load_dwordx4 v[140:143], v[174:175], off offset:144
	global_load_dwordx4 v[148:151], v[174:175], off offset:128
	s_waitcnt vmcnt(2)
	v_pk_mul_f32 v[202:203], v[154:155], s[86:87] op_sel_hi:[1,0]
	v_pk_mul_f32 v[204:205], v[152:153], s[86:87] op_sel_hi:[1,0]
	v_cvt_f32_i32_e32 v175, v165
	v_cvt_f32_i32_e32 v174, v167
	v_cvt_f32_u32_e32 v165, v164
	v_cvt_f32_u32_e32 v164, v166
	v_lshlrev_b32_e32 v166, 16, v160
	v_and_b32_e32 v160, 0xffff0000, v160
	v_and_b32_e32 v167, 0xffff0000, v161
	v_pk_fma_f32 v[164:165], v[174:175], s[30:31], v[164:165] op_sel_hi:[1,0,1]
	v_lshlrev_b32_e32 v174, 16, v161
	v_pk_mul_f32 v[164:165], v[164:165], s[90:91] op_sel_hi:[1,0]
	s_waitcnt vmcnt(1)
	v_pk_mul_f32 v[212:213], v[140:141], s[86:87] op_sel_hi:[1,0]
	s_waitcnt vmcnt(0)
	v_pk_mul_f32 v[206:207], v[150:151], s[86:87] op_sel_hi:[1,0]
	v_pk_mul_f32 v[208:209], v[148:149], s[86:87] op_sel_hi:[1,0]
	global_load_dwordx4 v[148:151], v[176:177], off offset:144
	global_load_dwordx4 v[152:155], v[176:177], off offset:128
	v_pk_mul_f32 v[164:165], v[164:165], s[92:93] op_sel_hi:[1,0]
	v_or_b32_e32 v140, 32, v188
	v_fma_f32 v164, -v165, v165, v164
	v_max_f32_e32 v164, 0, v164
	v_add_f32_e32 v164, 0x3727c5ac, v164
	v_rsq_f32_e32 v164, v164
	v_ashrrev_i32_e32 v141, 31, v140
	v_pk_mul_f32 v[210:211], v[142:143], s[86:87] op_sel_hi:[1,0]
	v_lshl_add_u64 v[142:143], v[140:141], 4, s[10:11]
	v_sub_f32_e32 v161, v160, v165
	v_sub_f32_e32 v160, v166, v165
	v_pk_mul_f32 v[160:161], v[160:161], v[164:165] op_sel_hi:[1,0]
	v_lshlrev_b64 v[140:141], 12, v[140:141]
	v_pk_fma_f32 v[160:161], v[192:193], v[160:161], v[204:205]
	v_lshl_add_u64 v[140:141], s[0:1], 0, v[140:141]
	v_pk_add_f32 v[128:129], v[128:129], v[160:161]
	v_lshlrev_b32_e32 v160, 16, v162
	v_and_b32_e32 v161, 0xffff0000, v162
	v_lshlrev_b32_e32 v162, 16, v163
	v_and_b32_e32 v163, 0xffff0000, v163
	v_sub_f32_e32 v161, v161, v165
	v_sub_f32_e32 v160, v160, v165
	v_sub_f32_e32 v163, v163, v165
	v_sub_f32_e32 v162, v162, v165
	v_pk_mul_f32 v[160:161], v[160:161], v[164:165] op_sel_hi:[1,0]
	v_pk_mul_f32 v[162:163], v[162:163], v[164:165] op_sel_hi:[1,0]
	v_pk_fma_f32 v[160:161], v[196:197], v[160:161], v[200:201]
	v_pk_fma_f32 v[162:163], v[194:195], v[162:163], v[198:199]
	v_pk_add_f32 v[124:125], v[124:125], v[160:161]
	v_lshlrev_b32_e32 v160, 16, v156
	v_and_b32_e32 v156, 0xffff0000, v156
	v_pk_add_f32 v[126:127], v[126:127], v[162:163]
	v_lshlrev_b32_e32 v162, 16, v157
	v_and_b32_e32 v161, 0xffff0000, v157
	v_sub_f32_e32 v157, v156, v165
	v_sub_f32_e32 v156, v160, v165
	v_pk_mul_f32 v[156:157], v[156:157], v[164:165] op_sel_hi:[1,0]
	v_sub_f32_e32 v167, v167, v165
	v_sub_f32_e32 v166, v174, v165
	v_lshl_add_u64 v[226:227], v[140:141], 0, v[222:223]
	v_pk_mul_f32 v[166:167], v[166:167], v[164:165] op_sel_hi:[1,0]
	v_sub_f32_e32 v161, v161, v165
	v_sub_f32_e32 v160, v162, v165
	v_pk_fma_f32 v[166:167], v[190:191], v[166:167], v[202:203]
	v_pk_mul_f32 v[160:161], v[160:161], v[164:165] op_sel_hi:[1,0]
	v_pk_add_f32 v[130:131], v[130:131], v[166:167]
	s_waitcnt vmcnt(1)
	v_pk_mul_f32 v[214:215], v[150:151], s[86:87] op_sel_hi:[1,0]
	s_waitcnt vmcnt(0)
	v_pk_mul_f32 v[218:219], v[154:155], s[86:87] op_sel_hi:[1,0]
	v_pk_mul_f32 v[220:221], v[152:153], s[86:87] op_sel_hi:[1,0]
	global_load_dwordx4 v[152:155], v[142:143], off
	v_pk_fma_f32 v[156:157], v[208:209], v[156:157], v[220:221]
	v_pk_mul_f32 v[216:217], v[148:149], s[86:87] op_sel_hi:[1,0]
	v_pk_add_f32 v[120:121], v[120:121], v[156:157]
	v_lshlrev_b32_e32 v156, 16, v158
	v_and_b32_e32 v157, 0xffff0000, v158
	v_lshlrev_b32_e32 v158, 16, v159
	v_and_b32_e32 v159, 0xffff0000, v159
	v_sub_f32_e32 v157, v157, v165
	v_sub_f32_e32 v156, v156, v165
	v_sub_f32_e32 v159, v159, v165
	v_sub_f32_e32 v158, v158, v165
	v_pk_mul_f32 v[158:159], v[158:159], v[164:165] op_sel_hi:[1,0]
	v_pk_mul_f32 v[156:157], v[156:157], v[164:165] op_sel_hi:[1,0]
	global_load_dwordx4 v[148:151], v[226:227], off
	global_load_dwordx4 v[140:143], v[226:227], off offset:64
	v_pk_fma_f32 v[156:157], v[156:157], v[212:213], v[216:217]
	v_pk_fma_f32 v[158:159], v[158:159], v[210:211], v[214:215]
	v_pk_fma_f32 v[160:161], v[206:207], v[160:161], v[218:219]
	v_pk_add_f32 v[158:159], v[118:119], v[158:159]
	v_pk_add_f32 v[156:157], v[116:117], v[156:157]
	v_cvt_pk_bf16_f32 v116, v128, v129
	v_cvt_pk_bf16_f32 v117, v130, v131
	v_cvt_pk_bf16_f32 v118, v124, v125
	v_cvt_pk_bf16_f32 v119, v126, v127
	v_pk_add_f32 v[122:123], v[122:123], v[160:161]
	global_store_dwordx4 v[228:229], v[116:119], off
	v_pk_add_f32 v[160:161], v[120:121], v[156:157]
	v_pk_add_f32 v[162:163], v[122:123], v[158:159]
	v_cvt_pk_bf16_f32 v116, v120, v121
	v_cvt_pk_bf16_f32 v117, v122, v123
	v_cvt_pk_bf16_f32 v118, v156, v157
	v_cvt_pk_bf16_f32 v119, v158, v159
	global_store_dwordx4 v[228:229], v[116:119], off offset:64
	s_nop 1
	v_pk_add_f32 v[116:117], v[128:129], v[124:125]
	v_pk_add_f32 v[118:119], v[130:131], v[126:127]
	v_pk_mul_f32 v[126:127], v[126:127], v[126:127]
	v_pk_mul_f32 v[124:125], v[124:125], v[124:125]
	v_pk_fma_f32 v[126:127], v[130:131], v[130:131], v[126:127]
	v_pk_fma_f32 v[124:125], v[128:129], v[128:129], v[124:125]
	v_pk_mul_f32 v[128:129], v[158:159], v[158:159]
	v_pk_mul_f32 v[130:131], v[156:157], v[156:157]
	v_pk_add_f32 v[118:119], v[118:119], v[162:163]
	v_pk_add_f32 v[116:117], v[116:117], v[160:161]
	v_pk_fma_f32 v[120:121], v[120:121], v[120:121], v[130:131]
	v_pk_fma_f32 v[122:123], v[122:123], v[122:123], v[128:129]
	v_pk_add_f32 v[120:121], v[124:125], v[120:121]
	v_pk_add_f32 v[122:123], v[126:127], v[122:123]
	v_add_f32_e32 v116, v116, v117
	v_add_f32_e32 v117, v118, v119
	v_add_f32_e32 v116, v116, v117
	v_add_f32_e32 v117, v120, v121
	v_add_f32_e32 v118, v122, v123
	v_and_b32_e32 v119, 64, v230
	v_add_f32_e32 v117, v117, v118
	v_xor_b32_e32 v118, 16, v230
	v_add_u32_e32 v119, 64, v119
	v_cmp_lt_i32_e32 vcc, v118, v119
	v_cvt_f32_i32_e32 v161, v145
	v_cvt_f32_i32_e32 v160, v147
	v_cndmask_b32_e32 v118, v230, v118, vcc
	v_lshlrev_b32_e32 v156, 2, v118
	ds_bpermute_b32 v118, v156, v116
	v_cvt_f32_u32_e32 v145, v144
	v_cvt_f32_u32_e32 v144, v146
	v_lshlrev_b32_e32 v146, 16, v136
	v_and_b32_e32 v136, 0xffff0000, v136
	s_waitcnt lgkmcnt(0)
	v_add_f32_e32 v130, v116, v118
	v_xor_b32_e32 v116, 32, v230
	v_cmp_lt_i32_e32 vcc, v116, v119
	v_pk_fma_f32 v[144:145], v[160:161], s[30:31], v[144:145] op_sel_hi:[1,0,1]
	v_lshlrev_b32_e32 v160, 16, v137
	v_cndmask_b32_e32 v116, v230, v116, vcc
	v_lshlrev_b32_e32 v158, 2, v116
	ds_bpermute_b32 v116, v156, v117
	v_pk_mul_f32 v[144:145], v[144:145], s[90:91] op_sel_hi:[1,0]
	v_and_b32_e32 v147, 0xffff0000, v137
	v_pk_mul_f32 v[144:145], v[144:145], s[92:93] op_sel_hi:[1,0]
	ds_bpermute_b32 v131, v158, v130
	s_waitcnt lgkmcnt(1)
	v_add_f32_e32 v157, v117, v116
	v_or_b32_e32 v116, 48, v188
	v_ashrrev_i32_e32 v117, 31, v116
	v_lshl_add_u64 v[118:119], v[116:117], 4, s[10:11]
	global_load_dwordx4 v[124:127], v[118:119], off
	v_fma_f32 v144, -v145, v145, v144
	v_max_f32_e32 v144, 0, v144
	v_add_f32_e32 v144, 0x3727c5ac, v144
	v_rsq_f32_e32 v144, v144
	v_lshlrev_b64 v[116:117], 12, v[116:117]
	v_lshl_add_u64 v[116:117], s[0:1], 0, v[116:117]
	v_lshl_add_u64 v[128:129], v[116:117], 0, v[222:223]
	v_sub_f32_e32 v137, v136, v145
	v_sub_f32_e32 v136, v146, v145
	global_load_dwordx4 v[120:123], v[128:129], off
	global_load_dwordx4 v[116:119], v[128:129], off offset:64
	v_pk_mul_f32 v[136:137], v[136:137], v[144:145] op_sel_hi:[1,0]
	v_sub_f32_e32 v147, v147, v145
	v_pk_fma_f32 v[136:137], v[192:193], v[136:137], v[204:205]
	v_sub_f32_e32 v146, v160, v145
	v_pk_add_f32 v[112:113], v[112:113], v[136:137]
	v_lshlrev_b32_e32 v136, 16, v138
	v_and_b32_e32 v137, 0xffff0000, v138
	v_lshlrev_b32_e32 v138, 16, v139
	v_and_b32_e32 v139, 0xffff0000, v139
	v_sub_f32_e32 v137, v137, v145
	v_sub_f32_e32 v136, v136, v145
	v_sub_f32_e32 v139, v139, v145
	v_sub_f32_e32 v138, v138, v145
	v_pk_mul_f32 v[136:137], v[136:137], v[144:145] op_sel_hi:[1,0]
	v_pk_mul_f32 v[138:139], v[138:139], v[144:145] op_sel_hi:[1,0]
	v_pk_fma_f32 v[136:137], v[196:197], v[136:137], v[200:201]
	v_pk_fma_f32 v[138:139], v[194:195], v[138:139], v[198:199]
	v_pk_add_f32 v[108:109], v[108:109], v[136:137]
	v_lshlrev_b32_e32 v136, 16, v132
	v_and_b32_e32 v132, 0xffff0000, v132
	v_pk_add_f32 v[110:111], v[110:111], v[138:139]
	v_lshlrev_b32_e32 v138, 16, v133
	v_and_b32_e32 v137, 0xffff0000, v133
	v_sub_f32_e32 v133, v132, v145
	v_sub_f32_e32 v132, v136, v145
	v_pk_mul_f32 v[132:133], v[132:133], v[144:145] op_sel_hi:[1,0]
	v_pk_mul_f32 v[146:147], v[146:147], v[144:145] op_sel_hi:[1,0]
	v_pk_fma_f32 v[132:133], v[208:209], v[132:133], v[220:221]
	v_sub_f32_e32 v137, v137, v145
	v_pk_add_f32 v[104:105], v[104:105], v[132:133]
	v_lshlrev_b32_e32 v132, 16, v134
	v_and_b32_e32 v133, 0xffff0000, v134
	v_lshlrev_b32_e32 v134, 16, v135
	v_and_b32_e32 v135, 0xffff0000, v135
	v_sub_f32_e32 v133, v133, v145
	v_sub_f32_e32 v132, v132, v145
	v_sub_f32_e32 v135, v135, v145
	v_sub_f32_e32 v134, v134, v145
	v_sub_f32_e32 v136, v138, v145
	v_pk_mul_f32 v[134:135], v[134:135], v[144:145] op_sel_hi:[1,0]
	v_pk_mul_f32 v[132:133], v[132:133], v[144:145] op_sel_hi:[1,0]
	v_pk_fma_f32 v[146:147], v[190:191], v[146:147], v[202:203]
	v_pk_mul_f32 v[136:137], v[136:137], v[144:145] op_sel_hi:[1,0]
	v_pk_fma_f32 v[132:133], v[212:213], v[132:133], v[216:217]
	v_pk_fma_f32 v[134:135], v[210:211], v[134:135], v[214:215]
	v_pk_add_f32 v[114:115], v[114:115], v[146:147]
	v_pk_fma_f32 v[136:137], v[206:207], v[136:137], v[218:219]
	v_pk_add_f32 v[134:135], v[102:103], v[134:135]
	v_pk_add_f32 v[132:133], v[100:101], v[132:133]
	v_cvt_pk_bf16_f32 v100, v112, v113
	v_cvt_pk_bf16_f32 v101, v114, v115
	v_cvt_pk_bf16_f32 v102, v108, v109
	v_cvt_pk_bf16_f32 v103, v110, v111
	v_pk_add_f32 v[106:107], v[106:107], v[136:137]
	global_store_dwordx4 v[224:225], v[100:103], off
	v_pk_add_f32 v[136:137], v[104:105], v[132:133]
	v_pk_add_f32 v[138:139], v[106:107], v[134:135]
	v_cvt_pk_bf16_f32 v100, v104, v105
	v_cvt_pk_bf16_f32 v101, v106, v107
	v_cvt_pk_bf16_f32 v102, v132, v133
	v_cvt_pk_bf16_f32 v103, v134, v135
	global_store_dwordx4 v[224:225], v[100:103], off offset:64
	s_waitcnt vmcnt(8)
	v_lshlrev_b32_e32 v144, 16, v149
	v_and_b32_e32 v145, 0xffff0000, v149
	v_pk_add_f32 v[100:101], v[112:113], v[108:109]
	v_pk_add_f32 v[102:103], v[114:115], v[110:111]
	v_pk_mul_f32 v[110:111], v[110:111], v[110:111]
	v_pk_mul_f32 v[108:109], v[108:109], v[108:109]
	v_pk_fma_f32 v[110:111], v[114:115], v[114:115], v[110:111]
	v_pk_fma_f32 v[108:109], v[112:113], v[112:113], v[108:109]
	v_pk_mul_f32 v[112:113], v[134:135], v[134:135]
	v_pk_mul_f32 v[114:115], v[132:133], v[132:133]
	v_pk_add_f32 v[102:103], v[102:103], v[138:139]
	v_pk_add_f32 v[100:101], v[100:101], v[136:137]
	v_pk_fma_f32 v[104:105], v[104:105], v[104:105], v[114:115]
	v_pk_fma_f32 v[106:107], v[106:107], v[106:107], v[112:113]
	v_pk_add_f32 v[104:105], v[108:109], v[104:105]
	v_pk_add_f32 v[106:107], v[110:111], v[106:107]
	v_add_f32_e32 v100, v100, v101
	v_add_f32_e32 v101, v102, v103
	v_add_f32_e32 v100, v100, v101
	v_add_f32_e32 v101, v104, v105
	v_add_f32_e32 v102, v106, v107
	v_add_f32_e32 v101, v101, v102
	ds_bpermute_b32 v102, v156, v100
	v_cvt_f32_i32_e32 v137, v153
	v_cvt_f32_i32_e32 v136, v155
	v_cvt_f32_u32_e32 v139, v152
	v_cvt_f32_u32_e32 v138, v154
	s_waitcnt lgkmcnt(0)
	v_add_f32_e32 v132, v100, v102
	ds_bpermute_b32 v100, v156, v101
	v_add_u32_e32 v112, 0x80, v188
	v_ashrrev_i32_e32 v113, 31, v112
	v_pk_fma_f32 v[136:137], v[136:137], s[30:31], v[138:139] op_sel_hi:[1,0,1]
	v_and_b32_e32 v138, 0xffff0000, v148
	s_waitcnt lgkmcnt(0)
	v_add_f32_e32 v134, v101, v100
	v_lshl_add_u64 v[100:101], v[112:113], 4, s[10:11]
	v_pk_mul_f32 v[136:137], v[136:137], s[90:91] op_sel_hi:[1,0]
	global_load_dwordx4 v[108:111], v[100:101], off
	v_pk_mul_f32 v[136:137], v[136:137], s[92:93] op_sel_hi:[1,0]
	v_lshlrev_b64 v[100:101], 12, v[112:113]
	v_fma_f32 v113, -v137, v137, v136
	v_max_f32_e32 v113, 0, v113
	v_add_f32_e32 v113, 0x3727c5ac, v113
	v_rsq_f32_e32 v136, v113
	v_lshlrev_b32_e32 v113, 16, v148
	v_sub_f32_e32 v139, v138, v137
	v_sub_f32_e32 v138, v113, v137
	v_pk_mul_f32 v[138:139], v[138:139], v[136:137] op_sel_hi:[1,0]
	v_lshlrev_b32_e32 v113, 16, v150
	v_pk_fma_f32 v[138:139], v[192:193], v[138:139], v[204:205]
	v_lshl_add_u64 v[100:101], s[0:1], 0, v[100:101]
	v_pk_add_f32 v[96:97], v[96:97], v[138:139]
	v_and_b32_e32 v138, 0xffff0000, v150
	v_sub_f32_e32 v139, v138, v137
	v_sub_f32_e32 v138, v113, v137
	v_lshl_add_u64 v[114:115], v[100:101], 0, v[222:223]
	v_pk_mul_f32 v[138:139], v[138:139], v[136:137] op_sel_hi:[1,0]
	global_load_dwordx4 v[104:107], v[114:115], off
	global_load_dwordx4 v[100:103], v[114:115], off offset:64
	v_pk_fma_f32 v[138:139], v[196:197], v[138:139], v[200:201]
	s_waitcnt vmcnt(10)
	v_lshlrev_b32_e32 v113, 16, v140
	v_pk_add_f32 v[92:93], v[92:93], v[138:139]
	v_and_b32_e32 v138, 0xffff0000, v140
	v_lshlrev_b32_e32 v140, 16, v141
	v_and_b32_e32 v141, 0xffff0000, v141
	v_sub_f32_e32 v145, v145, v137
	v_sub_f32_e32 v144, v144, v137
	v_sub_f32_e32 v139, v138, v137
	v_sub_f32_e32 v138, v113, v137
	v_sub_f32_e32 v141, v141, v137
	v_sub_f32_e32 v140, v140, v137
	v_pk_mul_f32 v[144:145], v[144:145], v[136:137] op_sel_hi:[1,0]
	v_pk_mul_f32 v[140:141], v[140:141], v[136:137] op_sel_hi:[1,0]
	v_pk_mul_f32 v[138:139], v[138:139], v[136:137] op_sel_hi:[1,0]
	v_pk_fma_f32 v[144:145], v[190:191], v[144:145], v[202:203]
	v_pk_fma_f32 v[138:139], v[208:209], v[138:139], v[220:221]
	v_pk_fma_f32 v[140:141], v[206:207], v[140:141], v[218:219]
	v_pk_add_f32 v[98:99], v[98:99], v[144:145]
	v_lshlrev_b32_e32 v144, 16, v151
	v_and_b32_e32 v145, 0xffff0000, v151
	v_pk_add_f32 v[90:91], v[90:91], v[140:141]
	v_pk_add_f32 v[88:89], v[88:89], v[138:139]
	v_lshlrev_b32_e32 v113, 16, v142
	v_and_b32_e32 v138, 0xffff0000, v142
	v_lshlrev_b32_e32 v140, 16, v143
	v_and_b32_e32 v141, 0xffff0000, v143
	v_sub_f32_e32 v145, v145, v137
	v_sub_f32_e32 v144, v144, v137
	v_sub_f32_e32 v139, v138, v137
	v_sub_f32_e32 v138, v113, v137
	v_sub_f32_e32 v141, v141, v137
	v_sub_f32_e32 v140, v140, v137
	v_pk_mul_f32 v[144:145], v[144:145], v[136:137] op_sel_hi:[1,0]
	v_pk_mul_f32 v[140:141], v[140:141], v[136:137] op_sel_hi:[1,0]
	v_pk_mul_f32 v[136:137], v[138:139], v[136:137] op_sel_hi:[1,0]
	v_pk_fma_f32 v[144:145], v[194:195], v[144:145], v[198:199]
	v_pk_fma_f32 v[136:137], v[212:213], v[136:137], v[216:217]
	v_pk_fma_f32 v[138:139], v[210:211], v[140:141], v[214:215]
	v_pk_add_f32 v[94:95], v[94:95], v[144:145]
	v_pk_add_f32 v[138:139], v[86:87], v[138:139]
	v_pk_add_f32 v[136:137], v[84:85], v[136:137]
	v_cvt_pk_bf16_f32 v84, v96, v97
	v_cvt_pk_bf16_f32 v85, v98, v99
	v_cvt_pk_bf16_f32 v86, v92, v93
	v_cvt_pk_bf16_f32 v87, v94, v95
	global_store_dwordx4 v[226:227], v[84:87], off
	v_pk_add_f32 v[140:141], v[88:89], v[136:137]
	v_pk_add_f32 v[142:143], v[90:91], v[138:139]
	v_cvt_pk_bf16_f32 v84, v88, v89
	v_cvt_pk_bf16_f32 v85, v90, v91
	v_cvt_pk_bf16_f32 v86, v136, v137
	v_cvt_pk_bf16_f32 v87, v138, v139
	global_store_dwordx4 v[226:227], v[84:87], off offset:64
	ds_bpermute_b32 v159, v158, v157
	ds_bpermute_b32 v135, v158, v134
	v_pk_add_f32 v[84:85], v[96:97], v[92:93]
	v_pk_add_f32 v[86:87], v[98:99], v[94:95]
	v_pk_mul_f32 v[94:95], v[94:95], v[94:95]
	v_pk_mul_f32 v[92:93], v[92:93], v[92:93]
	v_pk_fma_f32 v[94:95], v[98:99], v[98:99], v[94:95]
	v_pk_fma_f32 v[92:93], v[96:97], v[96:97], v[92:93]
	v_pk_mul_f32 v[96:97], v[138:139], v[138:139]
	v_pk_mul_f32 v[98:99], v[136:137], v[136:137]
	v_pk_add_f32 v[86:87], v[86:87], v[142:143]
	v_pk_add_f32 v[84:85], v[84:85], v[140:141]
	v_pk_fma_f32 v[88:89], v[88:89], v[88:89], v[98:99]
	v_pk_fma_f32 v[90:91], v[90:91], v[90:91], v[96:97]
	v_pk_add_f32 v[88:89], v[92:93], v[88:89]
	v_pk_add_f32 v[90:91], v[94:95], v[90:91]
	v_add_f32_e32 v84, v84, v85
	v_add_f32_e32 v85, v86, v87
	v_add_f32_e32 v84, v84, v85
	v_add_f32_e32 v85, v88, v89
	v_add_f32_e32 v86, v90, v91
	v_add_f32_e32 v85, v85, v86
	ds_bpermute_b32 v86, v156, v84
	s_waitcnt vmcnt(9)
	v_cvt_f32_i32_e32 v139, v125
	v_cvt_f32_i32_e32 v138, v127
	v_cvt_f32_u32_e32 v125, v124
	v_cvt_f32_u32_e32 v124, v126
	s_waitcnt lgkmcnt(0)
	v_add_f32_e32 v98, v84, v86
	ds_bpermute_b32 v84, v156, v85
	s_waitcnt vmcnt(8)
	v_lshlrev_b32_e32 v126, 16, v120
	v_pk_fma_f32 v[124:125], v[138:139], s[30:31], v[124:125] op_sel_hi:[1,0,1]
	v_and_b32_e32 v120, 0xffff0000, v120
	v_pk_mul_f32 v[124:125], v[124:125], s[90:91] op_sel_hi:[1,0]
	s_waitcnt lgkmcnt(0)
	v_add_f32_e32 v113, v85, v84
	v_add_u32_e32 v84, 0x90, v188
	v_ashrrev_i32_e32 v85, 31, v84
	v_lshl_add_u64 v[86:87], v[84:85], 4, s[10:11]
	v_pk_mul_f32 v[124:125], v[124:125], s[92:93] op_sel_hi:[1,0]
	global_load_dwordx4 v[92:95], v[86:87], off
	v_fma_f32 v124, -v125, v125, v124
	v_max_f32_e32 v124, 0, v124
	v_add_f32_e32 v124, 0x3727c5ac, v124
	v_rsq_f32_e32 v124, v124
	v_lshlrev_b32_e32 v137, 16, v121
	v_and_b32_e32 v127, 0xffff0000, v121
	v_sub_f32_e32 v121, v120, v125
	v_sub_f32_e32 v120, v126, v125
	v_pk_mul_f32 v[120:121], v[120:121], v[124:125] op_sel_hi:[1,0]
	v_lshlrev_b64 v[84:85], 12, v[84:85]
	v_pk_fma_f32 v[120:121], v[192:193], v[120:121], v[204:205]
	v_lshl_add_u64 v[84:85], s[0:1], 0, v[84:85]
	v_pk_add_f32 v[80:81], v[80:81], v[120:121]
	v_lshlrev_b32_e32 v120, 16, v122
	v_and_b32_e32 v121, 0xffff0000, v122
	v_lshlrev_b32_e32 v122, 16, v123
	v_and_b32_e32 v123, 0xffff0000, v123
	v_sub_f32_e32 v121, v121, v125
	v_sub_f32_e32 v120, v120, v125
	v_sub_f32_e32 v123, v123, v125
	v_sub_f32_e32 v122, v122, v125
	v_pk_mul_f32 v[120:121], v[120:121], v[124:125] op_sel_hi:[1,0]
	v_lshl_add_u64 v[96:97], v[84:85], 0, v[222:223]
	v_pk_mul_f32 v[122:123], v[122:123], v[124:125] op_sel_hi:[1,0]
	v_pk_fma_f32 v[120:121], v[196:197], v[120:121], v[200:201]
	global_load_dwordx4 v[88:91], v[96:97], off
	global_load_dwordx4 v[84:87], v[96:97], off offset:64
	v_pk_fma_f32 v[122:123], v[194:195], v[122:123], v[198:199]
	v_pk_add_f32 v[76:77], v[76:77], v[120:121]
	s_waitcnt vmcnt(10)
	v_lshlrev_b32_e32 v120, 16, v116
	v_and_b32_e32 v116, 0xffff0000, v116
	v_pk_add_f32 v[78:79], v[78:79], v[122:123]
	v_lshlrev_b32_e32 v122, 16, v117
	v_and_b32_e32 v121, 0xffff0000, v117
	v_sub_f32_e32 v117, v116, v125
	v_sub_f32_e32 v116, v120, v125
	v_pk_mul_f32 v[116:117], v[116:117], v[124:125] op_sel_hi:[1,0]
	v_sub_f32_e32 v127, v127, v125
	v_pk_fma_f32 v[116:117], v[208:209], v[116:117], v[220:221]
	v_sub_f32_e32 v126, v137, v125
	v_pk_add_f32 v[72:73], v[72:73], v[116:117]
	v_lshlrev_b32_e32 v116, 16, v118
	v_and_b32_e32 v117, 0xffff0000, v118
	v_lshlrev_b32_e32 v118, 16, v119
	v_and_b32_e32 v119, 0xffff0000, v119
	v_sub_f32_e32 v117, v117, v125
	v_sub_f32_e32 v116, v116, v125
	v_sub_f32_e32 v119, v119, v125
	v_sub_f32_e32 v118, v118, v125
	v_pk_mul_f32 v[126:127], v[126:127], v[124:125] op_sel_hi:[1,0]
	v_sub_f32_e32 v121, v121, v125
	v_sub_f32_e32 v120, v122, v125
	v_pk_mul_f32 v[118:119], v[118:119], v[124:125] op_sel_hi:[1,0]
	v_pk_mul_f32 v[116:117], v[116:117], v[124:125] op_sel_hi:[1,0]
	v_pk_fma_f32 v[126:127], v[190:191], v[126:127], v[202:203]
	v_pk_mul_f32 v[120:121], v[120:121], v[124:125] op_sel_hi:[1,0]
	v_pk_fma_f32 v[116:117], v[212:213], v[116:117], v[216:217]
	v_pk_fma_f32 v[118:119], v[210:211], v[118:119], v[214:215]
	v_pk_add_f32 v[82:83], v[82:83], v[126:127]
	v_pk_fma_f32 v[120:121], v[206:207], v[120:121], v[218:219]
	v_pk_add_f32 v[118:119], v[70:71], v[118:119]
	v_pk_add_f32 v[116:117], v[68:69], v[116:117]
	v_cvt_pk_bf16_f32 v68, v80, v81
	v_cvt_pk_bf16_f32 v69, v82, v83
	v_cvt_pk_bf16_f32 v70, v76, v77
	v_cvt_pk_bf16_f32 v71, v78, v79
	v_pk_add_f32 v[74:75], v[74:75], v[120:121]
	global_store_dwordx4 v[128:129], v[68:71], off
	v_pk_add_f32 v[120:121], v[72:73], v[116:117]
	v_pk_add_f32 v[122:123], v[74:75], v[118:119]
	v_cvt_pk_bf16_f32 v68, v72, v73
	v_cvt_pk_bf16_f32 v69, v74, v75
	v_cvt_pk_bf16_f32 v70, v116, v117
	v_cvt_pk_bf16_f32 v71, v118, v119
	global_store_dwordx4 v[128:129], v[68:71], off offset:64
	ds_bpermute_b32 v136, v158, v113
	ds_bpermute_b32 v133, v158, v132
	v_pk_add_f32 v[68:69], v[80:81], v[76:77]
	v_pk_add_f32 v[70:71], v[82:83], v[78:79]
	v_pk_mul_f32 v[78:79], v[78:79], v[78:79]
	v_pk_mul_f32 v[76:77], v[76:77], v[76:77]
	v_pk_fma_f32 v[78:79], v[82:83], v[82:83], v[78:79]
	v_pk_fma_f32 v[76:77], v[80:81], v[80:81], v[76:77]
	v_pk_mul_f32 v[80:81], v[118:119], v[118:119]
	v_pk_mul_f32 v[82:83], v[116:117], v[116:117]
	v_pk_add_f32 v[70:71], v[70:71], v[122:123]
	v_pk_add_f32 v[68:69], v[68:69], v[120:121]
	v_pk_fma_f32 v[72:73], v[72:73], v[72:73], v[82:83]
	v_pk_fma_f32 v[74:75], v[74:75], v[74:75], v[80:81]
	v_pk_add_f32 v[72:73], v[76:77], v[72:73]
	v_pk_add_f32 v[74:75], v[78:79], v[74:75]
	v_add_f32_e32 v68, v68, v69
	v_add_f32_e32 v69, v70, v71
	v_add_f32_e32 v68, v68, v69
	v_add_f32_e32 v69, v72, v73
	v_add_f32_e32 v70, v74, v75
	v_add_f32_e32 v69, v69, v70
	ds_bpermute_b32 v70, v156, v68
	s_waitcnt vmcnt(9)
	v_cvt_f32_i32_e32 v119, v109
	v_cvt_f32_i32_e32 v118, v111
	v_cvt_f32_u32_e32 v109, v108
	v_cvt_f32_u32_e32 v108, v110
	s_waitcnt lgkmcnt(0)
	v_add_f32_e32 v82, v68, v70
	ds_bpermute_b32 v68, v156, v69
	s_waitcnt vmcnt(8)
	v_lshlrev_b32_e32 v110, 16, v104
	v_pk_fma_f32 v[108:109], v[118:119], s[30:31], v[108:109] op_sel_hi:[1,0,1]
	v_and_b32_e32 v104, 0xffff0000, v104
	v_pk_mul_f32 v[108:109], v[108:109], s[90:91] op_sel_hi:[1,0]
	s_waitcnt lgkmcnt(0)
	v_add_f32_e32 v116, v69, v68
	v_add_u32_e32 v68, 0xa0, v188
	v_ashrrev_i32_e32 v69, 31, v68
	v_lshl_add_u64 v[70:71], v[68:69], 4, s[10:11]
	global_load_dwordx4 v[76:79], v[70:71], off
	v_pk_mul_f32 v[108:109], v[108:109], s[92:93] op_sel_hi:[1,0]
	v_lshlrev_b64 v[68:69], 12, v[68:69]
	v_fma_f32 v108, -v109, v109, v108
	v_max_f32_e32 v108, 0, v108
	v_add_f32_e32 v108, 0x3727c5ac, v108
	v_rsq_f32_e32 v108, v108
	v_lshlrev_b32_e32 v118, 16, v105
	v_and_b32_e32 v111, 0xffff0000, v105
	v_sub_f32_e32 v105, v104, v109
	v_sub_f32_e32 v104, v110, v109
	v_lshl_add_u64 v[68:69], s[0:1], 0, v[68:69]
	v_pk_mul_f32 v[104:105], v[104:105], v[108:109] op_sel_hi:[1,0]
	v_lshl_add_u64 v[80:81], v[68:69], 0, v[222:223]
	v_pk_fma_f32 v[104:105], v[192:193], v[104:105], v[204:205]
	global_load_dwordx4 v[72:75], v[80:81], off
	global_load_dwordx4 v[68:71], v[80:81], off offset:64
	v_pk_add_f32 v[64:65], v[64:65], v[104:105]
	v_lshlrev_b32_e32 v104, 16, v106
	v_and_b32_e32 v105, 0xffff0000, v106
	v_lshlrev_b32_e32 v106, 16, v107
	v_and_b32_e32 v107, 0xffff0000, v107
	v_sub_f32_e32 v105, v105, v109
	v_sub_f32_e32 v104, v104, v109
	v_sub_f32_e32 v107, v107, v109
	v_sub_f32_e32 v106, v106, v109
	v_pk_mul_f32 v[104:105], v[104:105], v[108:109] op_sel_hi:[1,0]
	v_pk_mul_f32 v[106:107], v[106:107], v[108:109] op_sel_hi:[1,0]
	v_pk_fma_f32 v[104:105], v[196:197], v[104:105], v[200:201]
	v_pk_fma_f32 v[106:107], v[194:195], v[106:107], v[198:199]
	v_pk_add_f32 v[60:61], v[60:61], v[104:105]
	s_waitcnt vmcnt(10)
	v_lshlrev_b32_e32 v104, 16, v100
	v_and_b32_e32 v100, 0xffff0000, v100
	v_pk_add_f32 v[62:63], v[62:63], v[106:107]
	v_lshlrev_b32_e32 v106, 16, v101
	v_and_b32_e32 v105, 0xffff0000, v101
	v_sub_f32_e32 v101, v100, v109
	v_sub_f32_e32 v100, v104, v109
	v_pk_mul_f32 v[100:101], v[100:101], v[108:109] op_sel_hi:[1,0]
	v_sub_f32_e32 v111, v111, v109
	v_pk_fma_f32 v[100:101], v[208:209], v[100:101], v[220:221]
	v_sub_f32_e32 v110, v118, v109
	v_pk_add_f32 v[56:57], v[56:57], v[100:101]
	v_lshlrev_b32_e32 v100, 16, v102
	v_and_b32_e32 v101, 0xffff0000, v102
	v_lshlrev_b32_e32 v102, 16, v103
	v_and_b32_e32 v103, 0xffff0000, v103
	v_sub_f32_e32 v101, v101, v109
	v_sub_f32_e32 v100, v100, v109
	v_sub_f32_e32 v103, v103, v109
	v_sub_f32_e32 v102, v102, v109
	v_pk_mul_f32 v[110:111], v[110:111], v[108:109] op_sel_hi:[1,0]
	v_sub_f32_e32 v105, v105, v109
	v_sub_f32_e32 v104, v106, v109
	v_pk_mul_f32 v[102:103], v[102:103], v[108:109] op_sel_hi:[1,0]
	v_pk_mul_f32 v[100:101], v[100:101], v[108:109] op_sel_hi:[1,0]
	v_pk_fma_f32 v[110:111], v[190:191], v[110:111], v[202:203]
	v_pk_mul_f32 v[104:105], v[104:105], v[108:109] op_sel_hi:[1,0]
	v_pk_fma_f32 v[100:101], v[212:213], v[100:101], v[216:217]
	v_pk_fma_f32 v[102:103], v[210:211], v[102:103], v[214:215]
	v_pk_add_f32 v[66:67], v[66:67], v[110:111]
	v_pk_fma_f32 v[104:105], v[206:207], v[104:105], v[218:219]
	v_pk_add_f32 v[102:103], v[54:55], v[102:103]
	v_pk_add_f32 v[100:101], v[52:53], v[100:101]
	v_cvt_pk_bf16_f32 v52, v64, v65
	v_cvt_pk_bf16_f32 v53, v66, v67
	v_cvt_pk_bf16_f32 v54, v60, v61
	v_cvt_pk_bf16_f32 v55, v62, v63
	v_pk_add_f32 v[58:59], v[58:59], v[104:105]
	global_store_dwordx4 v[114:115], v[52:55], off
	v_pk_add_f32 v[104:105], v[56:57], v[100:101]
	v_pk_add_f32 v[106:107], v[58:59], v[102:103]
	v_cvt_pk_bf16_f32 v52, v56, v57
	v_cvt_pk_bf16_f32 v53, v58, v59
	v_cvt_pk_bf16_f32 v54, v100, v101
	v_cvt_pk_bf16_f32 v55, v102, v103
	global_store_dwordx4 v[114:115], v[52:55], off offset:64
	ds_bpermute_b32 v117, v158, v116
	ds_bpermute_b32 v99, v158, v98
	v_pk_add_f32 v[52:53], v[64:65], v[60:61]
	v_pk_add_f32 v[54:55], v[66:67], v[62:63]
	v_pk_mul_f32 v[62:63], v[62:63], v[62:63]
	v_pk_mul_f32 v[60:61], v[60:61], v[60:61]
	v_pk_fma_f32 v[62:63], v[66:67], v[66:67], v[62:63]
	v_pk_fma_f32 v[60:61], v[64:65], v[64:65], v[60:61]
	v_pk_mul_f32 v[64:65], v[102:103], v[102:103]
	v_pk_mul_f32 v[66:67], v[100:101], v[100:101]
	v_pk_add_f32 v[54:55], v[54:55], v[106:107]
	v_pk_add_f32 v[52:53], v[52:53], v[104:105]
	v_pk_fma_f32 v[56:57], v[56:57], v[56:57], v[66:67]
	v_pk_fma_f32 v[58:59], v[58:59], v[58:59], v[64:65]
	v_pk_add_f32 v[56:57], v[60:61], v[56:57]
	v_pk_add_f32 v[58:59], v[62:63], v[58:59]
	v_add_f32_e32 v52, v52, v53
	v_add_f32_e32 v53, v54, v55
	v_add_f32_e32 v52, v52, v53
	v_add_f32_e32 v53, v56, v57
	v_add_f32_e32 v54, v58, v59
	v_add_f32_e32 v53, v53, v54
	ds_bpermute_b32 v54, v156, v52
	s_waitcnt vmcnt(9)
	v_cvt_f32_i32_e32 v103, v93
	v_cvt_f32_i32_e32 v102, v95
	v_cvt_f32_u32_e32 v93, v92
	v_cvt_f32_u32_e32 v92, v94
	s_waitcnt lgkmcnt(0)
	v_add_f32_e32 v66, v52, v54
	ds_bpermute_b32 v52, v156, v53
	s_waitcnt vmcnt(8)
	v_lshlrev_b32_e32 v94, 16, v88
	v_pk_fma_f32 v[92:93], v[102:103], s[30:31], v[92:93] op_sel_hi:[1,0,1]
	v_and_b32_e32 v88, 0xffff0000, v88
	v_pk_mul_f32 v[92:93], v[92:93], s[90:91] op_sel_hi:[1,0]
	s_waitcnt lgkmcnt(0)
	v_add_f32_e32 v100, v53, v52
	v_add_u32_e32 v52, 0xb0, v188
	v_ashrrev_i32_e32 v53, 31, v52
	v_lshl_add_u64 v[54:55], v[52:53], 4, s[10:11]
	global_load_dwordx4 v[60:63], v[54:55], off
	v_pk_mul_f32 v[92:93], v[92:93], s[92:93] op_sel_hi:[1,0]
	v_lshlrev_b32_e32 v102, 16, v89
	v_fma_f32 v92, -v93, v93, v92
	v_max_f32_e32 v92, 0, v92
	v_add_f32_e32 v92, 0x3727c5ac, v92
	v_rsq_f32_e32 v92, v92
	v_and_b32_e32 v95, 0xffff0000, v89
	v_sub_f32_e32 v89, v88, v93
	v_sub_f32_e32 v88, v94, v93
	v_pk_mul_f32 v[88:89], v[88:89], v[92:93] op_sel_hi:[1,0]
	v_lshlrev_b64 v[52:53], 12, v[52:53]
	v_pk_fma_f32 v[88:89], v[192:193], v[88:89], v[204:205]
	v_lshl_add_u64 v[52:53], s[0:1], 0, v[52:53]
	v_pk_add_f32 v[48:49], v[48:49], v[88:89]
	v_lshlrev_b32_e32 v88, 16, v90
	v_and_b32_e32 v89, 0xffff0000, v90
	v_lshlrev_b32_e32 v90, 16, v91
	v_and_b32_e32 v91, 0xffff0000, v91
	v_sub_f32_e32 v89, v89, v93
	v_sub_f32_e32 v88, v88, v93
	v_lshl_add_u64 v[64:65], v[52:53], 0, v[222:223]
	v_sub_f32_e32 v91, v91, v93
	v_sub_f32_e32 v90, v90, v93
	v_pk_mul_f32 v[88:89], v[88:89], v[92:93] op_sel_hi:[1,0]
	global_load_dwordx4 v[56:59], v[64:65], off
	global_load_dwordx4 v[52:55], v[64:65], off offset:64
	v_pk_mul_f32 v[90:91], v[90:91], v[92:93] op_sel_hi:[1,0]
	v_pk_fma_f32 v[88:89], v[196:197], v[88:89], v[200:201]
	v_pk_fma_f32 v[90:91], v[194:195], v[90:91], v[198:199]
	v_pk_add_f32 v[44:45], v[44:45], v[88:89]
	s_waitcnt vmcnt(10)
	v_lshlrev_b32_e32 v88, 16, v84
	v_and_b32_e32 v84, 0xffff0000, v84
	v_pk_add_f32 v[46:47], v[46:47], v[90:91]
	v_lshlrev_b32_e32 v90, 16, v85
	v_and_b32_e32 v89, 0xffff0000, v85
	v_sub_f32_e32 v85, v84, v93
	v_sub_f32_e32 v84, v88, v93
	v_pk_mul_f32 v[84:85], v[84:85], v[92:93] op_sel_hi:[1,0]
	v_sub_f32_e32 v95, v95, v93
	v_pk_fma_f32 v[84:85], v[208:209], v[84:85], v[220:221]
	v_sub_f32_e32 v94, v102, v93
	v_pk_add_f32 v[40:41], v[40:41], v[84:85]
	v_lshlrev_b32_e32 v84, 16, v86
	v_and_b32_e32 v85, 0xffff0000, v86
	v_lshlrev_b32_e32 v86, 16, v87
	v_and_b32_e32 v87, 0xffff0000, v87
	v_sub_f32_e32 v85, v85, v93
	v_sub_f32_e32 v84, v84, v93
	v_sub_f32_e32 v87, v87, v93
	v_sub_f32_e32 v86, v86, v93
	v_pk_mul_f32 v[94:95], v[94:95], v[92:93] op_sel_hi:[1,0]
	v_sub_f32_e32 v89, v89, v93
	v_sub_f32_e32 v88, v90, v93
	v_pk_mul_f32 v[86:87], v[86:87], v[92:93] op_sel_hi:[1,0]
	v_pk_mul_f32 v[84:85], v[84:85], v[92:93] op_sel_hi:[1,0]
	v_pk_fma_f32 v[94:95], v[190:191], v[94:95], v[202:203]
	v_pk_mul_f32 v[88:89], v[88:89], v[92:93] op_sel_hi:[1,0]
	v_pk_fma_f32 v[84:85], v[212:213], v[84:85], v[216:217]
	v_pk_fma_f32 v[86:87], v[210:211], v[86:87], v[214:215]
	v_pk_add_f32 v[50:51], v[50:51], v[94:95]
	v_pk_fma_f32 v[88:89], v[206:207], v[88:89], v[218:219]
	v_pk_add_f32 v[86:87], v[38:39], v[86:87]
	v_pk_add_f32 v[84:85], v[36:37], v[84:85]
	v_cvt_pk_bf16_f32 v36, v48, v49
	v_cvt_pk_bf16_f32 v37, v50, v51
	v_cvt_pk_bf16_f32 v38, v44, v45
	v_cvt_pk_bf16_f32 v39, v46, v47
	v_pk_add_f32 v[42:43], v[42:43], v[88:89]
	global_store_dwordx4 v[96:97], v[36:39], off
	v_pk_add_f32 v[88:89], v[40:41], v[84:85]
	v_pk_add_f32 v[90:91], v[42:43], v[86:87]
	v_cvt_pk_bf16_f32 v36, v40, v41
	v_cvt_pk_bf16_f32 v37, v42, v43
	v_cvt_pk_bf16_f32 v38, v84, v85
	v_cvt_pk_bf16_f32 v39, v86, v87
	global_store_dwordx4 v[96:97], v[36:39], off offset:64
	ds_bpermute_b32 v101, v158, v100
	ds_bpermute_b32 v67, v158, v66
	v_pk_add_f32 v[36:37], v[48:49], v[44:45]
	v_pk_add_f32 v[38:39], v[50:51], v[46:47]
	v_pk_mul_f32 v[46:47], v[46:47], v[46:47]
	v_pk_mul_f32 v[44:45], v[44:45], v[44:45]
	v_pk_fma_f32 v[46:47], v[50:51], v[50:51], v[46:47]
	v_pk_fma_f32 v[44:45], v[48:49], v[48:49], v[44:45]
	v_pk_mul_f32 v[48:49], v[86:87], v[86:87]
	v_pk_mul_f32 v[50:51], v[84:85], v[84:85]
	v_pk_add_f32 v[38:39], v[38:39], v[90:91]
	v_pk_add_f32 v[36:37], v[36:37], v[88:89]
	v_pk_fma_f32 v[40:41], v[40:41], v[40:41], v[50:51]
	v_pk_fma_f32 v[42:43], v[42:43], v[42:43], v[48:49]
	v_pk_add_f32 v[40:41], v[44:45], v[40:41]
	v_pk_add_f32 v[42:43], v[46:47], v[42:43]
	v_add_f32_e32 v36, v36, v37
	v_add_f32_e32 v37, v38, v39
	v_add_f32_e32 v36, v36, v37
	v_add_f32_e32 v37, v40, v41
	v_add_f32_e32 v38, v42, v43
	v_add_f32_e32 v38, v37, v38
	ds_bpermute_b32 v39, v156, v38
	s_waitcnt vmcnt(9)
	v_cvt_f32_u32_e32 v41, v76
	v_cvt_f32_u32_e32 v40, v78
	s_waitcnt vmcnt(8)
	v_lshlrev_b32_e32 v42, 16, v73
	v_and_b32_e32 v43, 0xffff0000, v73
	s_waitcnt lgkmcnt(0)
	v_add_f32_e32 v46, v38, v39
	v_cvt_f32_i32_e32 v39, v77
	v_cvt_f32_i32_e32 v38, v79
	ds_bpermute_b32 v37, v156, v36
	ds_bpermute_b32 v47, v158, v46
	ds_bpermute_b32 v83, v158, v82
	v_pk_fma_f32 v[38:39], v[38:39], s[30:31], v[40:41] op_sel_hi:[1,0,1]
	v_lshlrev_b32_e32 v40, 16, v72
	v_pk_mul_f32 v[38:39], v[38:39], s[90:91] op_sel_hi:[1,0]
	v_and_b32_e32 v41, 0xffff0000, v72
	v_pk_mul_f32 v[38:39], v[38:39], s[92:93] op_sel_hi:[1,0]
	s_waitcnt lgkmcnt(2)
	v_add_f32_e32 v36, v36, v37
	v_fma_f32 v38, -v39, v39, v38
	v_max_f32_e32 v38, 0, v38
	v_add_f32_e32 v38, 0x3727c5ac, v38
	v_rsq_f32_e32 v38, v38
	v_sub_f32_e32 v41, v41, v39
	v_sub_f32_e32 v40, v40, v39
	v_sub_f32_e32 v43, v43, v39
	v_sub_f32_e32 v42, v42, v39
	v_pk_mul_f32 v[42:43], v[42:43], v[38:39] op_sel_hi:[1,0]
	v_pk_mul_f32 v[40:41], v[40:41], v[38:39] op_sel_hi:[1,0]
	v_pk_fma_f32 v[42:43], v[190:191], v[42:43], v[202:203]
	v_pk_fma_f32 v[40:41], v[192:193], v[40:41], v[204:205]
	v_pk_add_f32 v[34:35], v[34:35], v[42:43]
	v_pk_add_f32 v[32:33], v[32:33], v[40:41]
	v_lshlrev_b32_e32 v40, 16, v74
	v_and_b32_e32 v41, 0xffff0000, v74
	v_lshlrev_b32_e32 v42, 16, v75
	v_and_b32_e32 v43, 0xffff0000, v75
	v_sub_f32_e32 v41, v41, v39
	v_sub_f32_e32 v40, v40, v39
	v_sub_f32_e32 v43, v43, v39
	v_sub_f32_e32 v42, v42, v39
	v_pk_mul_f32 v[42:43], v[42:43], v[38:39] op_sel_hi:[1,0]
	v_pk_mul_f32 v[40:41], v[40:41], v[38:39] op_sel_hi:[1,0]
	v_pk_fma_f32 v[42:43], v[194:195], v[42:43], v[198:199]
	v_pk_fma_f32 v[40:41], v[196:197], v[40:41], v[200:201]
	v_pk_add_f32 v[30:31], v[30:31], v[42:43]
	v_pk_add_f32 v[28:29], v[28:29], v[40:41]
	s_waitcnt vmcnt(7)
	v_lshlrev_b32_e32 v40, 16, v68
	v_and_b32_e32 v41, 0xffff0000, v68
	v_lshlrev_b32_e32 v42, 16, v69
	v_and_b32_e32 v43, 0xffff0000, v69
	v_sub_f32_e32 v41, v41, v39
	v_sub_f32_e32 v40, v40, v39
	v_sub_f32_e32 v43, v43, v39
	v_sub_f32_e32 v42, v42, v39
	v_pk_mul_f32 v[42:43], v[42:43], v[38:39] op_sel_hi:[1,0]
	v_pk_mul_f32 v[40:41], v[40:41], v[38:39] op_sel_hi:[1,0]
	v_pk_fma_f32 v[42:43], v[206:207], v[42:43], v[218:219]
	v_pk_fma_f32 v[40:41], v[208:209], v[40:41], v[220:221]
	v_pk_add_f32 v[26:27], v[26:27], v[42:43]
	v_pk_add_f32 v[24:25], v[24:25], v[40:41]
	v_lshlrev_b32_e32 v40, 16, v70
	v_and_b32_e32 v41, 0xffff0000, v70
	v_lshlrev_b32_e32 v42, 16, v71
	v_and_b32_e32 v43, 0xffff0000, v71
	v_sub_f32_e32 v41, v41, v39
	v_sub_f32_e32 v40, v40, v39
	v_sub_f32_e32 v43, v43, v39
	v_sub_f32_e32 v42, v42, v39
	v_pk_mul_f32 v[42:43], v[42:43], v[38:39] op_sel_hi:[1,0]
	v_pk_mul_f32 v[38:39], v[40:41], v[38:39] op_sel_hi:[1,0]
	v_pk_fma_f32 v[40:41], v[210:211], v[42:43], v[214:215]
	v_pk_fma_f32 v[38:39], v[212:213], v[38:39], v[216:217]
	v_pk_add_f32 v[40:41], v[22:23], v[40:41]
	v_pk_add_f32 v[38:39], v[20:21], v[38:39]
	v_cvt_pk_bf16_f32 v20, v32, v33
	v_cvt_pk_bf16_f32 v21, v34, v35
	v_cvt_pk_bf16_f32 v22, v28, v29
	v_cvt_pk_bf16_f32 v23, v30, v31
	global_store_dwordx4 v[80:81], v[20:23], off
	v_pk_add_f32 v[42:43], v[24:25], v[38:39]
	v_pk_add_f32 v[44:45], v[26:27], v[40:41]
	v_cvt_pk_bf16_f32 v20, v24, v25
	v_cvt_pk_bf16_f32 v21, v26, v27
	v_cvt_pk_bf16_f32 v22, v38, v39
	v_cvt_pk_bf16_f32 v23, v40, v41
	global_store_dwordx4 v[80:81], v[20:23], off offset:64
	ds_bpermute_b32 v37, v158, v36
	s_mov_b32 s10, 0x2f800000
	v_pk_add_f32 v[20:21], v[32:33], v[28:29]
	v_pk_add_f32 v[22:23], v[34:35], v[30:31]
	v_pk_mul_f32 v[30:31], v[30:31], v[30:31]
	v_pk_mul_f32 v[28:29], v[28:29], v[28:29]
	v_pk_fma_f32 v[30:31], v[34:35], v[34:35], v[30:31]
	v_pk_fma_f32 v[28:29], v[32:33], v[32:33], v[28:29]
	v_pk_mul_f32 v[32:33], v[40:41], v[40:41]
	v_pk_mul_f32 v[34:35], v[38:39], v[38:39]
	v_pk_add_f32 v[22:23], v[22:23], v[44:45]
	v_pk_add_f32 v[20:21], v[20:21], v[42:43]
	v_pk_fma_f32 v[24:25], v[24:25], v[24:25], v[34:35]
	v_pk_fma_f32 v[26:27], v[26:27], v[26:27], v[32:33]
	v_pk_add_f32 v[24:25], v[28:29], v[24:25]
	v_pk_add_f32 v[26:27], v[30:31], v[26:27]
	v_add_f32_e32 v20, v20, v21
	v_add_f32_e32 v21, v22, v23
	v_add_f32_e32 v20, v20, v21
	v_add_f32_e32 v21, v24, v25
	v_add_f32_e32 v22, v26, v27
	v_add_f32_e32 v21, v21, v22
	ds_bpermute_b32 v22, v156, v20
	s_waitcnt vmcnt(6)
	v_cvt_f32_u32_e32 v23, v60
	s_waitcnt vmcnt(5)
	v_lshlrev_b32_e32 v24, 16, v57
	v_and_b32_e32 v25, 0xffff0000, v57
	s_mov_b32 s11, 0xcf800000
	s_waitcnt lgkmcnt(0)
	v_add_f32_e32 v28, v20, v22
	ds_bpermute_b32 v20, v156, v21
	v_cvt_f32_u32_e32 v22, v62
	ds_bpermute_b32 v29, v158, v28
	s_waitcnt lgkmcnt(1)
	v_add_f32_e32 v30, v21, v20
	v_cvt_f32_i32_e32 v21, v61
	v_cvt_f32_i32_e32 v20, v63
	ds_bpermute_b32 v31, v158, v30
	v_pk_fma_f32 v[20:21], v[20:21], s[30:31], v[22:23] op_sel_hi:[1,0,1]
	s_nop 0
	v_pk_mul_f32 v[20:21], v[20:21], s[90:91] op_sel_hi:[1,0]
	v_lshlrev_b32_e32 v22, 16, v56
	v_pk_mul_f32 v[20:21], v[20:21], s[92:93] op_sel_hi:[1,0]
	v_and_b32_e32 v23, 0xffff0000, v56
	v_fma_f32 v20, -v21, v21, v20
	v_max_f32_e32 v20, 0, v20
	v_add_f32_e32 v20, 0x3727c5ac, v20
	v_rsq_f32_e32 v20, v20
	v_sub_f32_e32 v23, v23, v21
	v_sub_f32_e32 v22, v22, v21
	v_sub_f32_e32 v25, v25, v21
	v_sub_f32_e32 v24, v24, v21
	v_pk_mul_f32 v[24:25], v[24:25], v[20:21] op_sel_hi:[1,0]
	v_pk_mul_f32 v[22:23], v[22:23], v[20:21] op_sel_hi:[1,0]
	v_pk_fma_f32 v[24:25], v[190:191], v[24:25], v[202:203]
	v_pk_fma_f32 v[22:23], v[192:193], v[22:23], v[204:205]
	v_pk_add_f32 v[18:19], v[18:19], v[24:25]
	v_pk_add_f32 v[16:17], v[16:17], v[22:23]
	v_lshlrev_b32_e32 v22, 16, v58
	v_and_b32_e32 v23, 0xffff0000, v58
	v_lshlrev_b32_e32 v24, 16, v59
	v_and_b32_e32 v25, 0xffff0000, v59
	v_sub_f32_e32 v23, v23, v21
	v_sub_f32_e32 v22, v22, v21
	v_sub_f32_e32 v25, v25, v21
	v_sub_f32_e32 v24, v24, v21
	v_pk_mul_f32 v[24:25], v[24:25], v[20:21] op_sel_hi:[1,0]
	v_pk_mul_f32 v[22:23], v[22:23], v[20:21] op_sel_hi:[1,0]
	v_pk_fma_f32 v[24:25], v[194:195], v[24:25], v[198:199]
	v_pk_fma_f32 v[22:23], v[196:197], v[22:23], v[200:201]
	v_pk_add_f32 v[14:15], v[14:15], v[24:25]
	v_pk_add_f32 v[12:13], v[12:13], v[22:23]
	s_waitcnt vmcnt(4)
	v_lshlrev_b32_e32 v22, 16, v52
	v_and_b32_e32 v23, 0xffff0000, v52
	v_lshlrev_b32_e32 v24, 16, v53
	v_and_b32_e32 v25, 0xffff0000, v53
	v_sub_f32_e32 v23, v23, v21
	v_sub_f32_e32 v22, v22, v21
	v_sub_f32_e32 v25, v25, v21
	v_sub_f32_e32 v24, v24, v21
	v_pk_mul_f32 v[24:25], v[24:25], v[20:21] op_sel_hi:[1,0]
	v_pk_mul_f32 v[22:23], v[22:23], v[20:21] op_sel_hi:[1,0]
	v_pk_fma_f32 v[24:25], v[206:207], v[24:25], v[218:219]
	v_pk_fma_f32 v[22:23], v[208:209], v[22:23], v[220:221]
	v_pk_add_f32 v[10:11], v[10:11], v[24:25]
	v_pk_add_f32 v[8:9], v[8:9], v[22:23]
	v_lshlrev_b32_e32 v22, 16, v54
	v_and_b32_e32 v23, 0xffff0000, v54
	v_lshlrev_b32_e32 v24, 16, v55
	v_and_b32_e32 v25, 0xffff0000, v55
	v_sub_f32_e32 v23, v23, v21
	v_sub_f32_e32 v22, v22, v21
	v_sub_f32_e32 v25, v25, v21
	v_sub_f32_e32 v24, v24, v21
	v_pk_mul_f32 v[24:25], v[24:25], v[20:21] op_sel_hi:[1,0]
	v_pk_mul_f32 v[20:21], v[22:23], v[20:21] op_sel_hi:[1,0]
	v_pk_fma_f32 v[22:23], v[210:211], v[24:25], v[214:215]
	v_pk_fma_f32 v[20:21], v[212:213], v[20:21], v[216:217]
	v_pk_add_f32 v[22:23], v[6:7], v[22:23]
	v_pk_add_f32 v[20:21], v[4:5], v[20:21]
	v_cvt_pk_bf16_f32 v4, v16, v17
	v_cvt_pk_bf16_f32 v5, v18, v19
	v_cvt_pk_bf16_f32 v6, v12, v13
	v_cvt_pk_bf16_f32 v7, v14, v15
	global_store_dwordx4 v[64:65], v[4:7], off
	v_pk_add_f32 v[24:25], v[8:9], v[20:21]
	v_pk_add_f32 v[26:27], v[10:11], v[22:23]
	v_cvt_pk_bf16_f32 v4, v8, v9
	v_cvt_pk_bf16_f32 v5, v10, v11
	v_cvt_pk_bf16_f32 v6, v20, v21
	v_cvt_pk_bf16_f32 v7, v22, v23
	global_store_dwordx4 v[64:65], v[4:7], off offset:64
	s_nop 1
	v_pk_add_f32 v[4:5], v[16:17], v[12:13]
	v_pk_add_f32 v[6:7], v[18:19], v[14:15]
	v_pk_mul_f32 v[14:15], v[14:15], v[14:15]
	v_pk_mul_f32 v[12:13], v[12:13], v[12:13]
	v_pk_fma_f32 v[14:15], v[18:19], v[18:19], v[14:15]
	v_pk_fma_f32 v[12:13], v[16:17], v[16:17], v[12:13]
	v_pk_mul_f32 v[16:17], v[22:23], v[22:23]
	v_pk_mul_f32 v[18:19], v[20:21], v[20:21]
	v_pk_add_f32 v[6:7], v[6:7], v[26:27]
	v_pk_add_f32 v[4:5], v[4:5], v[24:25]
	v_pk_fma_f32 v[8:9], v[8:9], v[8:9], v[18:19]
	v_pk_fma_f32 v[10:11], v[10:11], v[10:11], v[16:17]
	v_pk_add_f32 v[8:9], v[12:13], v[8:9]
	v_pk_add_f32 v[10:11], v[14:15], v[10:11]
	v_add_f32_e32 v4, v4, v5
	v_add_f32_e32 v5, v6, v7
	v_add_f32_e32 v4, v4, v5
	v_add_f32_e32 v5, v8, v9
	v_add_f32_e32 v6, v10, v11
	v_add_f32_e32 v5, v5, v6
	ds_bpermute_b32 v7, v156, v5
	ds_bpermute_b32 v6, v156, v4
	v_add_f32_e32 v9, v100, v101
	v_add_f32_e32 v8, v46, v47
	v_cndmask_b32_e64 v9, 0, v9, s[44:45]
	s_waitcnt lgkmcnt(1)
	v_add_f32_e32 v5, v5, v7
	ds_bpermute_b32 v7, v158, v5
	s_waitcnt lgkmcnt(1)
	v_add_f32_e32 v4, v4, v6
	ds_bpermute_b32 v6, v158, v4
	v_cndmask_b32_e64 v8, v9, v8, s[42:43]
	s_waitcnt lgkmcnt(1)
	v_add_f32_e32 v5, v5, v7
	v_add_f32_e32 v7, v30, v31
	v_cndmask_b32_e64 v7, v8, v7, s[40:41]
	v_cndmask_b32_e64 v10, v7, v5, s[38:39]
	v_add_f32_e32 v7, v66, v67
	s_waitcnt lgkmcnt(0)
	v_add_f32_e32 v4, v4, v6
	v_add_f32_e32 v6, v36, v37
	v_cndmask_b32_e64 v7, 0, v7, s[44:45]
	v_add_f32_e32 v5, v28, v29
	v_cndmask_b32_e64 v6, v7, v6, s[42:43]
	v_add_f32_e32 v7, v157, v159
	v_cndmask_b32_e64 v5, v6, v5, s[40:41]
	v_add_f32_e32 v6, v134, v135
	v_cndmask_b32_e64 v7, 0, v7, s[44:45]
	v_cndmask_b32_e64 v11, v5, v4, s[38:39]
	v_add_f32_e32 v5, v113, v136
	v_cndmask_b32_e64 v6, v7, v6, s[42:43]
	v_add_f32_e32 v7, v130, v131
	v_add_f32_e32 v4, v116, v117
	v_cndmask_b32_e64 v5, v6, v5, s[40:41]
	v_add_f32_e32 v6, v132, v133
	v_cndmask_b32_e64 v7, 0, v7, s[44:45]
	v_cndmask_b32_e64 v12, v5, v4, s[38:39]
	v_add_f32_e32 v5, v98, v99
	v_cndmask_b32_e64 v6, v7, v6, s[42:43]
	v_add_f32_e32 v4, v82, v83
	v_cndmask_b32_e64 v5, v6, v5, s[40:41]
	v_cndmask_b32_e64 v8, v5, v4, s[38:39]
	v_mul_f32_e32 v8, 0x4b800000, v8
	v_rndne_f32_e32 v8, v8
	v_mul_f32_e64 v9, |v8|, s10
	v_floor_f32_e32 v9, v9
	v_fma_f32 v13, v9, s11, |v8|
	v_cvt_u32_f32_e32 v13, v13
	v_cvt_u32_f32_e32 v9, v9
	v_ashrrev_i32_e32 v14, 31, v8
	v_or_b32_e32 v4, v188, v243
	v_xor_b32_e32 v8, v13, v14
	v_ashrrev_i32_e32 v5, 31, v4
	v_xor_b32_e32 v9, v9, v14
	v_sub_co_u32_e32 v8, vcc, v8, v14
	v_lshl_add_u64 v[4:5], v[4:5], 4, s[14:15]
	s_nop 0
	v_subb_co_u32_e32 v9, vcc, v9, v14, vcc
	global_atomic_add_x2 v[4:5], v[8:9], off
	v_mul_f32_e32 v8, 0x4b800000, v12
	v_rndne_f32_e32 v8, v8
	v_mul_f32_e64 v9, |v8|, s10
	v_floor_f32_e32 v9, v9
	v_fma_f32 v12, v9, s11, |v8|
	v_cvt_u32_f32_e32 v12, v12
	v_cvt_u32_f32_e32 v9, v9
	v_ashrrev_i32_e32 v13, 31, v8
	v_or_b32_e32 v6, v112, v243
	v_xor_b32_e32 v8, v12, v13
	v_xor_b32_e32 v9, v9, v13
	v_sub_co_u32_e32 v8, vcc, v8, v13
	v_ashrrev_i32_e32 v7, 31, v6
	s_nop 0
	v_subb_co_u32_e32 v9, vcc, v9, v13, vcc
	global_atomic_add_x2 v[4:5], v[8:9], off offset:8
	v_mul_f32_e32 v4, 0x4b800000, v11
	v_rndne_f32_e32 v4, v4
	v_mul_f32_e64 v5, |v4|, s10
	v_floor_f32_e32 v5, v5
	v_fma_f32 v8, v5, s11, |v4|
	v_cvt_u32_f32_e32 v8, v8
	v_cvt_u32_f32_e32 v5, v5
	v_ashrrev_i32_e32 v9, 31, v4
	v_lshl_add_u64 v[6:7], v[6:7], 4, s[14:15]
	v_xor_b32_e32 v4, v8, v9
	v_xor_b32_e32 v5, v5, v9
	v_sub_co_u32_e32 v4, vcc, v4, v9
	s_nop 1
	v_subb_co_u32_e32 v5, vcc, v5, v9, vcc
	global_atomic_add_x2 v[6:7], v[4:5], off
	v_mul_f32_e32 v4, 0x4b800000, v10
	v_rndne_f32_e32 v4, v4
	v_mul_f32_e64 v5, |v4|, s10
	v_floor_f32_e32 v5, v5
	v_fma_f32 v8, v5, s11, |v4|
	v_cvt_u32_f32_e32 v8, v8
	v_cvt_u32_f32_e32 v5, v5
	v_ashrrev_i32_e32 v9, 31, v4
	v_xor_b32_e32 v4, v8, v9
	v_xor_b32_e32 v5, v5, v9
	v_sub_co_u32_e32 v4, vcc, v4, v9
	s_nop 1
	v_subb_co_u32_e32 v5, vcc, v5, v9, vcc
	global_atomic_add_x2 v[6:7], v[4:5], off offset:8
	s_andn2_b64 vcc, exec, s[46:47]
	s_cbranch_vccnz .LBB0_786
	v_readlane_b32 s10, v251, 62
	v_readlane_b32 s11, v251, 63
	s_andn2_b64 vcc, exec, s[10:11]
	s_cbranch_vccnz .LBB0_785
	s_barrier
	s_branch .LBB0_785

.LBB0_873:
	v_lshl_or_b32 v132, s77, 8, v228
	v_ashrrev_i32_e32 v133, 31, v132
	v_lshlrev_b64 v[136:137], 2, v[132:133]
	v_lshl_add_u64 v[148:149], s[12:13], 0, v[136:137]
	v_lshl_add_u64 v[150:151], s[18:19], 0, v[136:137]
	global_load_dwordx4 v[132:135], v[148:149], off
	global_load_dwordx4 v[136:139], v[150:151], off
	global_load_dwordx4 v[140:143], v[148:149], off offset:16
	global_load_dwordx4 v[144:147], v[150:151], off offset:16
	global_load_dwordx4 v[166:169], v[148:149], off offset:512
	global_load_dwordx4 v[170:173], v[150:151], off offset:512
	global_load_dwordx4 v[184:187], v[148:149], off offset:528
	global_load_dwordx4 v[188:191], v[150:151], off offset:528
	v_lshl_add_u32 v174, s78, 8, v226
	v_ashrrev_i32_e32 v175, 31, v174
	v_lshl_add_u64 v[148:149], v[174:175], 4, s[14:15]
	global_load_dwordx4 v[210:213], v[148:149], off
	v_or_b32_e32 v224, 16, v174
	v_or_b32_e32 v222, 32, v174
	v_or_b32_e32 v220, 48, v174
	v_ashrrev_i32_e32 v225, 31, v224
	v_ashrrev_i32_e32 v223, 31, v222
	v_ashrrev_i32_e32 v221, 31, v220
	v_lshl_add_u64 v[148:149], v[224:225], 4, s[14:15]
	v_lshl_add_u64 v[150:151], v[222:223], 4, s[14:15]
	v_lshl_add_u64 v[176:177], v[220:221], 4, s[14:15]
	global_load_dwordx4 v[242:245], v[148:149], off
	global_load_dwordx4 v[152:155], v[150:151], off
	s_nop 0
	global_load_dwordx4 v[148:151], v[176:177], off
	v_add_u32_e32 v218, 0x80, v174
	s_brev_b32 s16, 44
	v_add_u32_e32 v216, 0x90, v174
	v_ashrrev_i32_e32 v219, 31, v218
	v_ashrrev_i32_e32 v217, 31, v216
	v_lshl_add_u64 v[178:179], v[218:219], 4, s[14:15]
	v_add_u32_e32 v214, 0xa0, v174
	v_add_u32_e32 v208, 0xb0, v174
	v_ashrrev_i32_e32 v215, 31, v214
	v_ashrrev_i32_e32 v209, 31, v208
	s_movk_i32 s27, 0x2c00
	s_andn2_b64 vcc, exec, s[38:39]
	s_mov_b64 s[28:29], -1
	s_and_b64 s[100:101], exec, s[22:23]
	s_cbranch_scc0 .Lalign_870
	s_barrier
.Lalign_870:
	s_waitcnt vmcnt(0)
	v_cvt_f32_i32_e32 v137, v137
	v_cvt_f32_i32_e32 v136, v136
	v_cvt_f32_i32_e32 v139, v139
	v_cvt_f32_i32_e32 v138, v138
	v_cvt_f32_i32_e32 v141, v141
	v_cvt_f32_i32_e32 v133, v133
	v_cvt_f32_i32_e32 v132, v132
	v_cvt_f32_i32_e32 v135, v135
	v_cvt_f32_i32_e32 v134, v134
	v_cvt_f32_i32_e32 v140, v140
	v_cvt_f32_i32_e32 v143, v143
	v_cvt_f32_i32_e32 v142, v142
	v_cvt_f32_i32_e32 v145, v145
	v_cvt_f32_i32_e32 v144, v144
	v_cvt_f32_i32_e32 v147, v147
	v_cvt_f32_i32_e32 v146, v146
	v_cvt_f32_i32_e32 v167, v167
	v_cvt_f32_i32_e32 v166, v166
	v_cvt_f32_i32_e32 v169, v169
	v_cvt_f32_i32_e32 v168, v168
	v_cvt_f32_i32_e32 v171, v171
	v_cvt_f32_i32_e32 v170, v170
	v_cvt_f32_i32_e32 v177, v173
	v_cvt_f32_i32_e32 v176, v172
	v_cvt_f32_i32_e32 v181, v185
	v_cvt_f32_i32_e32 v180, v184
	v_cvt_f32_i32_e32 v183, v187
	v_cvt_f32_i32_e32 v182, v186
	v_cvt_f32_i32_e32 v189, v189
	v_cvt_f32_i32_e32 v188, v188
	v_cvt_f32_i32_e32 v193, v191
	v_cvt_f32_i32_e32 v192, v190
	v_pk_mul_f32 v[186:187], v[134:135], s[16:17] op_sel_hi:[1,0]
	v_pk_mul_f32 v[194:195], v[132:133], s[16:17] op_sel_hi:[1,0]
	v_pk_mul_f32 v[132:133], v[138:139], s[16:17] op_sel_hi:[1,0]
	v_pk_mul_f32 v[134:135], v[136:137], s[16:17] op_sel_hi:[1,0]
	v_pk_mul_f32 v[172:173], v[142:143], s[16:17] op_sel_hi:[1,0]
	v_pk_mul_f32 v[190:191], v[140:141], s[16:17] op_sel_hi:[1,0]
	v_pk_mul_f32 v[136:137], v[146:147], s[16:17] op_sel_hi:[1,0]
	v_pk_mul_f32 v[138:139], v[144:145], s[16:17] op_sel_hi:[1,0]
	v_pk_mul_f32 v[168:169], v[168:169], s[16:17] op_sel_hi:[1,0]
	v_pk_mul_f32 v[184:185], v[166:167], s[16:17] op_sel_hi:[1,0]
	v_pk_mul_f32 v[140:141], v[176:177], s[16:17] op_sel_hi:[1,0]
	v_pk_mul_f32 v[142:143], v[170:171], s[16:17] op_sel_hi:[1,0]
	v_pk_mul_f32 v[166:167], v[182:183], s[16:17] op_sel_hi:[1,0]
	v_pk_mul_f32 v[170:171], v[180:181], s[16:17] op_sel_hi:[1,0]
	v_pk_mul_f32 v[144:145], v[192:193], s[16:17] op_sel_hi:[1,0]
	v_pk_mul_f32 v[146:147], v[188:189], s[16:17] op_sel_hi:[1,0]
	s_mov_b32 s16, 0xbfb8aa3b
	v_pk_mul_f32 v[204:205], v[134:135], s[16:17] op_sel_hi:[1,0]
	v_pk_mul_f32 v[206:207], v[132:133], s[16:17] op_sel_hi:[1,0]
	v_pk_mul_f32 v[200:201], v[138:139], s[16:17] op_sel_hi:[1,0]
	v_pk_mul_f32 v[202:203], v[136:137], s[16:17] op_sel_hi:[1,0]
	s_mov_b32 s16, 0xbf317218
	v_pk_mul_f32 v[196:197], v[142:143], s[16:17] op_sel_hi:[1,0]
	v_pk_mul_f32 v[198:199], v[140:141], s[16:17] op_sel_hi:[1,0]
	v_pk_mul_f32 v[188:189], v[146:147], s[16:17] op_sel_hi:[1,0]
	v_pk_mul_f32 v[192:193], v[144:145], s[16:17] op_sel_hi:[1,0]
	v_lshl_add_u64 v[132:133], v[216:217], 4, s[14:15]
	global_load_dwordx4 v[144:147], v[178:179], off
	global_load_dwordx4 v[140:143], v[132:133], off
	v_cvt_f32_i32_e32 v177, v211
	v_cvt_f32_i32_e32 v176, v213
	v_cvt_f32_u32_e32 v179, v210
	v_cvt_f32_u32_e32 v178, v212
	v_lshl_or_b32 v180, s77, 7, v228
	v_ashrrev_i32_e32 v181, 31, v180
	v_lshlrev_b64 v[212:213], 1, v[180:181]
	v_pk_fma_f32 v[176:177], v[176:177], s[30:31], v[178:179] op_sel_hi:[1,0,1]
	v_lshl_add_u64 v[132:133], v[214:215], 4, s[14:15]
	v_pk_mul_f32 v[176:177], v[176:177], s[90:91] op_sel_hi:[1,0]
	v_lshl_add_u64 v[134:135], v[208:209], 4, s[14:15]
	v_pk_mul_f32 v[176:177], v[176:177], s[92:93] op_sel_hi:[1,0]
	global_load_dwordx4 v[136:139], v[132:133], off
	s_nop 0
	global_load_dwordx4 v[132:135], v[134:135], off
	v_fma_f32 v175, -v177, v177, v176
	v_max_f32_e32 v175, 0, v175
	v_add_f32_e32 v175, 0x3727c5ac, v175
	v_rsq_f32_e32 v179, v175
	v_pk_fma_f32 v[128:129], v[194:195], v[176:177], v[128:129] op_sel:[0,1,0] neg_lo:[1,0,0] neg_hi:[1,0,0]
	v_pk_fma_f32 v[130:131], v[186:187], v[176:177], v[130:131] op_sel:[0,1,0] neg_lo:[1,0,0] neg_hi:[1,0,0]
	v_pk_fma_f32 v[124:125], v[190:191], v[176:177], v[124:125] op_sel:[0,1,0] neg_lo:[1,0,0] neg_hi:[1,0,0]
	v_mul_f32_e32 v178, 0xbfb8aa3b, v179
	v_pk_fma_f32 v[128:129], v[128:129], v[178:179], v[204:205] op_sel_hi:[1,0,1]
	v_pk_fma_f32 v[126:127], v[172:173], v[176:177], v[126:127] op_sel:[0,1,0] neg_lo:[1,0,0] neg_hi:[1,0,0]
	v_mul_f32_e32 v180, 0xbf317218, v179
	v_pk_fma_f32 v[130:131], v[130:131], v[178:179], v[206:207] op_sel_hi:[1,0,1]
	v_pk_fma_f32 v[126:127], v[126:127], v[178:179], v[202:203] op_sel_hi:[1,0,1]
	v_pk_fma_f32 v[124:125], v[124:125], v[178:179], v[200:201] op_sel_hi:[1,0,1]
	v_pk_fma_f32 v[116:117], v[170:171], v[176:177], v[116:117] op_sel:[0,1,0] neg_lo:[1,0,0] neg_hi:[1,0,0]
	v_pk_fma_f32 v[118:119], v[166:167], v[176:177], v[118:119] op_sel:[0,1,0] neg_lo:[1,0,0] neg_hi:[1,0,0]
	v_exp_f32_e32 v178, v128
	v_pk_fma_f32 v[120:121], v[184:185], v[176:177], v[120:121] op_sel:[0,1,0] neg_lo:[1,0,0] neg_hi:[1,0,0]
	v_pk_fma_f32 v[122:123], v[168:169], v[176:177], v[122:123] op_sel:[0,1,0] neg_lo:[1,0,0] neg_hi:[1,0,0]
	v_pk_fma_f32 v[176:177], v[118:119], v[180:181], v[192:193] op_sel_hi:[1,0,1]
	v_pk_fma_f32 v[118:119], v[116:117], v[180:181], v[188:189] op_sel_hi:[1,0,1]
	v_exp_f32_e32 v116, v129
	v_add_f32_e32 v117, 1.0, v178
	v_rcp_f32_e32 v117, v117
	v_pk_fma_f32 v[120:121], v[120:121], v[180:181], v[196:197] op_sel_hi:[1,0,1]
	v_add_f32_e32 v116, 1.0, v116
	v_rcp_f32_e32 v116, v116
	v_mul_f32_e32 v120, v128, v120
	v_mul_f32_e32 v117, v120, v117
	v_mul_f32_e32 v120, v129, v121
	v_exp_f32_e32 v121, v130
	v_mul_f32_e32 v116, v120, v116
	v_exp_f32_e32 v120, v131
	v_cvt_pk_bf16_f32 v116, v117, v116
	v_add_f32_e32 v117, 1.0, v121
	v_rcp_f32_e32 v117, v117
	v_add_f32_e32 v120, 1.0, v120
	v_rcp_f32_e32 v120, v120
	v_pk_fma_f32 v[122:123], v[122:123], v[180:181], v[198:199] op_sel_hi:[1,0,1]
	v_mul_f32_e32 v118, v124, v118
	v_mul_f32_e32 v121, v130, v122
	v_mul_f32_e32 v117, v121, v117
	v_mul_f32_e32 v121, v131, v123
	v_mul_f32_e32 v120, v121, v120
	v_exp_f32_e32 v121, v124
	v_cvt_pk_bf16_f32 v117, v117, v120
	v_exp_f32_e32 v120, v125
	v_exp_f32_e32 v122, v126
	v_add_f32_e32 v121, 1.0, v121
	v_rcp_f32_e32 v121, v121
	v_add_f32_e32 v120, 1.0, v120
	v_rcp_f32_e32 v120, v120
	v_mul_f32_e32 v119, v125, v119
	v_mul_f32_e32 v118, v118, v121
	v_mul_f32_e32 v121, v126, v176
	v_mul_f32_e32 v119, v119, v120
	v_cvt_pk_bf16_f32 v118, v118, v119
	v_exp_f32_e32 v119, v127
	v_add_f32_e32 v120, 1.0, v122
	v_rcp_f32_e32 v120, v120
	v_cvt_f32_u32_e32 v123, v242
	v_add_f32_e32 v119, 1.0, v119
	v_rcp_f32_e32 v119, v119
	v_mul_f32_e32 v124, v121, v120
	v_cvt_f32_i32_e32 v121, v243
	v_cvt_f32_i32_e32 v120, v245
	v_cvt_f32_u32_e32 v122, v244
	v_mov_b64_e32 v[210:211], s[70:71]
	v_mad_i64_i32 v[174:175], s[16:17], v174, s27, v[210:211]
	v_mul_f32_e32 v125, v127, v177
	v_lshl_add_u64 v[174:175], v[174:175], 0, v[212:213]
	v_mul_f32_e32 v119, v125, v119
	v_cvt_pk_bf16_f32 v119, v124, v119
	global_store_dwordx4 v[174:175], v[116:119], off
	s_nop 1
	v_pk_fma_f32 v[116:117], v[120:121], s[30:31], v[122:123] op_sel_hi:[1,0,1]
	s_nop 0
	v_pk_mul_f32 v[116:117], v[116:117], s[90:91] op_sel_hi:[1,0]
	s_nop 0
	v_pk_mul_f32 v[116:117], v[116:117], s[92:93] op_sel_hi:[1,0]
	s_nop 0
	v_fma_f32 v118, -v117, v117, v116
	v_max_f32_e32 v118, 0, v118
	v_add_f32_e32 v118, 0x3727c5ac, v118
	v_rsq_f32_e32 v121, v118
	v_pk_fma_f32 v[112:113], v[194:195], v[116:117], v[112:113] op_sel:[0,1,0] neg_lo:[1,0,0] neg_hi:[1,0,0]
	v_pk_fma_f32 v[114:115], v[186:187], v[116:117], v[114:115] op_sel:[0,1,0] neg_lo:[1,0,0] neg_hi:[1,0,0]
	v_pk_fma_f32 v[108:109], v[190:191], v[116:117], v[108:109] op_sel:[0,1,0] neg_lo:[1,0,0] neg_hi:[1,0,0]
	v_mul_f32_e32 v120, 0xbfb8aa3b, v121
	v_pk_fma_f32 v[112:113], v[112:113], v[120:121], v[204:205] op_sel_hi:[1,0,1]
	v_pk_fma_f32 v[110:111], v[172:173], v[116:117], v[110:111] op_sel:[0,1,0] neg_lo:[1,0,0] neg_hi:[1,0,0]
	v_mul_f32_e32 v122, 0xbf317218, v121
	v_pk_fma_f32 v[114:115], v[114:115], v[120:121], v[206:207] op_sel_hi:[1,0,1]
	v_pk_fma_f32 v[110:111], v[110:111], v[120:121], v[202:203] op_sel_hi:[1,0,1]
	v_pk_fma_f32 v[108:109], v[108:109], v[120:121], v[200:201] op_sel_hi:[1,0,1]
	v_pk_fma_f32 v[100:101], v[170:171], v[116:117], v[100:101] op_sel:[0,1,0] neg_lo:[1,0,0] neg_hi:[1,0,0]
	v_pk_fma_f32 v[102:103], v[166:167], v[116:117], v[102:103] op_sel:[0,1,0] neg_lo:[1,0,0] neg_hi:[1,0,0]
	v_exp_f32_e32 v120, v112
	v_pk_fma_f32 v[104:105], v[184:185], v[116:117], v[104:105] op_sel:[0,1,0] neg_lo:[1,0,0] neg_hi:[1,0,0]
	v_pk_fma_f32 v[106:107], v[168:169], v[116:117], v[106:107] op_sel:[0,1,0] neg_lo:[1,0,0] neg_hi:[1,0,0]
	v_pk_fma_f32 v[116:117], v[102:103], v[122:123], v[192:193] op_sel_hi:[1,0,1]
	v_pk_fma_f32 v[102:103], v[100:101], v[122:123], v[188:189] op_sel_hi:[1,0,1]
	v_exp_f32_e32 v100, v113
	v_add_f32_e32 v101, 1.0, v120
	v_rcp_f32_e32 v101, v101
	v_pk_fma_f32 v[104:105], v[104:105], v[122:123], v[196:197] op_sel_hi:[1,0,1]
	v_add_f32_e32 v100, 1.0, v100
	v_rcp_f32_e32 v100, v100
	v_mul_f32_e32 v104, v112, v104
	v_mul_f32_e32 v101, v104, v101
	v_mul_f32_e32 v104, v113, v105
	v_exp_f32_e32 v105, v114
	v_mul_f32_e32 v100, v104, v100
	v_exp_f32_e32 v104, v115
	v_cvt_pk_bf16_f32 v100, v101, v100
	v_add_f32_e32 v101, 1.0, v105
	v_rcp_f32_e32 v101, v101
	v_add_f32_e32 v104, 1.0, v104
	v_rcp_f32_e32 v104, v104
	v_pk_fma_f32 v[106:107], v[106:107], v[122:123], v[198:199] op_sel_hi:[1,0,1]
	v_mul_f32_e32 v102, v108, v102
	v_mul_f32_e32 v105, v114, v106
	v_mul_f32_e32 v101, v105, v101
	v_mul_f32_e32 v105, v115, v107
	v_mul_f32_e32 v104, v105, v104
	v_exp_f32_e32 v105, v108
	v_cvt_pk_bf16_f32 v101, v101, v104
	v_exp_f32_e32 v104, v109
	v_exp_f32_e32 v106, v110
	v_add_f32_e32 v105, 1.0, v105
	v_rcp_f32_e32 v105, v105
	v_add_f32_e32 v104, 1.0, v104
	v_rcp_f32_e32 v104, v104
	v_mul_f32_e32 v103, v109, v103
	v_mul_f32_e32 v102, v102, v105
	v_mul_f32_e32 v105, v110, v116
	v_mul_f32_e32 v103, v103, v104
	v_cvt_pk_bf16_f32 v102, v102, v103
	v_exp_f32_e32 v103, v111
	v_add_f32_e32 v104, 1.0, v106
	v_rcp_f32_e32 v104, v104
	v_cvt_f32_u32_e32 v107, v152
	v_add_f32_e32 v103, 1.0, v103
	v_rcp_f32_e32 v103, v103
	v_mul_f32_e32 v108, v105, v104
	v_cvt_f32_i32_e32 v105, v153
	v_cvt_f32_i32_e32 v104, v155
	v_cvt_f32_u32_e32 v106, v154
	v_mad_i64_i32 v[118:119], s[16:17], v224, s27, v[210:211]
	v_mul_f32_e32 v109, v111, v117
	v_lshl_add_u64 v[118:119], v[118:119], 0, v[212:213]
	v_mul_f32_e32 v103, v109, v103
	v_cvt_pk_bf16_f32 v103, v108, v103
	global_store_dwordx4 v[118:119], v[100:103], off
	s_nop 1
	v_pk_fma_f32 v[100:101], v[104:105], s[30:31], v[106:107] op_sel_hi:[1,0,1]
	s_nop 0
	v_pk_mul_f32 v[100:101], v[100:101], s[90:91] op_sel_hi:[1,0]
	s_nop 0
	v_pk_mul_f32 v[100:101], v[100:101], s[92:93] op_sel_hi:[1,0]
	s_nop 0
	v_fma_f32 v102, -v101, v101, v100
	v_max_f32_e32 v102, 0, v102
	v_add_f32_e32 v102, 0x3727c5ac, v102
	v_rsq_f32_e32 v105, v102
	v_pk_fma_f32 v[96:97], v[194:195], v[100:101], v[96:97] op_sel:[0,1,0] neg_lo:[1,0,0] neg_hi:[1,0,0]
	v_pk_fma_f32 v[98:99], v[186:187], v[100:101], v[98:99] op_sel:[0,1,0] neg_lo:[1,0,0] neg_hi:[1,0,0]
	v_pk_fma_f32 v[92:93], v[190:191], v[100:101], v[92:93] op_sel:[0,1,0] neg_lo:[1,0,0] neg_hi:[1,0,0]
	v_mul_f32_e32 v104, 0xbfb8aa3b, v105
	v_pk_fma_f32 v[96:97], v[96:97], v[104:105], v[204:205] op_sel_hi:[1,0,1]
	v_pk_fma_f32 v[94:95], v[172:173], v[100:101], v[94:95] op_sel:[0,1,0] neg_lo:[1,0,0] neg_hi:[1,0,0]
	v_mul_f32_e32 v106, 0xbf317218, v105
	v_pk_fma_f32 v[98:99], v[98:99], v[104:105], v[206:207] op_sel_hi:[1,0,1]
	v_pk_fma_f32 v[94:95], v[94:95], v[104:105], v[202:203] op_sel_hi:[1,0,1]
	v_pk_fma_f32 v[92:93], v[92:93], v[104:105], v[200:201] op_sel_hi:[1,0,1]
	v_pk_fma_f32 v[84:85], v[170:171], v[100:101], v[84:85] op_sel:[0,1,0] neg_lo:[1,0,0] neg_hi:[1,0,0]
	v_pk_fma_f32 v[86:87], v[166:167], v[100:101], v[86:87] op_sel:[0,1,0] neg_lo:[1,0,0] neg_hi:[1,0,0]
	v_exp_f32_e32 v104, v96
	v_pk_fma_f32 v[88:89], v[184:185], v[100:101], v[88:89] op_sel:[0,1,0] neg_lo:[1,0,0] neg_hi:[1,0,0]
	v_pk_fma_f32 v[90:91], v[168:169], v[100:101], v[90:91] op_sel:[0,1,0] neg_lo:[1,0,0] neg_hi:[1,0,0]
	v_pk_fma_f32 v[100:101], v[86:87], v[106:107], v[192:193] op_sel_hi:[1,0,1]
	v_pk_fma_f32 v[86:87], v[84:85], v[106:107], v[188:189] op_sel_hi:[1,0,1]
	v_exp_f32_e32 v84, v97
	v_add_f32_e32 v85, 1.0, v104
	v_rcp_f32_e32 v85, v85
	v_pk_fma_f32 v[88:89], v[88:89], v[106:107], v[196:197] op_sel_hi:[1,0,1]
	v_add_f32_e32 v84, 1.0, v84
	v_rcp_f32_e32 v84, v84
	v_mul_f32_e32 v88, v96, v88
	v_mul_f32_e32 v85, v88, v85
	v_mul_f32_e32 v88, v97, v89
	v_exp_f32_e32 v89, v98
	v_mul_f32_e32 v84, v88, v84
	v_exp_f32_e32 v88, v99
	v_cvt_pk_bf16_f32 v84, v85, v84
	v_add_f32_e32 v85, 1.0, v89
	v_rcp_f32_e32 v85, v85
	v_add_f32_e32 v88, 1.0, v88
	v_rcp_f32_e32 v88, v88
	v_pk_fma_f32 v[90:91], v[90:91], v[106:107], v[198:199] op_sel_hi:[1,0,1]
	v_mul_f32_e32 v86, v92, v86
	v_mul_f32_e32 v89, v98, v90
	v_mul_f32_e32 v85, v89, v85
	v_mul_f32_e32 v89, v99, v91
	v_mul_f32_e32 v88, v89, v88
	v_exp_f32_e32 v89, v92
	v_cvt_pk_bf16_f32 v85, v85, v88
	v_exp_f32_e32 v88, v93
	v_exp_f32_e32 v90, v94
	v_add_f32_e32 v89, 1.0, v89
	v_rcp_f32_e32 v89, v89
	v_add_f32_e32 v88, 1.0, v88
	v_rcp_f32_e32 v88, v88
	v_mul_f32_e32 v87, v93, v87
	v_mul_f32_e32 v86, v86, v89
	v_mul_f32_e32 v89, v94, v100
	v_mul_f32_e32 v87, v87, v88
	v_cvt_pk_bf16_f32 v86, v86, v87
	v_exp_f32_e32 v87, v95
	v_add_f32_e32 v88, 1.0, v90
	v_rcp_f32_e32 v88, v88
	v_cvt_f32_u32_e32 v91, v148
	v_add_f32_e32 v87, 1.0, v87
	v_rcp_f32_e32 v87, v87
	v_mul_f32_e32 v92, v89, v88
	v_cvt_f32_i32_e32 v89, v149
	v_cvt_f32_i32_e32 v88, v151
	v_cvt_f32_u32_e32 v90, v150
	v_mad_i64_i32 v[102:103], s[16:17], v222, s27, v[210:211]
	v_mul_f32_e32 v93, v95, v101
	v_lshl_add_u64 v[102:103], v[102:103], 0, v[212:213]
	v_mul_f32_e32 v87, v93, v87
	v_cvt_pk_bf16_f32 v87, v92, v87
	global_store_dwordx4 v[102:103], v[84:87], off
	s_nop 1
	v_pk_fma_f32 v[84:85], v[88:89], s[30:31], v[90:91] op_sel_hi:[1,0,1]
	s_nop 0
	v_pk_mul_f32 v[84:85], v[84:85], s[90:91] op_sel_hi:[1,0]
	s_nop 0
	v_pk_mul_f32 v[84:85], v[84:85], s[92:93] op_sel_hi:[1,0]
	s_nop 0
	v_fma_f32 v86, -v85, v85, v84
	v_max_f32_e32 v86, 0, v86
	v_add_f32_e32 v86, 0x3727c5ac, v86
	v_rsq_f32_e32 v89, v86
	v_pk_fma_f32 v[80:81], v[194:195], v[84:85], v[80:81] op_sel:[0,1,0] neg_lo:[1,0,0] neg_hi:[1,0,0]
	v_pk_fma_f32 v[82:83], v[186:187], v[84:85], v[82:83] op_sel:[0,1,0] neg_lo:[1,0,0] neg_hi:[1,0,0]
	v_pk_fma_f32 v[76:77], v[190:191], v[84:85], v[76:77] op_sel:[0,1,0] neg_lo:[1,0,0] neg_hi:[1,0,0]
	v_mul_f32_e32 v88, 0xbfb8aa3b, v89
	v_pk_fma_f32 v[80:81], v[80:81], v[88:89], v[204:205] op_sel_hi:[1,0,1]
	v_pk_fma_f32 v[78:79], v[172:173], v[84:85], v[78:79] op_sel:[0,1,0] neg_lo:[1,0,0] neg_hi:[1,0,0]
	v_mul_f32_e32 v90, 0xbf317218, v89
	v_pk_fma_f32 v[82:83], v[82:83], v[88:89], v[206:207] op_sel_hi:[1,0,1]
	v_pk_fma_f32 v[78:79], v[78:79], v[88:89], v[202:203] op_sel_hi:[1,0,1]
	v_pk_fma_f32 v[76:77], v[76:77], v[88:89], v[200:201] op_sel_hi:[1,0,1]
	v_pk_fma_f32 v[68:69], v[170:171], v[84:85], v[68:69] op_sel:[0,1,0] neg_lo:[1,0,0] neg_hi:[1,0,0]
	v_pk_fma_f32 v[70:71], v[166:167], v[84:85], v[70:71] op_sel:[0,1,0] neg_lo:[1,0,0] neg_hi:[1,0,0]
	v_exp_f32_e32 v88, v80
	v_pk_fma_f32 v[72:73], v[184:185], v[84:85], v[72:73] op_sel:[0,1,0] neg_lo:[1,0,0] neg_hi:[1,0,0]
	v_pk_fma_f32 v[74:75], v[168:169], v[84:85], v[74:75] op_sel:[0,1,0] neg_lo:[1,0,0] neg_hi:[1,0,0]
	v_pk_fma_f32 v[84:85], v[70:71], v[90:91], v[192:193] op_sel_hi:[1,0,1]
	v_pk_fma_f32 v[70:71], v[68:69], v[90:91], v[188:189] op_sel_hi:[1,0,1]
	v_exp_f32_e32 v68, v81
	v_add_f32_e32 v69, 1.0, v88
	v_rcp_f32_e32 v69, v69
	v_pk_fma_f32 v[72:73], v[72:73], v[90:91], v[196:197] op_sel_hi:[1,0,1]
	v_add_f32_e32 v68, 1.0, v68
	v_rcp_f32_e32 v68, v68
	v_mul_f32_e32 v72, v80, v72
	v_mul_f32_e32 v69, v72, v69
	v_mul_f32_e32 v72, v81, v73
	v_exp_f32_e32 v73, v82
	v_mul_f32_e32 v68, v72, v68
	v_exp_f32_e32 v72, v83
	v_cvt_pk_bf16_f32 v68, v69, v68
	v_add_f32_e32 v69, 1.0, v73
	v_rcp_f32_e32 v69, v69
	v_add_f32_e32 v72, 1.0, v72
	v_rcp_f32_e32 v72, v72
	v_pk_fma_f32 v[74:75], v[74:75], v[90:91], v[198:199] op_sel_hi:[1,0,1]
	v_mul_f32_e32 v70, v76, v70
	v_mul_f32_e32 v73, v82, v74
	v_mul_f32_e32 v69, v73, v69
	v_mul_f32_e32 v73, v83, v75
	v_mul_f32_e32 v72, v73, v72
	v_exp_f32_e32 v73, v76
	v_cvt_pk_bf16_f32 v69, v69, v72
	v_exp_f32_e32 v72, v77
	v_exp_f32_e32 v74, v78
	v_add_f32_e32 v73, 1.0, v73
	v_rcp_f32_e32 v73, v73
	v_add_f32_e32 v72, 1.0, v72
	v_rcp_f32_e32 v72, v72
	v_mul_f32_e32 v71, v77, v71
	v_mul_f32_e32 v70, v70, v73
	v_mul_f32_e32 v73, v78, v84
	v_mul_f32_e32 v71, v71, v72
	v_cvt_pk_bf16_f32 v70, v70, v71
	v_exp_f32_e32 v71, v79
	v_add_f32_e32 v72, 1.0, v74
	v_rcp_f32_e32 v72, v72
	s_waitcnt vmcnt(6)
	v_cvt_f32_u32_e32 v75, v144
	v_add_f32_e32 v71, 1.0, v71
	v_rcp_f32_e32 v71, v71
	v_mul_f32_e32 v76, v73, v72
	v_cvt_f32_i32_e32 v73, v145
	v_cvt_f32_i32_e32 v72, v147
	v_cvt_f32_u32_e32 v74, v146
	v_mad_i64_i32 v[86:87], s[16:17], v220, s27, v[210:211]
	v_mul_f32_e32 v77, v79, v85
	v_lshl_add_u64 v[86:87], v[86:87], 0, v[212:213]
	v_mul_f32_e32 v71, v77, v71
	v_cvt_pk_bf16_f32 v71, v76, v71
	global_store_dwordx4 v[86:87], v[68:71], off
	s_nop 1
	v_pk_fma_f32 v[68:69], v[72:73], s[30:31], v[74:75] op_sel_hi:[1,0,1]
	s_nop 0
	v_pk_mul_f32 v[68:69], v[68:69], s[90:91] op_sel_hi:[1,0]
	s_nop 0
	v_pk_mul_f32 v[68:69], v[68:69], s[92:93] op_sel_hi:[1,0]
	s_nop 0
	v_fma_f32 v70, -v69, v69, v68
	v_max_f32_e32 v70, 0, v70
	v_add_f32_e32 v70, 0x3727c5ac, v70
	v_rsq_f32_e32 v73, v70
	v_pk_fma_f32 v[64:65], v[194:195], v[68:69], v[64:65] op_sel:[0,1,0] neg_lo:[1,0,0] neg_hi:[1,0,0]
	v_pk_fma_f32 v[66:67], v[186:187], v[68:69], v[66:67] op_sel:[0,1,0] neg_lo:[1,0,0] neg_hi:[1,0,0]
	v_pk_fma_f32 v[60:61], v[190:191], v[68:69], v[60:61] op_sel:[0,1,0] neg_lo:[1,0,0] neg_hi:[1,0,0]
	v_mul_f32_e32 v72, 0xbfb8aa3b, v73
	v_pk_fma_f32 v[64:65], v[64:65], v[72:73], v[204:205] op_sel_hi:[1,0,1]
	v_pk_fma_f32 v[62:63], v[172:173], v[68:69], v[62:63] op_sel:[0,1,0] neg_lo:[1,0,0] neg_hi:[1,0,0]
	v_mul_f32_e32 v74, 0xbf317218, v73
	v_pk_fma_f32 v[66:67], v[66:67], v[72:73], v[206:207] op_sel_hi:[1,0,1]
	v_pk_fma_f32 v[62:63], v[62:63], v[72:73], v[202:203] op_sel_hi:[1,0,1]
	v_pk_fma_f32 v[60:61], v[60:61], v[72:73], v[200:201] op_sel_hi:[1,0,1]
	v_pk_fma_f32 v[52:53], v[170:171], v[68:69], v[52:53] op_sel:[0,1,0] neg_lo:[1,0,0] neg_hi:[1,0,0]
	v_pk_fma_f32 v[54:55], v[166:167], v[68:69], v[54:55] op_sel:[0,1,0] neg_lo:[1,0,0] neg_hi:[1,0,0]
	v_exp_f32_e32 v72, v64
	v_pk_fma_f32 v[56:57], v[184:185], v[68:69], v[56:57] op_sel:[0,1,0] neg_lo:[1,0,0] neg_hi:[1,0,0]
	v_pk_fma_f32 v[58:59], v[168:169], v[68:69], v[58:59] op_sel:[0,1,0] neg_lo:[1,0,0] neg_hi:[1,0,0]
	v_pk_fma_f32 v[68:69], v[54:55], v[74:75], v[192:193] op_sel_hi:[1,0,1]
	v_pk_fma_f32 v[54:55], v[52:53], v[74:75], v[188:189] op_sel_hi:[1,0,1]
	v_exp_f32_e32 v52, v65
	v_add_f32_e32 v53, 1.0, v72
	v_rcp_f32_e32 v53, v53
	v_pk_fma_f32 v[56:57], v[56:57], v[74:75], v[196:197] op_sel_hi:[1,0,1]
	v_add_f32_e32 v52, 1.0, v52
	v_rcp_f32_e32 v52, v52
	v_mul_f32_e32 v56, v64, v56
	v_mul_f32_e32 v53, v56, v53
	v_mul_f32_e32 v56, v65, v57
	v_exp_f32_e32 v57, v66
	v_mul_f32_e32 v52, v56, v52
	v_exp_f32_e32 v56, v67
	v_cvt_pk_bf16_f32 v52, v53, v52
	v_add_f32_e32 v53, 1.0, v57
	v_rcp_f32_e32 v53, v53
	v_add_f32_e32 v56, 1.0, v56
	v_rcp_f32_e32 v56, v56
	v_pk_fma_f32 v[58:59], v[58:59], v[74:75], v[198:199] op_sel_hi:[1,0,1]
	v_mul_f32_e32 v54, v60, v54
	v_mul_f32_e32 v57, v66, v58
	v_mul_f32_e32 v53, v57, v53
	v_mul_f32_e32 v57, v67, v59
	v_mul_f32_e32 v56, v57, v56
	v_exp_f32_e32 v57, v60
	v_cvt_pk_bf16_f32 v53, v53, v56
	v_exp_f32_e32 v56, v61
	v_exp_f32_e32 v58, v62
	v_add_f32_e32 v57, 1.0, v57
	v_rcp_f32_e32 v57, v57
	v_add_f32_e32 v56, 1.0, v56
	v_rcp_f32_e32 v56, v56
	v_mul_f32_e32 v55, v61, v55
	v_mul_f32_e32 v54, v54, v57
	v_mul_f32_e32 v57, v62, v68
	v_mul_f32_e32 v55, v55, v56
	v_cvt_pk_bf16_f32 v54, v54, v55
	v_exp_f32_e32 v55, v63
	v_add_f32_e32 v56, 1.0, v58
	v_rcp_f32_e32 v56, v56
	s_waitcnt vmcnt(6)
	v_cvt_f32_u32_e32 v59, v140
	v_add_f32_e32 v55, 1.0, v55
	v_rcp_f32_e32 v55, v55
	v_mul_f32_e32 v60, v57, v56
	v_cvt_f32_i32_e32 v57, v141
	v_cvt_f32_i32_e32 v56, v143
	v_cvt_f32_u32_e32 v58, v142
	v_mad_i64_i32 v[70:71], s[16:17], v218, s27, v[210:211]
	v_mul_f32_e32 v61, v63, v69
	v_lshl_add_u64 v[70:71], v[70:71], 0, v[212:213]
	v_mul_f32_e32 v55, v61, v55
	v_cvt_pk_bf16_f32 v55, v60, v55
	global_store_dwordx4 v[70:71], v[52:55], off
	s_nop 1
	v_pk_fma_f32 v[52:53], v[56:57], s[30:31], v[58:59] op_sel_hi:[1,0,1]
	s_nop 0
	v_pk_mul_f32 v[52:53], v[52:53], s[90:91] op_sel_hi:[1,0]
	s_nop 0
	v_pk_mul_f32 v[52:53], v[52:53], s[92:93] op_sel_hi:[1,0]
	s_nop 0
	v_fma_f32 v54, -v53, v53, v52
	v_max_f32_e32 v54, 0, v54
	v_add_f32_e32 v54, 0x3727c5ac, v54
	v_rsq_f32_e32 v57, v54
	v_pk_fma_f32 v[48:49], v[194:195], v[52:53], v[48:49] op_sel:[0,1,0] neg_lo:[1,0,0] neg_hi:[1,0,0]
	v_pk_fma_f32 v[50:51], v[186:187], v[52:53], v[50:51] op_sel:[0,1,0] neg_lo:[1,0,0] neg_hi:[1,0,0]
	v_pk_fma_f32 v[44:45], v[190:191], v[52:53], v[44:45] op_sel:[0,1,0] neg_lo:[1,0,0] neg_hi:[1,0,0]
	v_mul_f32_e32 v56, 0xbfb8aa3b, v57
	v_pk_fma_f32 v[48:49], v[48:49], v[56:57], v[204:205] op_sel_hi:[1,0,1]
	v_pk_fma_f32 v[46:47], v[172:173], v[52:53], v[46:47] op_sel:[0,1,0] neg_lo:[1,0,0] neg_hi:[1,0,0]
	v_mul_f32_e32 v58, 0xbf317218, v57
	v_pk_fma_f32 v[50:51], v[50:51], v[56:57], v[206:207] op_sel_hi:[1,0,1]
	v_pk_fma_f32 v[46:47], v[46:47], v[56:57], v[202:203] op_sel_hi:[1,0,1]
	v_pk_fma_f32 v[44:45], v[44:45], v[56:57], v[200:201] op_sel_hi:[1,0,1]
	v_pk_fma_f32 v[36:37], v[170:171], v[52:53], v[36:37] op_sel:[0,1,0] neg_lo:[1,0,0] neg_hi:[1,0,0]
	v_pk_fma_f32 v[38:39], v[166:167], v[52:53], v[38:39] op_sel:[0,1,0] neg_lo:[1,0,0] neg_hi:[1,0,0]
	v_exp_f32_e32 v56, v48
	v_pk_fma_f32 v[40:41], v[184:185], v[52:53], v[40:41] op_sel:[0,1,0] neg_lo:[1,0,0] neg_hi:[1,0,0]
	v_pk_fma_f32 v[42:43], v[168:169], v[52:53], v[42:43] op_sel:[0,1,0] neg_lo:[1,0,0] neg_hi:[1,0,0]
	v_pk_fma_f32 v[52:53], v[38:39], v[58:59], v[192:193] op_sel_hi:[1,0,1]
	v_pk_fma_f32 v[38:39], v[36:37], v[58:59], v[188:189] op_sel_hi:[1,0,1]
	v_exp_f32_e32 v36, v49
	v_add_f32_e32 v37, 1.0, v56
	v_rcp_f32_e32 v37, v37
	v_pk_fma_f32 v[40:41], v[40:41], v[58:59], v[196:197] op_sel_hi:[1,0,1]
	v_add_f32_e32 v36, 1.0, v36
	v_rcp_f32_e32 v36, v36
	v_mul_f32_e32 v40, v48, v40
	v_mul_f32_e32 v37, v40, v37
	v_mul_f32_e32 v40, v49, v41
	v_exp_f32_e32 v41, v50
	v_mul_f32_e32 v36, v40, v36
	v_exp_f32_e32 v40, v51
	v_cvt_pk_bf16_f32 v36, v37, v36
	v_add_f32_e32 v37, 1.0, v41
	v_rcp_f32_e32 v37, v37
	v_add_f32_e32 v40, 1.0, v40
	v_rcp_f32_e32 v40, v40
	v_pk_fma_f32 v[42:43], v[42:43], v[58:59], v[198:199] op_sel_hi:[1,0,1]
	v_mul_f32_e32 v38, v44, v38
	v_mul_f32_e32 v41, v50, v42
	v_mul_f32_e32 v37, v41, v37
	v_mul_f32_e32 v41, v51, v43
	v_mul_f32_e32 v40, v41, v40
	v_exp_f32_e32 v41, v44
	v_cvt_pk_bf16_f32 v37, v37, v40
	v_exp_f32_e32 v40, v45
	v_exp_f32_e32 v42, v46
	v_add_f32_e32 v41, 1.0, v41
	v_rcp_f32_e32 v41, v41
	v_add_f32_e32 v40, 1.0, v40
	v_rcp_f32_e32 v40, v40
	v_mul_f32_e32 v39, v45, v39
	v_mul_f32_e32 v38, v38, v41
	v_mul_f32_e32 v41, v46, v52
	v_mul_f32_e32 v39, v39, v40
	v_cvt_pk_bf16_f32 v38, v38, v39
	v_exp_f32_e32 v39, v47
	v_add_f32_e32 v40, 1.0, v42
	v_rcp_f32_e32 v40, v40
	s_waitcnt vmcnt(6)
	v_cvt_f32_u32_e32 v43, v136
	v_add_f32_e32 v39, 1.0, v39
	v_rcp_f32_e32 v39, v39
	v_mul_f32_e32 v44, v41, v40
	v_cvt_f32_i32_e32 v41, v137
	v_cvt_f32_i32_e32 v40, v139
	v_cvt_f32_u32_e32 v42, v138
	v_mad_i64_i32 v[54:55], s[16:17], v216, s27, v[210:211]
	v_mul_f32_e32 v45, v47, v53
	v_lshl_add_u64 v[54:55], v[54:55], 0, v[212:213]
	v_mul_f32_e32 v39, v45, v39
	v_cvt_pk_bf16_f32 v39, v44, v39
	global_store_dwordx4 v[54:55], v[36:39], off
	s_nop 1
	v_pk_fma_f32 v[36:37], v[40:41], s[30:31], v[42:43] op_sel_hi:[1,0,1]
	s_nop 0
	v_pk_mul_f32 v[36:37], v[36:37], s[90:91] op_sel_hi:[1,0]
	s_nop 0
	v_pk_mul_f32 v[36:37], v[36:37], s[92:93] op_sel_hi:[1,0]
	s_nop 0
	v_fma_f32 v38, -v37, v37, v36
	v_max_f32_e32 v38, 0, v38
	v_add_f32_e32 v38, 0x3727c5ac, v38
	v_rsq_f32_e32 v41, v38
	v_pk_fma_f32 v[32:33], v[194:195], v[36:37], v[32:33] op_sel:[0,1,0] neg_lo:[1,0,0] neg_hi:[1,0,0]
	v_pk_fma_f32 v[34:35], v[186:187], v[36:37], v[34:35] op_sel:[0,1,0] neg_lo:[1,0,0] neg_hi:[1,0,0]
	v_pk_fma_f32 v[28:29], v[190:191], v[36:37], v[28:29] op_sel:[0,1,0] neg_lo:[1,0,0] neg_hi:[1,0,0]
	v_mul_f32_e32 v40, 0xbfb8aa3b, v41
	v_pk_fma_f32 v[32:33], v[32:33], v[40:41], v[204:205] op_sel_hi:[1,0,1]
	v_pk_fma_f32 v[30:31], v[172:173], v[36:37], v[30:31] op_sel:[0,1,0] neg_lo:[1,0,0] neg_hi:[1,0,0]
	v_mul_f32_e32 v42, 0xbf317218, v41
	v_pk_fma_f32 v[34:35], v[34:35], v[40:41], v[206:207] op_sel_hi:[1,0,1]
	v_pk_fma_f32 v[30:31], v[30:31], v[40:41], v[202:203] op_sel_hi:[1,0,1]
	v_pk_fma_f32 v[28:29], v[28:29], v[40:41], v[200:201] op_sel_hi:[1,0,1]
	v_pk_fma_f32 v[20:21], v[170:171], v[36:37], v[20:21] op_sel:[0,1,0] neg_lo:[1,0,0] neg_hi:[1,0,0]
	v_pk_fma_f32 v[22:23], v[166:167], v[36:37], v[22:23] op_sel:[0,1,0] neg_lo:[1,0,0] neg_hi:[1,0,0]
	v_exp_f32_e32 v40, v32
	v_pk_fma_f32 v[24:25], v[184:185], v[36:37], v[24:25] op_sel:[0,1,0] neg_lo:[1,0,0] neg_hi:[1,0,0]
	v_pk_fma_f32 v[26:27], v[168:169], v[36:37], v[26:27] op_sel:[0,1,0] neg_lo:[1,0,0] neg_hi:[1,0,0]
	v_pk_fma_f32 v[36:37], v[22:23], v[42:43], v[192:193] op_sel_hi:[1,0,1]
	v_pk_fma_f32 v[22:23], v[20:21], v[42:43], v[188:189] op_sel_hi:[1,0,1]
	v_exp_f32_e32 v20, v33
	v_add_f32_e32 v21, 1.0, v40
	v_rcp_f32_e32 v21, v21
	v_pk_fma_f32 v[24:25], v[24:25], v[42:43], v[196:197] op_sel_hi:[1,0,1]
	v_add_f32_e32 v20, 1.0, v20
	v_rcp_f32_e32 v20, v20
	v_mul_f32_e32 v24, v32, v24
	v_mul_f32_e32 v21, v24, v21
	v_mul_f32_e32 v24, v33, v25
	v_exp_f32_e32 v25, v34
	v_mul_f32_e32 v20, v24, v20
	v_exp_f32_e32 v24, v35
	v_cvt_pk_bf16_f32 v20, v21, v20
	v_add_f32_e32 v21, 1.0, v25
	v_rcp_f32_e32 v21, v21
	v_add_f32_e32 v24, 1.0, v24
	v_rcp_f32_e32 v24, v24
	v_pk_fma_f32 v[26:27], v[26:27], v[42:43], v[198:199] op_sel_hi:[1,0,1]
	v_mul_f32_e32 v22, v28, v22
	v_mul_f32_e32 v25, v34, v26
	v_mul_f32_e32 v21, v25, v21
	v_mul_f32_e32 v25, v35, v27
	v_mul_f32_e32 v24, v25, v24
	v_exp_f32_e32 v25, v28
	v_cvt_pk_bf16_f32 v21, v21, v24
	v_exp_f32_e32 v24, v29
	v_exp_f32_e32 v26, v30
	v_add_f32_e32 v25, 1.0, v25
	v_rcp_f32_e32 v25, v25
	v_add_f32_e32 v24, 1.0, v24
	v_rcp_f32_e32 v24, v24
	v_mul_f32_e32 v23, v29, v23
	v_mul_f32_e32 v22, v22, v25
	v_mul_f32_e32 v25, v30, v36
	v_mul_f32_e32 v23, v23, v24
	v_cvt_pk_bf16_f32 v22, v22, v23
	v_exp_f32_e32 v23, v31
	v_add_f32_e32 v24, 1.0, v26
	v_rcp_f32_e32 v24, v24
	s_waitcnt vmcnt(6)
	v_cvt_f32_u32_e32 v27, v132
	v_add_f32_e32 v23, 1.0, v23
	v_rcp_f32_e32 v23, v23
	v_mul_f32_e32 v28, v25, v24
	v_cvt_f32_i32_e32 v25, v133
	v_cvt_f32_i32_e32 v24, v135
	v_cvt_f32_u32_e32 v26, v134
	v_mad_i64_i32 v[38:39], s[16:17], v214, s27, v[210:211]
	v_mul_f32_e32 v29, v31, v37
	v_lshl_add_u64 v[38:39], v[38:39], 0, v[212:213]
	v_mul_f32_e32 v23, v29, v23
	v_cvt_pk_bf16_f32 v23, v28, v23
	global_store_dwordx4 v[38:39], v[20:23], off
	s_nop 1
	v_pk_fma_f32 v[20:21], v[24:25], s[30:31], v[26:27] op_sel_hi:[1,0,1]
	s_nop 0
	v_pk_mul_f32 v[20:21], v[20:21], s[90:91] op_sel_hi:[1,0]
	s_nop 0
	v_pk_mul_f32 v[20:21], v[20:21], s[92:93] op_sel_hi:[1,0]
	s_nop 0
	v_fma_f32 v22, -v21, v21, v20
	v_max_f32_e32 v22, 0, v22
	v_add_f32_e32 v22, 0x3727c5ac, v22
	v_rsq_f32_e32 v25, v22
	v_pk_fma_f32 v[16:17], v[194:195], v[20:21], v[16:17] op_sel:[0,1,0] neg_lo:[1,0,0] neg_hi:[1,0,0]
	v_pk_fma_f32 v[18:19], v[186:187], v[20:21], v[18:19] op_sel:[0,1,0] neg_lo:[1,0,0] neg_hi:[1,0,0]
	v_pk_fma_f32 v[12:13], v[190:191], v[20:21], v[12:13] op_sel:[0,1,0] neg_lo:[1,0,0] neg_hi:[1,0,0]
	v_mul_f32_e32 v24, 0xbfb8aa3b, v25
	v_pk_fma_f32 v[16:17], v[16:17], v[24:25], v[204:205] op_sel_hi:[1,0,1]
	v_pk_fma_f32 v[14:15], v[172:173], v[20:21], v[14:15] op_sel:[0,1,0] neg_lo:[1,0,0] neg_hi:[1,0,0]
	v_mul_f32_e32 v26, 0xbf317218, v25
	v_pk_fma_f32 v[18:19], v[18:19], v[24:25], v[206:207] op_sel_hi:[1,0,1]
	v_pk_fma_f32 v[14:15], v[14:15], v[24:25], v[202:203] op_sel_hi:[1,0,1]
	v_pk_fma_f32 v[12:13], v[12:13], v[24:25], v[200:201] op_sel_hi:[1,0,1]
	v_pk_fma_f32 v[4:5], v[170:171], v[20:21], v[4:5] op_sel:[0,1,0] neg_lo:[1,0,0] neg_hi:[1,0,0]
	v_pk_fma_f32 v[6:7], v[166:167], v[20:21], v[6:7] op_sel:[0,1,0] neg_lo:[1,0,0] neg_hi:[1,0,0]
	v_exp_f32_e32 v24, v16
	v_pk_fma_f32 v[8:9], v[184:185], v[20:21], v[8:9] op_sel:[0,1,0] neg_lo:[1,0,0] neg_hi:[1,0,0]
	v_pk_fma_f32 v[10:11], v[168:169], v[20:21], v[10:11] op_sel:[0,1,0] neg_lo:[1,0,0] neg_hi:[1,0,0]
	v_pk_fma_f32 v[20:21], v[6:7], v[26:27], v[192:193] op_sel_hi:[1,0,1]
	v_pk_fma_f32 v[6:7], v[4:5], v[26:27], v[188:189] op_sel_hi:[1,0,1]
	v_exp_f32_e32 v4, v17
	v_add_f32_e32 v5, 1.0, v24
	v_rcp_f32_e32 v5, v5
	v_pk_fma_f32 v[8:9], v[8:9], v[26:27], v[196:197] op_sel_hi:[1,0,1]
	v_add_f32_e32 v4, 1.0, v4
	v_rcp_f32_e32 v4, v4
	v_mul_f32_e32 v8, v16, v8
	v_mul_f32_e32 v5, v8, v5
	v_mul_f32_e32 v8, v17, v9
	v_exp_f32_e32 v9, v18
	v_mul_f32_e32 v4, v8, v4
	v_cvt_pk_bf16_f32 v4, v5, v4
	v_exp_f32_e32 v5, v19
	v_add_f32_e32 v8, 1.0, v9
	v_rcp_f32_e32 v8, v8
	v_pk_fma_f32 v[10:11], v[10:11], v[26:27], v[198:199] op_sel_hi:[1,0,1]
	v_add_f32_e32 v5, 1.0, v5
	v_rcp_f32_e32 v5, v5
	v_mul_f32_e32 v9, v18, v10
	v_mul_f32_e32 v8, v9, v8
	v_mul_f32_e32 v9, v19, v11
	v_exp_f32_e32 v10, v12
	v_mul_f32_e32 v5, v9, v5
	v_cvt_pk_bf16_f32 v5, v8, v5
	v_exp_f32_e32 v8, v13
	v_add_f32_e32 v9, 1.0, v10
	v_rcp_f32_e32 v9, v9
	v_mul_f32_e32 v6, v12, v6
	v_add_f32_e32 v8, 1.0, v8
	v_rcp_f32_e32 v8, v8
	v_mul_f32_e32 v6, v6, v9
	v_mul_f32_e32 v7, v13, v7
	v_exp_f32_e32 v9, v14
	v_mul_f32_e32 v7, v7, v8
	v_exp_f32_e32 v8, v15
	v_cvt_pk_bf16_f32 v6, v6, v7
	v_add_f32_e32 v7, 1.0, v9
	v_rcp_f32_e32 v7, v7
	v_add_f32_e32 v8, 1.0, v8
	v_rcp_f32_e32 v8, v8
	v_mad_i64_i32 v[22:23], s[16:17], v208, s27, v[210:211]
	v_mul_f32_e32 v9, v14, v20
	v_lshl_add_u64 v[22:23], v[22:23], 0, v[212:213]
	v_mul_f32_e32 v7, v9, v7
	v_mul_f32_e32 v9, v15, v21
	v_mul_f32_e32 v8, v9, v8
	v_cvt_pk_bf16_f32 v7, v7, v8
	global_store_dwordx4 v[22:23], v[4:7], off
	s_cbranch_vccnz .LBB0_866
	s_andn2_b64 vcc, exec, s[10:11]
	s_cbranch_vccnz .LBB0_865
	s_barrier
	s_branch .LBB0_865

.LBB0_1038:
	v_lshl_add_u32 v188, s31, 8, v242
	v_ashrrev_i32_e32 v189, 31, v188
	v_lshl_or_b32 v140, s91, 8, v245
	v_lshl_add_u64 v[132:133], v[188:189], 4, s[14:15]
	v_ashrrev_i32_e32 v141, 31, v140
	global_load_dwordx4 v[164:167], v[132:133], off
	v_lshlrev_b64 v[132:133], 12, v[188:189]
	v_lshl_add_u64 v[132:133], s[0:1], 0, v[132:133]
	v_lshlrev_b64 v[222:223], 1, v[140:141]
	v_lshl_add_u64 v[228:229], v[132:133], 0, v[222:223]
	v_or_b32_e32 v132, 16, v188
	v_ashrrev_i32_e32 v133, 31, v132
	v_lshl_add_u64 v[134:135], v[132:133], 4, s[14:15]
	v_lshlrev_b64 v[132:133], 12, v[132:133]
	v_lshl_add_u64 v[132:133], s[0:1], 0, v[132:133]
	v_lshlrev_b64 v[140:141], 2, v[140:141]
	v_lshl_add_u64 v[224:225], v[132:133], 0, v[222:223]
	v_lshl_add_u64 v[174:175], s[10:11], 0, v[140:141]
	global_load_dwordx4 v[160:163], v[228:229], off
	global_load_dwordx4 v[156:159], v[228:229], off offset:64
	global_load_dwordx4 v[144:147], v[134:135], off
	global_load_dwordx4 v[136:139], v[224:225], off
	s_nop 0
	global_load_dwordx4 v[132:135], v[224:225], off offset:64
	v_lshl_add_u64 v[176:177], s[12:13], 0, v[140:141]
	global_load_dwordx4 v[140:143], v[174:175], off offset:16
	global_load_dwordx4 v[148:151], v[174:175], off
	v_readlane_b32 s16, v252, 10
	v_readlane_b32 s17, v252, 11
	s_mov_b64 s[28:29], -1
	v_readlane_b32 s100, v252, 12
	v_readlane_b32 s101, v252, 13
	s_and_b64 s[100:101], exec, s[100:101]
	s_cbranch_scc0 .Lalign_1035
	s_barrier
.Lalign_1035:
	s_waitcnt vmcnt(0)
	v_pk_mul_f32 v[194:195], v[142:143], s[86:87] op_sel_hi:[1,0]
	v_pk_mul_f32 v[190:191], v[150:151], s[86:87] op_sel_hi:[1,0]
	v_pk_mul_f32 v[192:193], v[148:149], s[86:87] op_sel_hi:[1,0]
	global_load_dwordx4 v[148:151], v[176:177], off offset:16
	global_load_dwordx4 v[152:155], v[176:177], off
	v_pk_mul_f32 v[196:197], v[140:141], s[86:87] op_sel_hi:[1,0]
	s_waitcnt vmcnt(1)
	v_pk_mul_f32 v[198:199], v[150:151], s[86:87] op_sel_hi:[1,0]
	v_pk_mul_f32 v[200:201], v[148:149], s[86:87] op_sel_hi:[1,0]
	global_load_dwordx4 v[140:143], v[174:175], off offset:144
	global_load_dwordx4 v[148:151], v[174:175], off offset:128
	s_waitcnt vmcnt(2)
	v_pk_mul_f32 v[202:203], v[154:155], s[86:87] op_sel_hi:[1,0]
	v_pk_mul_f32 v[204:205], v[152:153], s[86:87] op_sel_hi:[1,0]
	v_cvt_f32_i32_e32 v175, v165
	v_cvt_f32_i32_e32 v174, v167
	v_cvt_f32_u32_e32 v165, v164
	v_cvt_f32_u32_e32 v164, v166
	v_lshlrev_b32_e32 v166, 16, v160
	v_and_b32_e32 v160, 0xffff0000, v160
	v_and_b32_e32 v167, 0xffff0000, v161
	v_pk_fma_f32 v[164:165], v[174:175], s[30:31], v[164:165] op_sel_hi:[1,0,1]
	v_lshlrev_b32_e32 v174, 16, v161
	v_pk_mul_f32 v[164:165], v[164:165], s[90:91] op_sel_hi:[1,0]
	s_waitcnt vmcnt(1)
	v_pk_mul_f32 v[212:213], v[140:141], s[86:87] op_sel_hi:[1,0]
	s_waitcnt vmcnt(0)
	v_pk_mul_f32 v[206:207], v[150:151], s[86:87] op_sel_hi:[1,0]
	v_pk_mul_f32 v[208:209], v[148:149], s[86:87] op_sel_hi:[1,0]
	global_load_dwordx4 v[148:151], v[176:177], off offset:144
	global_load_dwordx4 v[152:155], v[176:177], off offset:128
	v_pk_mul_f32 v[164:165], v[164:165], s[92:93] op_sel_hi:[1,0]
	v_or_b32_e32 v140, 32, v188
	v_fma_f32 v164, -v165, v165, v164
	v_max_f32_e32 v164, 0, v164
	v_add_f32_e32 v164, 0x3727c5ac, v164
	v_rsq_f32_e32 v164, v164
	v_ashrrev_i32_e32 v141, 31, v140
	v_pk_mul_f32 v[210:211], v[142:143], s[86:87] op_sel_hi:[1,0]
	v_lshl_add_u64 v[142:143], v[140:141], 4, s[14:15]
	v_sub_f32_e32 v161, v160, v165
	v_sub_f32_e32 v160, v166, v165
	v_pk_mul_f32 v[160:161], v[160:161], v[164:165] op_sel_hi:[1,0]
	v_lshlrev_b64 v[140:141], 12, v[140:141]
	v_pk_fma_f32 v[160:161], v[192:193], v[160:161], v[204:205]
	v_lshl_add_u64 v[140:141], s[0:1], 0, v[140:141]
	v_pk_fma_f32 v[128:129], v[128:129], 0.5, v[160:161] op_sel_hi:[1,0,1]
	v_lshlrev_b32_e32 v160, 16, v162
	v_and_b32_e32 v161, 0xffff0000, v162
	v_lshlrev_b32_e32 v162, 16, v163
	v_and_b32_e32 v163, 0xffff0000, v163
	v_sub_f32_e32 v161, v161, v165
	v_sub_f32_e32 v160, v160, v165
	v_sub_f32_e32 v163, v163, v165
	v_sub_f32_e32 v162, v162, v165
	v_pk_mul_f32 v[160:161], v[160:161], v[164:165] op_sel_hi:[1,0]
	v_pk_mul_f32 v[162:163], v[162:163], v[164:165] op_sel_hi:[1,0]
	v_pk_fma_f32 v[160:161], v[196:197], v[160:161], v[200:201]
	v_pk_fma_f32 v[162:163], v[194:195], v[162:163], v[198:199]
	v_pk_fma_f32 v[124:125], v[124:125], 0.5, v[160:161] op_sel_hi:[1,0,1]
	v_lshlrev_b32_e32 v160, 16, v156
	v_and_b32_e32 v156, 0xffff0000, v156
	v_pk_fma_f32 v[126:127], v[126:127], 0.5, v[162:163] op_sel_hi:[1,0,1]
	v_lshlrev_b32_e32 v162, 16, v157
	v_and_b32_e32 v161, 0xffff0000, v157
	v_sub_f32_e32 v157, v156, v165
	v_sub_f32_e32 v156, v160, v165
	v_pk_mul_f32 v[156:157], v[156:157], v[164:165] op_sel_hi:[1,0]
	v_sub_f32_e32 v167, v167, v165
	v_sub_f32_e32 v166, v174, v165
	v_lshl_add_u64 v[226:227], v[140:141], 0, v[222:223]
	v_pk_mul_f32 v[166:167], v[166:167], v[164:165] op_sel_hi:[1,0]
	v_sub_f32_e32 v161, v161, v165
	v_sub_f32_e32 v160, v162, v165
	v_pk_fma_f32 v[166:167], v[190:191], v[166:167], v[202:203]
	v_pk_mul_f32 v[160:161], v[160:161], v[164:165] op_sel_hi:[1,0]
	v_pk_fma_f32 v[130:131], v[130:131], 0.5, v[166:167] op_sel_hi:[1,0,1]
	s_waitcnt vmcnt(1)
	v_pk_mul_f32 v[214:215], v[150:151], s[86:87] op_sel_hi:[1,0]
	s_waitcnt vmcnt(0)
	v_pk_mul_f32 v[218:219], v[154:155], s[86:87] op_sel_hi:[1,0]
	v_pk_mul_f32 v[220:221], v[152:153], s[86:87] op_sel_hi:[1,0]
	global_load_dwordx4 v[152:155], v[142:143], off
	v_pk_fma_f32 v[156:157], v[208:209], v[156:157], v[220:221]
	v_pk_mul_f32 v[216:217], v[148:149], s[86:87] op_sel_hi:[1,0]
	v_pk_fma_f32 v[120:121], v[120:121], 0.5, v[156:157] op_sel_hi:[1,0,1]
	v_lshlrev_b32_e32 v156, 16, v158
	v_and_b32_e32 v157, 0xffff0000, v158
	v_lshlrev_b32_e32 v158, 16, v159
	v_and_b32_e32 v159, 0xffff0000, v159
	v_sub_f32_e32 v157, v157, v165
	v_sub_f32_e32 v156, v156, v165
	v_sub_f32_e32 v159, v159, v165
	v_sub_f32_e32 v158, v158, v165
	v_pk_mul_f32 v[158:159], v[158:159], v[164:165] op_sel_hi:[1,0]
	v_pk_mul_f32 v[156:157], v[156:157], v[164:165] op_sel_hi:[1,0]
	global_load_dwordx4 v[148:151], v[226:227], off
	global_load_dwordx4 v[140:143], v[226:227], off offset:64
	v_pk_fma_f32 v[156:157], v[156:157], v[212:213], v[216:217]
	v_pk_fma_f32 v[158:159], v[158:159], v[210:211], v[214:215]
	v_pk_fma_f32 v[160:161], v[206:207], v[160:161], v[218:219]
	v_pk_fma_f32 v[158:159], v[118:119], 0.5, v[158:159] op_sel_hi:[1,0,1]
	v_pk_fma_f32 v[156:157], v[116:117], 0.5, v[156:157] op_sel_hi:[1,0,1]
	v_cvt_pk_bf16_f32 v116, v128, v129
	v_cvt_pk_bf16_f32 v117, v130, v131
	v_cvt_pk_bf16_f32 v118, v124, v125
	v_cvt_pk_bf16_f32 v119, v126, v127
	v_pk_fma_f32 v[122:123], v[122:123], 0.5, v[160:161] op_sel_hi:[1,0,1]
	global_store_dwordx4 v[228:229], v[116:119], off
	v_pk_add_f32 v[160:161], v[120:121], v[156:157]
	v_pk_add_f32 v[162:163], v[122:123], v[158:159]
	v_cvt_pk_bf16_f32 v116, v120, v121
	v_cvt_pk_bf16_f32 v117, v122, v123
	v_cvt_pk_bf16_f32 v118, v156, v157
	v_cvt_pk_bf16_f32 v119, v158, v159
	global_store_dwordx4 v[228:229], v[116:119], off offset:64
	s_nop 1
	v_pk_add_f32 v[116:117], v[128:129], v[124:125]
	v_pk_add_f32 v[118:119], v[130:131], v[126:127]
	v_pk_mul_f32 v[126:127], v[126:127], v[126:127]
	v_pk_mul_f32 v[124:125], v[124:125], v[124:125]
	v_pk_fma_f32 v[126:127], v[130:131], v[130:131], v[126:127]
	v_pk_fma_f32 v[124:125], v[128:129], v[128:129], v[124:125]
	v_pk_mul_f32 v[128:129], v[158:159], v[158:159]
	v_pk_mul_f32 v[130:131], v[156:157], v[156:157]
	v_pk_add_f32 v[118:119], v[118:119], v[162:163]
	v_pk_add_f32 v[116:117], v[116:117], v[160:161]
	v_pk_fma_f32 v[120:121], v[120:121], v[120:121], v[130:131]
	v_pk_fma_f32 v[122:123], v[122:123], v[122:123], v[128:129]
	v_pk_add_f32 v[120:121], v[124:125], v[120:121]
	v_pk_add_f32 v[122:123], v[126:127], v[122:123]
	v_add_f32_e32 v116, v116, v117
	v_add_f32_e32 v117, v118, v119
	v_add_f32_e32 v116, v116, v117
	v_add_f32_e32 v117, v120, v121
	v_add_f32_e32 v118, v122, v123
	v_and_b32_e32 v119, 64, v230
	v_add_f32_e32 v117, v117, v118
	v_xor_b32_e32 v118, 16, v230
	v_add_u32_e32 v119, 64, v119
	v_cmp_lt_i32_e32 vcc, v118, v119
	v_cvt_f32_i32_e32 v161, v145
	v_cvt_f32_i32_e32 v160, v147
	v_cndmask_b32_e32 v118, v230, v118, vcc
	v_lshlrev_b32_e32 v156, 2, v118
	ds_bpermute_b32 v118, v156, v116
	v_cvt_f32_u32_e32 v145, v144
	v_cvt_f32_u32_e32 v144, v146
	v_lshlrev_b32_e32 v146, 16, v136
	v_and_b32_e32 v136, 0xffff0000, v136
	s_waitcnt lgkmcnt(0)
	v_add_f32_e32 v130, v116, v118
	v_xor_b32_e32 v116, 32, v230
	v_cmp_lt_i32_e32 vcc, v116, v119
	v_pk_fma_f32 v[144:145], v[160:161], s[30:31], v[144:145] op_sel_hi:[1,0,1]
	v_lshlrev_b32_e32 v160, 16, v137
	v_cndmask_b32_e32 v116, v230, v116, vcc
	v_lshlrev_b32_e32 v158, 2, v116
	ds_bpermute_b32 v116, v156, v117
	v_pk_mul_f32 v[144:145], v[144:145], s[90:91] op_sel_hi:[1,0]
	v_and_b32_e32 v147, 0xffff0000, v137
	v_pk_mul_f32 v[144:145], v[144:145], s[92:93] op_sel_hi:[1,0]
	ds_bpermute_b32 v131, v158, v130
	s_waitcnt lgkmcnt(1)
	v_add_f32_e32 v157, v117, v116
	v_or_b32_e32 v116, 48, v188
	v_ashrrev_i32_e32 v117, 31, v116
	v_lshl_add_u64 v[118:119], v[116:117], 4, s[14:15]
	global_load_dwordx4 v[124:127], v[118:119], off
	v_fma_f32 v144, -v145, v145, v144
	v_max_f32_e32 v144, 0, v144
	v_add_f32_e32 v144, 0x3727c5ac, v144
	v_rsq_f32_e32 v144, v144
	v_lshlrev_b64 v[116:117], 12, v[116:117]
	v_lshl_add_u64 v[116:117], s[0:1], 0, v[116:117]
	v_lshl_add_u64 v[128:129], v[116:117], 0, v[222:223]
	v_sub_f32_e32 v137, v136, v145
	v_sub_f32_e32 v136, v146, v145
	global_load_dwordx4 v[120:123], v[128:129], off
	global_load_dwordx4 v[116:119], v[128:129], off offset:64
	v_pk_mul_f32 v[136:137], v[136:137], v[144:145] op_sel_hi:[1,0]
	v_sub_f32_e32 v147, v147, v145
	v_pk_fma_f32 v[136:137], v[192:193], v[136:137], v[204:205]
	v_sub_f32_e32 v146, v160, v145
	v_pk_fma_f32 v[112:113], v[112:113], 0.5, v[136:137] op_sel_hi:[1,0,1]
	v_lshlrev_b32_e32 v136, 16, v138
	v_and_b32_e32 v137, 0xffff0000, v138
	v_lshlrev_b32_e32 v138, 16, v139
	v_and_b32_e32 v139, 0xffff0000, v139
	v_sub_f32_e32 v137, v137, v145
	v_sub_f32_e32 v136, v136, v145
	v_sub_f32_e32 v139, v139, v145
	v_sub_f32_e32 v138, v138, v145
	v_pk_mul_f32 v[136:137], v[136:137], v[144:145] op_sel_hi:[1,0]
	v_pk_mul_f32 v[138:139], v[138:139], v[144:145] op_sel_hi:[1,0]
	v_pk_fma_f32 v[136:137], v[196:197], v[136:137], v[200:201]
	v_pk_fma_f32 v[138:139], v[194:195], v[138:139], v[198:199]
	v_pk_fma_f32 v[108:109], v[108:109], 0.5, v[136:137] op_sel_hi:[1,0,1]
	v_lshlrev_b32_e32 v136, 16, v132
	v_and_b32_e32 v132, 0xffff0000, v132
	v_pk_fma_f32 v[110:111], v[110:111], 0.5, v[138:139] op_sel_hi:[1,0,1]
	v_lshlrev_b32_e32 v138, 16, v133
	v_and_b32_e32 v137, 0xffff0000, v133
	v_sub_f32_e32 v133, v132, v145
	v_sub_f32_e32 v132, v136, v145
	v_pk_mul_f32 v[132:133], v[132:133], v[144:145] op_sel_hi:[1,0]
	v_pk_mul_f32 v[146:147], v[146:147], v[144:145] op_sel_hi:[1,0]
	v_pk_fma_f32 v[132:133], v[208:209], v[132:133], v[220:221]
	v_sub_f32_e32 v137, v137, v145
	v_pk_fma_f32 v[104:105], v[104:105], 0.5, v[132:133] op_sel_hi:[1,0,1]
	v_lshlrev_b32_e32 v132, 16, v134
	v_and_b32_e32 v133, 0xffff0000, v134
	v_lshlrev_b32_e32 v134, 16, v135
	v_and_b32_e32 v135, 0xffff0000, v135
	v_sub_f32_e32 v133, v133, v145
	v_sub_f32_e32 v132, v132, v145
	v_sub_f32_e32 v135, v135, v145
	v_sub_f32_e32 v134, v134, v145
	v_sub_f32_e32 v136, v138, v145
	v_pk_mul_f32 v[134:135], v[134:135], v[144:145] op_sel_hi:[1,0]
	v_pk_mul_f32 v[132:133], v[132:133], v[144:145] op_sel_hi:[1,0]
	v_pk_fma_f32 v[146:147], v[190:191], v[146:147], v[202:203]
	v_pk_mul_f32 v[136:137], v[136:137], v[144:145] op_sel_hi:[1,0]
	v_pk_fma_f32 v[132:133], v[212:213], v[132:133], v[216:217]
	v_pk_fma_f32 v[134:135], v[210:211], v[134:135], v[214:215]
	v_pk_fma_f32 v[114:115], v[114:115], 0.5, v[146:147] op_sel_hi:[1,0,1]
	v_pk_fma_f32 v[136:137], v[206:207], v[136:137], v[218:219]
	v_pk_fma_f32 v[134:135], v[102:103], 0.5, v[134:135] op_sel_hi:[1,0,1]
	v_pk_fma_f32 v[132:133], v[100:101], 0.5, v[132:133] op_sel_hi:[1,0,1]
	v_cvt_pk_bf16_f32 v100, v112, v113
	v_cvt_pk_bf16_f32 v101, v114, v115
	v_cvt_pk_bf16_f32 v102, v108, v109
	v_cvt_pk_bf16_f32 v103, v110, v111
	v_pk_fma_f32 v[106:107], v[106:107], 0.5, v[136:137] op_sel_hi:[1,0,1]
	global_store_dwordx4 v[224:225], v[100:103], off
	v_pk_add_f32 v[136:137], v[104:105], v[132:133]
	v_pk_add_f32 v[138:139], v[106:107], v[134:135]
	v_cvt_pk_bf16_f32 v100, v104, v105
	v_cvt_pk_bf16_f32 v101, v106, v107
	v_cvt_pk_bf16_f32 v102, v132, v133
	v_cvt_pk_bf16_f32 v103, v134, v135
	global_store_dwordx4 v[224:225], v[100:103], off offset:64
	s_waitcnt vmcnt(8)
	v_lshlrev_b32_e32 v144, 16, v149
	v_and_b32_e32 v145, 0xffff0000, v149
	v_pk_add_f32 v[100:101], v[112:113], v[108:109]
	v_pk_add_f32 v[102:103], v[114:115], v[110:111]
	v_pk_mul_f32 v[110:111], v[110:111], v[110:111]
	v_pk_mul_f32 v[108:109], v[108:109], v[108:109]
	v_pk_fma_f32 v[110:111], v[114:115], v[114:115], v[110:111]
	v_pk_fma_f32 v[108:109], v[112:113], v[112:113], v[108:109]
	v_pk_mul_f32 v[112:113], v[134:135], v[134:135]
	v_pk_mul_f32 v[114:115], v[132:133], v[132:133]
	v_pk_add_f32 v[102:103], v[102:103], v[138:139]
	v_pk_add_f32 v[100:101], v[100:101], v[136:137]
	v_pk_fma_f32 v[104:105], v[104:105], v[104:105], v[114:115]
	v_pk_fma_f32 v[106:107], v[106:107], v[106:107], v[112:113]
	v_pk_add_f32 v[104:105], v[108:109], v[104:105]
	v_pk_add_f32 v[106:107], v[110:111], v[106:107]
	v_add_f32_e32 v100, v100, v101
	v_add_f32_e32 v101, v102, v103
	v_add_f32_e32 v100, v100, v101
	v_add_f32_e32 v101, v104, v105
	v_add_f32_e32 v102, v106, v107
	v_add_f32_e32 v101, v101, v102
	ds_bpermute_b32 v102, v156, v100
	v_cvt_f32_i32_e32 v137, v153
	v_cvt_f32_i32_e32 v136, v155
	v_cvt_f32_u32_e32 v139, v152
	v_cvt_f32_u32_e32 v138, v154
	s_waitcnt lgkmcnt(0)
	v_add_f32_e32 v132, v100, v102
	ds_bpermute_b32 v100, v156, v101
	v_add_u32_e32 v112, 0x80, v188
	v_ashrrev_i32_e32 v113, 31, v112
	v_pk_fma_f32 v[136:137], v[136:137], s[30:31], v[138:139] op_sel_hi:[1,0,1]
	v_and_b32_e32 v138, 0xffff0000, v148
	s_waitcnt lgkmcnt(0)
	v_add_f32_e32 v134, v101, v100
	v_lshl_add_u64 v[100:101], v[112:113], 4, s[14:15]
	v_pk_mul_f32 v[136:137], v[136:137], s[90:91] op_sel_hi:[1,0]
	global_load_dwordx4 v[108:111], v[100:101], off
	v_pk_mul_f32 v[136:137], v[136:137], s[92:93] op_sel_hi:[1,0]
	v_lshlrev_b64 v[100:101], 12, v[112:113]
	v_fma_f32 v113, -v137, v137, v136
	v_max_f32_e32 v113, 0, v113
	v_add_f32_e32 v113, 0x3727c5ac, v113
	v_rsq_f32_e32 v136, v113
	v_lshlrev_b32_e32 v113, 16, v148
	v_sub_f32_e32 v139, v138, v137
	v_sub_f32_e32 v138, v113, v137
	v_pk_mul_f32 v[138:139], v[138:139], v[136:137] op_sel_hi:[1,0]
	v_lshlrev_b32_e32 v113, 16, v150
	v_pk_fma_f32 v[138:139], v[192:193], v[138:139], v[204:205]
	v_lshl_add_u64 v[100:101], s[0:1], 0, v[100:101]
	v_pk_fma_f32 v[96:97], v[96:97], 0.5, v[138:139] op_sel_hi:[1,0,1]
	v_and_b32_e32 v138, 0xffff0000, v150
	v_sub_f32_e32 v139, v138, v137
	v_sub_f32_e32 v138, v113, v137
	v_lshl_add_u64 v[114:115], v[100:101], 0, v[222:223]
	v_pk_mul_f32 v[138:139], v[138:139], v[136:137] op_sel_hi:[1,0]
	global_load_dwordx4 v[104:107], v[114:115], off
	global_load_dwordx4 v[100:103], v[114:115], off offset:64
	v_pk_fma_f32 v[138:139], v[196:197], v[138:139], v[200:201]
	s_waitcnt vmcnt(10)
	v_lshlrev_b32_e32 v113, 16, v140
	v_pk_fma_f32 v[92:93], v[92:93], 0.5, v[138:139] op_sel_hi:[1,0,1]
	v_and_b32_e32 v138, 0xffff0000, v140
	v_lshlrev_b32_e32 v140, 16, v141
	v_and_b32_e32 v141, 0xffff0000, v141
	v_sub_f32_e32 v145, v145, v137
	v_sub_f32_e32 v144, v144, v137
	v_sub_f32_e32 v139, v138, v137
	v_sub_f32_e32 v138, v113, v137
	v_sub_f32_e32 v141, v141, v137
	v_sub_f32_e32 v140, v140, v137
	v_pk_mul_f32 v[144:145], v[144:145], v[136:137] op_sel_hi:[1,0]
	v_pk_mul_f32 v[140:141], v[140:141], v[136:137] op_sel_hi:[1,0]
	v_pk_mul_f32 v[138:139], v[138:139], v[136:137] op_sel_hi:[1,0]
	v_pk_fma_f32 v[144:145], v[190:191], v[144:145], v[202:203]
	v_pk_fma_f32 v[138:139], v[208:209], v[138:139], v[220:221]
	v_pk_fma_f32 v[140:141], v[206:207], v[140:141], v[218:219]
	v_pk_fma_f32 v[98:99], v[98:99], 0.5, v[144:145] op_sel_hi:[1,0,1]
	v_lshlrev_b32_e32 v144, 16, v151
	v_and_b32_e32 v145, 0xffff0000, v151
	v_pk_fma_f32 v[90:91], v[90:91], 0.5, v[140:141] op_sel_hi:[1,0,1]
	v_pk_fma_f32 v[88:89], v[88:89], 0.5, v[138:139] op_sel_hi:[1,0,1]
	v_lshlrev_b32_e32 v113, 16, v142
	v_and_b32_e32 v138, 0xffff0000, v142
	v_lshlrev_b32_e32 v140, 16, v143
	v_and_b32_e32 v141, 0xffff0000, v143
	v_sub_f32_e32 v145, v145, v137
	v_sub_f32_e32 v144, v144, v137
	v_sub_f32_e32 v139, v138, v137
	v_sub_f32_e32 v138, v113, v137
	v_sub_f32_e32 v141, v141, v137
	v_sub_f32_e32 v140, v140, v137
	v_pk_mul_f32 v[144:145], v[144:145], v[136:137] op_sel_hi:[1,0]
	v_pk_mul_f32 v[140:141], v[140:141], v[136:137] op_sel_hi:[1,0]
	v_pk_mul_f32 v[136:137], v[138:139], v[136:137] op_sel_hi:[1,0]
	v_pk_fma_f32 v[144:145], v[194:195], v[144:145], v[198:199]
	v_pk_fma_f32 v[136:137], v[212:213], v[136:137], v[216:217]
	v_pk_fma_f32 v[138:139], v[210:211], v[140:141], v[214:215]
	v_pk_fma_f32 v[94:95], v[94:95], 0.5, v[144:145] op_sel_hi:[1,0,1]
	v_pk_fma_f32 v[138:139], v[86:87], 0.5, v[138:139] op_sel_hi:[1,0,1]
	v_pk_fma_f32 v[136:137], v[84:85], 0.5, v[136:137] op_sel_hi:[1,0,1]
	v_cvt_pk_bf16_f32 v84, v96, v97
	v_cvt_pk_bf16_f32 v85, v98, v99
	v_cvt_pk_bf16_f32 v86, v92, v93
	v_cvt_pk_bf16_f32 v87, v94, v95
	global_store_dwordx4 v[226:227], v[84:87], off
	v_pk_add_f32 v[140:141], v[88:89], v[136:137]
	v_pk_add_f32 v[142:143], v[90:91], v[138:139]
	v_cvt_pk_bf16_f32 v84, v88, v89
	v_cvt_pk_bf16_f32 v85, v90, v91
	v_cvt_pk_bf16_f32 v86, v136, v137
	v_cvt_pk_bf16_f32 v87, v138, v139
	global_store_dwordx4 v[226:227], v[84:87], off offset:64
	ds_bpermute_b32 v159, v158, v157
	ds_bpermute_b32 v135, v158, v134
	v_pk_add_f32 v[84:85], v[96:97], v[92:93]
	v_pk_add_f32 v[86:87], v[98:99], v[94:95]
	v_pk_mul_f32 v[94:95], v[94:95], v[94:95]
	v_pk_mul_f32 v[92:93], v[92:93], v[92:93]
	v_pk_fma_f32 v[94:95], v[98:99], v[98:99], v[94:95]
	v_pk_fma_f32 v[92:93], v[96:97], v[96:97], v[92:93]
	v_pk_mul_f32 v[96:97], v[138:139], v[138:139]
	v_pk_mul_f32 v[98:99], v[136:137], v[136:137]
	v_pk_add_f32 v[86:87], v[86:87], v[142:143]
	v_pk_add_f32 v[84:85], v[84:85], v[140:141]
	v_pk_fma_f32 v[88:89], v[88:89], v[88:89], v[98:99]
	v_pk_fma_f32 v[90:91], v[90:91], v[90:91], v[96:97]
	v_pk_add_f32 v[88:89], v[92:93], v[88:89]
	v_pk_add_f32 v[90:91], v[94:95], v[90:91]
	v_add_f32_e32 v84, v84, v85
	v_add_f32_e32 v85, v86, v87
	v_add_f32_e32 v84, v84, v85
	v_add_f32_e32 v85, v88, v89
	v_add_f32_e32 v86, v90, v91
	v_add_f32_e32 v85, v85, v86
	ds_bpermute_b32 v86, v156, v84
	s_waitcnt vmcnt(9)
	v_cvt_f32_i32_e32 v139, v125
	v_cvt_f32_i32_e32 v138, v127
	v_cvt_f32_u32_e32 v125, v124
	v_cvt_f32_u32_e32 v124, v126
	s_waitcnt lgkmcnt(0)
	v_add_f32_e32 v98, v84, v86
	ds_bpermute_b32 v84, v156, v85
	s_waitcnt vmcnt(8)
	v_lshlrev_b32_e32 v126, 16, v120
	v_pk_fma_f32 v[124:125], v[138:139], s[30:31], v[124:125] op_sel_hi:[1,0,1]
	v_and_b32_e32 v120, 0xffff0000, v120
	v_pk_mul_f32 v[124:125], v[124:125], s[90:91] op_sel_hi:[1,0]
	s_waitcnt lgkmcnt(0)
	v_add_f32_e32 v113, v85, v84
	v_add_u32_e32 v84, 0x90, v188
	v_ashrrev_i32_e32 v85, 31, v84
	v_lshl_add_u64 v[86:87], v[84:85], 4, s[14:15]
	v_pk_mul_f32 v[124:125], v[124:125], s[92:93] op_sel_hi:[1,0]
	global_load_dwordx4 v[92:95], v[86:87], off
	v_fma_f32 v124, -v125, v125, v124
	v_max_f32_e32 v124, 0, v124
	v_add_f32_e32 v124, 0x3727c5ac, v124
	v_rsq_f32_e32 v124, v124
	v_lshlrev_b32_e32 v137, 16, v121
	v_and_b32_e32 v127, 0xffff0000, v121
	v_sub_f32_e32 v121, v120, v125
	v_sub_f32_e32 v120, v126, v125
	v_pk_mul_f32 v[120:121], v[120:121], v[124:125] op_sel_hi:[1,0]
	v_lshlrev_b64 v[84:85], 12, v[84:85]
	v_pk_fma_f32 v[120:121], v[192:193], v[120:121], v[204:205]
	v_lshl_add_u64 v[84:85], s[0:1], 0, v[84:85]
	v_pk_fma_f32 v[80:81], v[80:81], 0.5, v[120:121] op_sel_hi:[1,0,1]
	v_lshlrev_b32_e32 v120, 16, v122
	v_and_b32_e32 v121, 0xffff0000, v122
	v_lshlrev_b32_e32 v122, 16, v123
	v_and_b32_e32 v123, 0xffff0000, v123
	v_sub_f32_e32 v121, v121, v125
	v_sub_f32_e32 v120, v120, v125
	v_sub_f32_e32 v123, v123, v125
	v_sub_f32_e32 v122, v122, v125
	v_pk_mul_f32 v[120:121], v[120:121], v[124:125] op_sel_hi:[1,0]
	v_lshl_add_u64 v[96:97], v[84:85], 0, v[222:223]
	v_pk_mul_f32 v[122:123], v[122:123], v[124:125] op_sel_hi:[1,0]
	v_pk_fma_f32 v[120:121], v[196:197], v[120:121], v[200:201]
	global_load_dwordx4 v[88:91], v[96:97], off
	global_load_dwordx4 v[84:87], v[96:97], off offset:64
	v_pk_fma_f32 v[122:123], v[194:195], v[122:123], v[198:199]
	v_pk_fma_f32 v[76:77], v[76:77], 0.5, v[120:121] op_sel_hi:[1,0,1]
	s_waitcnt vmcnt(10)
	v_lshlrev_b32_e32 v120, 16, v116
	v_and_b32_e32 v116, 0xffff0000, v116
	v_pk_fma_f32 v[78:79], v[78:79], 0.5, v[122:123] op_sel_hi:[1,0,1]
	v_lshlrev_b32_e32 v122, 16, v117
	v_and_b32_e32 v121, 0xffff0000, v117
	v_sub_f32_e32 v117, v116, v125
	v_sub_f32_e32 v116, v120, v125
	v_pk_mul_f32 v[116:117], v[116:117], v[124:125] op_sel_hi:[1,0]
	v_sub_f32_e32 v127, v127, v125
	v_pk_fma_f32 v[116:117], v[208:209], v[116:117], v[220:221]
	v_sub_f32_e32 v126, v137, v125
	v_pk_fma_f32 v[72:73], v[72:73], 0.5, v[116:117] op_sel_hi:[1,0,1]
	v_lshlrev_b32_e32 v116, 16, v118
	v_and_b32_e32 v117, 0xffff0000, v118
	v_lshlrev_b32_e32 v118, 16, v119
	v_and_b32_e32 v119, 0xffff0000, v119
	v_sub_f32_e32 v117, v117, v125
	v_sub_f32_e32 v116, v116, v125
	v_sub_f32_e32 v119, v119, v125
	v_sub_f32_e32 v118, v118, v125
	v_pk_mul_f32 v[126:127], v[126:127], v[124:125] op_sel_hi:[1,0]
	v_sub_f32_e32 v121, v121, v125
	v_sub_f32_e32 v120, v122, v125
	v_pk_mul_f32 v[118:119], v[118:119], v[124:125] op_sel_hi:[1,0]
	v_pk_mul_f32 v[116:117], v[116:117], v[124:125] op_sel_hi:[1,0]
	v_pk_fma_f32 v[126:127], v[190:191], v[126:127], v[202:203]
	v_pk_mul_f32 v[120:121], v[120:121], v[124:125] op_sel_hi:[1,0]
	v_pk_fma_f32 v[116:117], v[212:213], v[116:117], v[216:217]
	v_pk_fma_f32 v[118:119], v[210:211], v[118:119], v[214:215]
	v_pk_fma_f32 v[82:83], v[82:83], 0.5, v[126:127] op_sel_hi:[1,0,1]
	v_pk_fma_f32 v[120:121], v[206:207], v[120:121], v[218:219]
	v_pk_fma_f32 v[118:119], v[70:71], 0.5, v[118:119] op_sel_hi:[1,0,1]
	v_pk_fma_f32 v[116:117], v[68:69], 0.5, v[116:117] op_sel_hi:[1,0,1]
	v_cvt_pk_bf16_f32 v68, v80, v81
	v_cvt_pk_bf16_f32 v69, v82, v83
	v_cvt_pk_bf16_f32 v70, v76, v77
	v_cvt_pk_bf16_f32 v71, v78, v79
	v_pk_fma_f32 v[74:75], v[74:75], 0.5, v[120:121] op_sel_hi:[1,0,1]
	global_store_dwordx4 v[128:129], v[68:71], off
	v_pk_add_f32 v[120:121], v[72:73], v[116:117]
	v_pk_add_f32 v[122:123], v[74:75], v[118:119]
	v_cvt_pk_bf16_f32 v68, v72, v73
	v_cvt_pk_bf16_f32 v69, v74, v75
	v_cvt_pk_bf16_f32 v70, v116, v117
	v_cvt_pk_bf16_f32 v71, v118, v119
	global_store_dwordx4 v[128:129], v[68:71], off offset:64
	ds_bpermute_b32 v136, v158, v113
	ds_bpermute_b32 v133, v158, v132
	v_pk_add_f32 v[68:69], v[80:81], v[76:77]
	v_pk_add_f32 v[70:71], v[82:83], v[78:79]
	v_pk_mul_f32 v[78:79], v[78:79], v[78:79]
	v_pk_mul_f32 v[76:77], v[76:77], v[76:77]
	v_pk_fma_f32 v[78:79], v[82:83], v[82:83], v[78:79]
	v_pk_fma_f32 v[76:77], v[80:81], v[80:81], v[76:77]
	v_pk_mul_f32 v[80:81], v[118:119], v[118:119]
	v_pk_mul_f32 v[82:83], v[116:117], v[116:117]
	v_pk_add_f32 v[70:71], v[70:71], v[122:123]
	v_pk_add_f32 v[68:69], v[68:69], v[120:121]
	v_pk_fma_f32 v[72:73], v[72:73], v[72:73], v[82:83]
	v_pk_fma_f32 v[74:75], v[74:75], v[74:75], v[80:81]
	v_pk_add_f32 v[72:73], v[76:77], v[72:73]
	v_pk_add_f32 v[74:75], v[78:79], v[74:75]
	v_add_f32_e32 v68, v68, v69
	v_add_f32_e32 v69, v70, v71
	v_add_f32_e32 v68, v68, v69
	v_add_f32_e32 v69, v72, v73
	v_add_f32_e32 v70, v74, v75
	v_add_f32_e32 v69, v69, v70
	ds_bpermute_b32 v70, v156, v68
	s_waitcnt vmcnt(9)
	v_cvt_f32_i32_e32 v119, v109
	v_cvt_f32_i32_e32 v118, v111
	v_cvt_f32_u32_e32 v109, v108
	v_cvt_f32_u32_e32 v108, v110
	s_waitcnt lgkmcnt(0)
	v_add_f32_e32 v82, v68, v70
	ds_bpermute_b32 v68, v156, v69
	s_waitcnt vmcnt(8)
	v_lshlrev_b32_e32 v110, 16, v104
	v_pk_fma_f32 v[108:109], v[118:119], s[30:31], v[108:109] op_sel_hi:[1,0,1]
	v_and_b32_e32 v104, 0xffff0000, v104
	v_pk_mul_f32 v[108:109], v[108:109], s[90:91] op_sel_hi:[1,0]
	s_waitcnt lgkmcnt(0)
	v_add_f32_e32 v116, v69, v68
	v_add_u32_e32 v68, 0xa0, v188
	v_ashrrev_i32_e32 v69, 31, v68
	v_lshl_add_u64 v[70:71], v[68:69], 4, s[14:15]
	global_load_dwordx4 v[76:79], v[70:71], off
	v_pk_mul_f32 v[108:109], v[108:109], s[92:93] op_sel_hi:[1,0]
	v_lshlrev_b64 v[68:69], 12, v[68:69]
	v_fma_f32 v108, -v109, v109, v108
	v_max_f32_e32 v108, 0, v108
	v_add_f32_e32 v108, 0x3727c5ac, v108
	v_rsq_f32_e32 v108, v108
	v_lshlrev_b32_e32 v118, 16, v105
	v_and_b32_e32 v111, 0xffff0000, v105
	v_sub_f32_e32 v105, v104, v109
	v_sub_f32_e32 v104, v110, v109
	v_lshl_add_u64 v[68:69], s[0:1], 0, v[68:69]
	v_pk_mul_f32 v[104:105], v[104:105], v[108:109] op_sel_hi:[1,0]
	v_lshl_add_u64 v[80:81], v[68:69], 0, v[222:223]
	v_pk_fma_f32 v[104:105], v[192:193], v[104:105], v[204:205]
	global_load_dwordx4 v[72:75], v[80:81], off
	global_load_dwordx4 v[68:71], v[80:81], off offset:64
	v_pk_fma_f32 v[64:65], v[64:65], 0.5, v[104:105] op_sel_hi:[1,0,1]
	v_lshlrev_b32_e32 v104, 16, v106
	v_and_b32_e32 v105, 0xffff0000, v106
	v_lshlrev_b32_e32 v106, 16, v107
	v_and_b32_e32 v107, 0xffff0000, v107
	v_sub_f32_e32 v105, v105, v109
	v_sub_f32_e32 v104, v104, v109
	v_sub_f32_e32 v107, v107, v109
	v_sub_f32_e32 v106, v106, v109
	v_pk_mul_f32 v[104:105], v[104:105], v[108:109] op_sel_hi:[1,0]
	v_pk_mul_f32 v[106:107], v[106:107], v[108:109] op_sel_hi:[1,0]
	v_pk_fma_f32 v[104:105], v[196:197], v[104:105], v[200:201]
	v_pk_fma_f32 v[106:107], v[194:195], v[106:107], v[198:199]
	v_pk_fma_f32 v[60:61], v[60:61], 0.5, v[104:105] op_sel_hi:[1,0,1]
	s_waitcnt vmcnt(10)
	v_lshlrev_b32_e32 v104, 16, v100
	v_and_b32_e32 v100, 0xffff0000, v100
	v_pk_fma_f32 v[62:63], v[62:63], 0.5, v[106:107] op_sel_hi:[1,0,1]
	v_lshlrev_b32_e32 v106, 16, v101
	v_and_b32_e32 v105, 0xffff0000, v101
	v_sub_f32_e32 v101, v100, v109
	v_sub_f32_e32 v100, v104, v109
	v_pk_mul_f32 v[100:101], v[100:101], v[108:109] op_sel_hi:[1,0]
	v_sub_f32_e32 v111, v111, v109
	v_pk_fma_f32 v[100:101], v[208:209], v[100:101], v[220:221]
	v_sub_f32_e32 v110, v118, v109
	v_pk_fma_f32 v[56:57], v[56:57], 0.5, v[100:101] op_sel_hi:[1,0,1]
	v_lshlrev_b32_e32 v100, 16, v102
	v_and_b32_e32 v101, 0xffff0000, v102
	v_lshlrev_b32_e32 v102, 16, v103
	v_and_b32_e32 v103, 0xffff0000, v103
	v_sub_f32_e32 v101, v101, v109
	v_sub_f32_e32 v100, v100, v109
	v_sub_f32_e32 v103, v103, v109
	v_sub_f32_e32 v102, v102, v109
	v_pk_mul_f32 v[110:111], v[110:111], v[108:109] op_sel_hi:[1,0]
	v_sub_f32_e32 v105, v105, v109
	v_sub_f32_e32 v104, v106, v109
	v_pk_mul_f32 v[102:103], v[102:103], v[108:109] op_sel_hi:[1,0]
	v_pk_mul_f32 v[100:101], v[100:101], v[108:109] op_sel_hi:[1,0]
	v_pk_fma_f32 v[110:111], v[190:191], v[110:111], v[202:203]
	v_pk_mul_f32 v[104:105], v[104:105], v[108:109] op_sel_hi:[1,0]
	v_pk_fma_f32 v[100:101], v[212:213], v[100:101], v[216:217]
	v_pk_fma_f32 v[102:103], v[210:211], v[102:103], v[214:215]
	v_pk_fma_f32 v[66:67], v[66:67], 0.5, v[110:111] op_sel_hi:[1,0,1]
	v_pk_fma_f32 v[104:105], v[206:207], v[104:105], v[218:219]
	v_pk_fma_f32 v[102:103], v[54:55], 0.5, v[102:103] op_sel_hi:[1,0,1]
	v_pk_fma_f32 v[100:101], v[52:53], 0.5, v[100:101] op_sel_hi:[1,0,1]
	v_cvt_pk_bf16_f32 v52, v64, v65
	v_cvt_pk_bf16_f32 v53, v66, v67
	v_cvt_pk_bf16_f32 v54, v60, v61
	v_cvt_pk_bf16_f32 v55, v62, v63
	v_pk_fma_f32 v[58:59], v[58:59], 0.5, v[104:105] op_sel_hi:[1,0,1]
	global_store_dwordx4 v[114:115], v[52:55], off
	v_pk_add_f32 v[104:105], v[56:57], v[100:101]
	v_pk_add_f32 v[106:107], v[58:59], v[102:103]
	v_cvt_pk_bf16_f32 v52, v56, v57
	v_cvt_pk_bf16_f32 v53, v58, v59
	v_cvt_pk_bf16_f32 v54, v100, v101
	v_cvt_pk_bf16_f32 v55, v102, v103
	global_store_dwordx4 v[114:115], v[52:55], off offset:64
	ds_bpermute_b32 v117, v158, v116
	ds_bpermute_b32 v99, v158, v98
	v_pk_add_f32 v[52:53], v[64:65], v[60:61]
	v_pk_add_f32 v[54:55], v[66:67], v[62:63]
	v_pk_mul_f32 v[62:63], v[62:63], v[62:63]
	v_pk_mul_f32 v[60:61], v[60:61], v[60:61]
	v_pk_fma_f32 v[62:63], v[66:67], v[66:67], v[62:63]
	v_pk_fma_f32 v[60:61], v[64:65], v[64:65], v[60:61]
	v_pk_mul_f32 v[64:65], v[102:103], v[102:103]
	v_pk_mul_f32 v[66:67], v[100:101], v[100:101]
	v_pk_add_f32 v[54:55], v[54:55], v[106:107]
	v_pk_add_f32 v[52:53], v[52:53], v[104:105]
	v_pk_fma_f32 v[56:57], v[56:57], v[56:57], v[66:67]
	v_pk_fma_f32 v[58:59], v[58:59], v[58:59], v[64:65]
	v_pk_add_f32 v[56:57], v[60:61], v[56:57]
	v_pk_add_f32 v[58:59], v[62:63], v[58:59]
	v_add_f32_e32 v52, v52, v53
	v_add_f32_e32 v53, v54, v55
	v_add_f32_e32 v52, v52, v53
	v_add_f32_e32 v53, v56, v57
	v_add_f32_e32 v54, v58, v59
	v_add_f32_e32 v53, v53, v54
	ds_bpermute_b32 v54, v156, v52
	s_waitcnt vmcnt(9)
	v_cvt_f32_i32_e32 v103, v93
	v_cvt_f32_i32_e32 v102, v95
	v_cvt_f32_u32_e32 v93, v92
	v_cvt_f32_u32_e32 v92, v94
	s_waitcnt lgkmcnt(0)
	v_add_f32_e32 v66, v52, v54
	ds_bpermute_b32 v52, v156, v53
	s_waitcnt vmcnt(8)
	v_lshlrev_b32_e32 v94, 16, v88
	v_pk_fma_f32 v[92:93], v[102:103], s[30:31], v[92:93] op_sel_hi:[1,0,1]
	v_and_b32_e32 v88, 0xffff0000, v88
	v_pk_mul_f32 v[92:93], v[92:93], s[90:91] op_sel_hi:[1,0]
	s_waitcnt lgkmcnt(0)
	v_add_f32_e32 v100, v53, v52
	v_add_u32_e32 v52, 0xb0, v188
	v_ashrrev_i32_e32 v53, 31, v52
	v_lshl_add_u64 v[54:55], v[52:53], 4, s[14:15]
	global_load_dwordx4 v[60:63], v[54:55], off
	v_pk_mul_f32 v[92:93], v[92:93], s[92:93] op_sel_hi:[1,0]
	v_lshlrev_b32_e32 v102, 16, v89
	v_fma_f32 v92, -v93, v93, v92
	v_max_f32_e32 v92, 0, v92
	v_add_f32_e32 v92, 0x3727c5ac, v92
	v_rsq_f32_e32 v92, v92
	v_and_b32_e32 v95, 0xffff0000, v89
	v_sub_f32_e32 v89, v88, v93
	v_sub_f32_e32 v88, v94, v93
	v_pk_mul_f32 v[88:89], v[88:89], v[92:93] op_sel_hi:[1,0]
	v_lshlrev_b64 v[52:53], 12, v[52:53]
	v_pk_fma_f32 v[88:89], v[192:193], v[88:89], v[204:205]
	v_lshl_add_u64 v[52:53], s[0:1], 0, v[52:53]
	v_pk_fma_f32 v[48:49], v[48:49], 0.5, v[88:89] op_sel_hi:[1,0,1]
	v_lshlrev_b32_e32 v88, 16, v90
	v_and_b32_e32 v89, 0xffff0000, v90
	v_lshlrev_b32_e32 v90, 16, v91
	v_and_b32_e32 v91, 0xffff0000, v91
	v_sub_f32_e32 v89, v89, v93
	v_sub_f32_e32 v88, v88, v93
	v_lshl_add_u64 v[64:65], v[52:53], 0, v[222:223]
	v_sub_f32_e32 v91, v91, v93
	v_sub_f32_e32 v90, v90, v93
	v_pk_mul_f32 v[88:89], v[88:89], v[92:93] op_sel_hi:[1,0]
	global_load_dwordx4 v[56:59], v[64:65], off
	global_load_dwordx4 v[52:55], v[64:65], off offset:64
	v_pk_mul_f32 v[90:91], v[90:91], v[92:93] op_sel_hi:[1,0]
	v_pk_fma_f32 v[88:89], v[196:197], v[88:89], v[200:201]
	v_pk_fma_f32 v[90:91], v[194:195], v[90:91], v[198:199]
	v_pk_fma_f32 v[44:45], v[44:45], 0.5, v[88:89] op_sel_hi:[1,0,1]
	s_waitcnt vmcnt(10)
	v_lshlrev_b32_e32 v88, 16, v84
	v_and_b32_e32 v84, 0xffff0000, v84
	v_pk_fma_f32 v[46:47], v[46:47], 0.5, v[90:91] op_sel_hi:[1,0,1]
	v_lshlrev_b32_e32 v90, 16, v85
	v_and_b32_e32 v89, 0xffff0000, v85
	v_sub_f32_e32 v85, v84, v93
	v_sub_f32_e32 v84, v88, v93
	v_pk_mul_f32 v[84:85], v[84:85], v[92:93] op_sel_hi:[1,0]
	v_sub_f32_e32 v95, v95, v93
	v_pk_fma_f32 v[84:85], v[208:209], v[84:85], v[220:221]
	v_sub_f32_e32 v94, v102, v93
	v_pk_fma_f32 v[40:41], v[40:41], 0.5, v[84:85] op_sel_hi:[1,0,1]
	v_lshlrev_b32_e32 v84, 16, v86
	v_and_b32_e32 v85, 0xffff0000, v86
	v_lshlrev_b32_e32 v86, 16, v87
	v_and_b32_e32 v87, 0xffff0000, v87
	v_sub_f32_e32 v85, v85, v93
	v_sub_f32_e32 v84, v84, v93
	v_sub_f32_e32 v87, v87, v93
	v_sub_f32_e32 v86, v86, v93
	v_pk_mul_f32 v[94:95], v[94:95], v[92:93] op_sel_hi:[1,0]
	v_sub_f32_e32 v89, v89, v93
	v_sub_f32_e32 v88, v90, v93
	v_pk_mul_f32 v[86:87], v[86:87], v[92:93] op_sel_hi:[1,0]
	v_pk_mul_f32 v[84:85], v[84:85], v[92:93] op_sel_hi:[1,0]
	v_pk_fma_f32 v[94:95], v[190:191], v[94:95], v[202:203]
	v_pk_mul_f32 v[88:89], v[88:89], v[92:93] op_sel_hi:[1,0]
	v_pk_fma_f32 v[84:85], v[212:213], v[84:85], v[216:217]
	v_pk_fma_f32 v[86:87], v[210:211], v[86:87], v[214:215]
	v_pk_fma_f32 v[50:51], v[50:51], 0.5, v[94:95] op_sel_hi:[1,0,1]
	v_pk_fma_f32 v[88:89], v[206:207], v[88:89], v[218:219]
	v_pk_fma_f32 v[86:87], v[38:39], 0.5, v[86:87] op_sel_hi:[1,0,1]
	v_pk_fma_f32 v[84:85], v[36:37], 0.5, v[84:85] op_sel_hi:[1,0,1]
	v_cvt_pk_bf16_f32 v36, v48, v49
	v_cvt_pk_bf16_f32 v37, v50, v51
	v_cvt_pk_bf16_f32 v38, v44, v45
	v_cvt_pk_bf16_f32 v39, v46, v47
	v_pk_fma_f32 v[42:43], v[42:43], 0.5, v[88:89] op_sel_hi:[1,0,1]
	global_store_dwordx4 v[96:97], v[36:39], off
	v_pk_add_f32 v[88:89], v[40:41], v[84:85]
	v_pk_add_f32 v[90:91], v[42:43], v[86:87]
	v_cvt_pk_bf16_f32 v36, v40, v41
	v_cvt_pk_bf16_f32 v37, v42, v43
	v_cvt_pk_bf16_f32 v38, v84, v85
	v_cvt_pk_bf16_f32 v39, v86, v87
	global_store_dwordx4 v[96:97], v[36:39], off offset:64
	ds_bpermute_b32 v101, v158, v100
	ds_bpermute_b32 v67, v158, v66
	v_pk_add_f32 v[36:37], v[48:49], v[44:45]
	v_pk_add_f32 v[38:39], v[50:51], v[46:47]
	v_pk_mul_f32 v[46:47], v[46:47], v[46:47]
	v_pk_mul_f32 v[44:45], v[44:45], v[44:45]
	v_pk_fma_f32 v[46:47], v[50:51], v[50:51], v[46:47]
	v_pk_fma_f32 v[44:45], v[48:49], v[48:49], v[44:45]
	v_pk_mul_f32 v[48:49], v[86:87], v[86:87]
	v_pk_mul_f32 v[50:51], v[84:85], v[84:85]
	v_pk_add_f32 v[38:39], v[38:39], v[90:91]
	v_pk_add_f32 v[36:37], v[36:37], v[88:89]
	v_pk_fma_f32 v[40:41], v[40:41], v[40:41], v[50:51]
	v_pk_fma_f32 v[42:43], v[42:43], v[42:43], v[48:49]
	v_pk_add_f32 v[40:41], v[44:45], v[40:41]
	v_pk_add_f32 v[42:43], v[46:47], v[42:43]
	v_add_f32_e32 v36, v36, v37
	v_add_f32_e32 v37, v38, v39
	v_add_f32_e32 v36, v36, v37
	v_add_f32_e32 v37, v40, v41
	v_add_f32_e32 v38, v42, v43
	v_add_f32_e32 v38, v37, v38
	ds_bpermute_b32 v39, v156, v38
	s_waitcnt vmcnt(9)
	v_cvt_f32_u32_e32 v41, v76
	v_cvt_f32_u32_e32 v40, v78
	s_waitcnt vmcnt(8)
	v_lshlrev_b32_e32 v42, 16, v73
	v_and_b32_e32 v43, 0xffff0000, v73
	s_waitcnt lgkmcnt(0)
	v_add_f32_e32 v46, v38, v39
	v_cvt_f32_i32_e32 v39, v77
	v_cvt_f32_i32_e32 v38, v79
	ds_bpermute_b32 v37, v156, v36
	ds_bpermute_b32 v47, v158, v46
	ds_bpermute_b32 v83, v158, v82
	v_pk_fma_f32 v[38:39], v[38:39], s[30:31], v[40:41] op_sel_hi:[1,0,1]
	v_lshlrev_b32_e32 v40, 16, v72
	v_pk_mul_f32 v[38:39], v[38:39], s[90:91] op_sel_hi:[1,0]
	v_and_b32_e32 v41, 0xffff0000, v72
	v_pk_mul_f32 v[38:39], v[38:39], s[92:93] op_sel_hi:[1,0]
	s_waitcnt lgkmcnt(2)
	v_add_f32_e32 v36, v36, v37
	v_fma_f32 v38, -v39, v39, v38
	v_max_f32_e32 v38, 0, v38
	v_add_f32_e32 v38, 0x3727c5ac, v38
	v_rsq_f32_e32 v38, v38
	v_sub_f32_e32 v41, v41, v39
	v_sub_f32_e32 v40, v40, v39
	v_sub_f32_e32 v43, v43, v39
	v_sub_f32_e32 v42, v42, v39
	v_pk_mul_f32 v[42:43], v[42:43], v[38:39] op_sel_hi:[1,0]
	v_pk_mul_f32 v[40:41], v[40:41], v[38:39] op_sel_hi:[1,0]
	v_pk_fma_f32 v[42:43], v[190:191], v[42:43], v[202:203]
	v_pk_fma_f32 v[40:41], v[192:193], v[40:41], v[204:205]
	v_pk_fma_f32 v[34:35], v[34:35], 0.5, v[42:43] op_sel_hi:[1,0,1]
	v_pk_fma_f32 v[32:33], v[32:33], 0.5, v[40:41] op_sel_hi:[1,0,1]
	v_lshlrev_b32_e32 v40, 16, v74
	v_and_b32_e32 v41, 0xffff0000, v74
	v_lshlrev_b32_e32 v42, 16, v75
	v_and_b32_e32 v43, 0xffff0000, v75
	v_sub_f32_e32 v41, v41, v39
	v_sub_f32_e32 v40, v40, v39
	v_sub_f32_e32 v43, v43, v39
	v_sub_f32_e32 v42, v42, v39
	v_pk_mul_f32 v[42:43], v[42:43], v[38:39] op_sel_hi:[1,0]
	v_pk_mul_f32 v[40:41], v[40:41], v[38:39] op_sel_hi:[1,0]
	v_pk_fma_f32 v[42:43], v[194:195], v[42:43], v[198:199]
	v_pk_fma_f32 v[40:41], v[196:197], v[40:41], v[200:201]
	v_pk_fma_f32 v[30:31], v[30:31], 0.5, v[42:43] op_sel_hi:[1,0,1]
	v_pk_fma_f32 v[28:29], v[28:29], 0.5, v[40:41] op_sel_hi:[1,0,1]
	s_waitcnt vmcnt(7)
	v_lshlrev_b32_e32 v40, 16, v68
	v_and_b32_e32 v41, 0xffff0000, v68
	v_lshlrev_b32_e32 v42, 16, v69
	v_and_b32_e32 v43, 0xffff0000, v69
	v_sub_f32_e32 v41, v41, v39
	v_sub_f32_e32 v40, v40, v39
	v_sub_f32_e32 v43, v43, v39
	v_sub_f32_e32 v42, v42, v39
	v_pk_mul_f32 v[42:43], v[42:43], v[38:39] op_sel_hi:[1,0]
	v_pk_mul_f32 v[40:41], v[40:41], v[38:39] op_sel_hi:[1,0]
	v_pk_fma_f32 v[42:43], v[206:207], v[42:43], v[218:219]
	v_pk_fma_f32 v[40:41], v[208:209], v[40:41], v[220:221]
	v_pk_fma_f32 v[26:27], v[26:27], 0.5, v[42:43] op_sel_hi:[1,0,1]
	v_pk_fma_f32 v[24:25], v[24:25], 0.5, v[40:41] op_sel_hi:[1,0,1]
	v_lshlrev_b32_e32 v40, 16, v70
	v_and_b32_e32 v41, 0xffff0000, v70
	v_lshlrev_b32_e32 v42, 16, v71
	v_and_b32_e32 v43, 0xffff0000, v71
	v_sub_f32_e32 v41, v41, v39
	v_sub_f32_e32 v40, v40, v39
	v_sub_f32_e32 v43, v43, v39
	v_sub_f32_e32 v42, v42, v39
	v_pk_mul_f32 v[42:43], v[42:43], v[38:39] op_sel_hi:[1,0]
	v_pk_mul_f32 v[38:39], v[40:41], v[38:39] op_sel_hi:[1,0]
	v_pk_fma_f32 v[40:41], v[210:211], v[42:43], v[214:215]
	v_pk_fma_f32 v[38:39], v[212:213], v[38:39], v[216:217]
	v_pk_fma_f32 v[40:41], v[22:23], 0.5, v[40:41] op_sel_hi:[1,0,1]
	v_pk_fma_f32 v[38:39], v[20:21], 0.5, v[38:39] op_sel_hi:[1,0,1]
	v_cvt_pk_bf16_f32 v20, v32, v33
	v_cvt_pk_bf16_f32 v21, v34, v35
	v_cvt_pk_bf16_f32 v22, v28, v29
	v_cvt_pk_bf16_f32 v23, v30, v31
	global_store_dwordx4 v[80:81], v[20:23], off
	v_pk_add_f32 v[42:43], v[24:25], v[38:39]
	v_pk_add_f32 v[44:45], v[26:27], v[40:41]
	v_cvt_pk_bf16_f32 v20, v24, v25
	v_cvt_pk_bf16_f32 v21, v26, v27
	v_cvt_pk_bf16_f32 v22, v38, v39
	v_cvt_pk_bf16_f32 v23, v40, v41
	global_store_dwordx4 v[80:81], v[20:23], off offset:64
	ds_bpermute_b32 v37, v158, v36
	s_nop 0
	v_pk_add_f32 v[20:21], v[32:33], v[28:29]
	v_pk_add_f32 v[22:23], v[34:35], v[30:31]
	v_pk_mul_f32 v[30:31], v[30:31], v[30:31]
	v_pk_mul_f32 v[28:29], v[28:29], v[28:29]
	v_pk_fma_f32 v[30:31], v[34:35], v[34:35], v[30:31]
	v_pk_fma_f32 v[28:29], v[32:33], v[32:33], v[28:29]
	v_pk_mul_f32 v[32:33], v[40:41], v[40:41]
	v_pk_mul_f32 v[34:35], v[38:39], v[38:39]
	v_pk_add_f32 v[22:23], v[22:23], v[44:45]
	v_pk_add_f32 v[20:21], v[20:21], v[42:43]
	v_pk_fma_f32 v[24:25], v[24:25], v[24:25], v[34:35]
	v_pk_fma_f32 v[26:27], v[26:27], v[26:27], v[32:33]
	v_pk_add_f32 v[24:25], v[28:29], v[24:25]
	v_pk_add_f32 v[26:27], v[30:31], v[26:27]
	v_add_f32_e32 v20, v20, v21
	v_add_f32_e32 v21, v22, v23
	v_add_f32_e32 v20, v20, v21
	v_add_f32_e32 v21, v24, v25
	v_add_f32_e32 v22, v26, v27
	v_add_f32_e32 v21, v21, v22
	ds_bpermute_b32 v22, v156, v20
	s_waitcnt vmcnt(6)
	v_cvt_f32_u32_e32 v23, v60
	s_waitcnt vmcnt(5)
	v_lshlrev_b32_e32 v24, 16, v57
	v_and_b32_e32 v25, 0xffff0000, v57
	s_waitcnt lgkmcnt(0)
	v_add_f32_e32 v28, v20, v22
	ds_bpermute_b32 v20, v156, v21
	v_cvt_f32_u32_e32 v22, v62
	ds_bpermute_b32 v29, v158, v28
	s_waitcnt lgkmcnt(1)
	v_add_f32_e32 v30, v21, v20
	v_cvt_f32_i32_e32 v21, v61
	v_cvt_f32_i32_e32 v20, v63
	ds_bpermute_b32 v31, v158, v30
	v_pk_fma_f32 v[20:21], v[20:21], s[30:31], v[22:23] op_sel_hi:[1,0,1]
	s_nop 0
	v_pk_mul_f32 v[20:21], v[20:21], s[90:91] op_sel_hi:[1,0]
	v_lshlrev_b32_e32 v22, 16, v56
	v_pk_mul_f32 v[20:21], v[20:21], s[92:93] op_sel_hi:[1,0]
	v_and_b32_e32 v23, 0xffff0000, v56
	v_fma_f32 v20, -v21, v21, v20
	v_max_f32_e32 v20, 0, v20
	v_add_f32_e32 v20, 0x3727c5ac, v20
	v_rsq_f32_e32 v20, v20
	v_sub_f32_e32 v23, v23, v21
	v_sub_f32_e32 v22, v22, v21
	v_sub_f32_e32 v25, v25, v21
	v_sub_f32_e32 v24, v24, v21
	v_pk_mul_f32 v[24:25], v[24:25], v[20:21] op_sel_hi:[1,0]
	v_pk_mul_f32 v[22:23], v[22:23], v[20:21] op_sel_hi:[1,0]
	v_pk_fma_f32 v[24:25], v[190:191], v[24:25], v[202:203]
	v_pk_fma_f32 v[22:23], v[192:193], v[22:23], v[204:205]
	v_pk_fma_f32 v[18:19], v[18:19], 0.5, v[24:25] op_sel_hi:[1,0,1]
	v_pk_fma_f32 v[16:17], v[16:17], 0.5, v[22:23] op_sel_hi:[1,0,1]
	v_lshlrev_b32_e32 v22, 16, v58
	v_and_b32_e32 v23, 0xffff0000, v58
	v_lshlrev_b32_e32 v24, 16, v59
	v_and_b32_e32 v25, 0xffff0000, v59
	v_sub_f32_e32 v23, v23, v21
	v_sub_f32_e32 v22, v22, v21
	v_sub_f32_e32 v25, v25, v21
	v_sub_f32_e32 v24, v24, v21
	v_pk_mul_f32 v[24:25], v[24:25], v[20:21] op_sel_hi:[1,0]
	v_pk_mul_f32 v[22:23], v[22:23], v[20:21] op_sel_hi:[1,0]
	v_pk_fma_f32 v[24:25], v[194:195], v[24:25], v[198:199]
	v_pk_fma_f32 v[22:23], v[196:197], v[22:23], v[200:201]
	v_pk_fma_f32 v[14:15], v[14:15], 0.5, v[24:25] op_sel_hi:[1,0,1]
	v_pk_fma_f32 v[12:13], v[12:13], 0.5, v[22:23] op_sel_hi:[1,0,1]
	s_waitcnt vmcnt(4)
	v_lshlrev_b32_e32 v22, 16, v52
	v_and_b32_e32 v23, 0xffff0000, v52
	v_lshlrev_b32_e32 v24, 16, v53
	v_and_b32_e32 v25, 0xffff0000, v53
	v_sub_f32_e32 v23, v23, v21
	v_sub_f32_e32 v22, v22, v21
	v_sub_f32_e32 v25, v25, v21
	v_sub_f32_e32 v24, v24, v21
	v_pk_mul_f32 v[24:25], v[24:25], v[20:21] op_sel_hi:[1,0]
	v_pk_mul_f32 v[22:23], v[22:23], v[20:21] op_sel_hi:[1,0]
	v_pk_fma_f32 v[24:25], v[206:207], v[24:25], v[218:219]
	v_pk_fma_f32 v[22:23], v[208:209], v[22:23], v[220:221]
	v_pk_fma_f32 v[10:11], v[10:11], 0.5, v[24:25] op_sel_hi:[1,0,1]
	v_pk_fma_f32 v[8:9], v[8:9], 0.5, v[22:23] op_sel_hi:[1,0,1]
	v_lshlrev_b32_e32 v22, 16, v54
	v_and_b32_e32 v23, 0xffff0000, v54
	v_lshlrev_b32_e32 v24, 16, v55
	v_and_b32_e32 v25, 0xffff0000, v55
	v_sub_f32_e32 v23, v23, v21
	v_sub_f32_e32 v22, v22, v21
	v_sub_f32_e32 v25, v25, v21
	v_sub_f32_e32 v24, v24, v21
	v_pk_mul_f32 v[24:25], v[24:25], v[20:21] op_sel_hi:[1,0]
	v_pk_mul_f32 v[20:21], v[22:23], v[20:21] op_sel_hi:[1,0]
	v_pk_fma_f32 v[22:23], v[210:211], v[24:25], v[214:215]
	v_pk_fma_f32 v[20:21], v[212:213], v[20:21], v[216:217]
	v_pk_fma_f32 v[22:23], v[6:7], 0.5, v[22:23] op_sel_hi:[1,0,1]
	v_pk_fma_f32 v[20:21], v[4:5], 0.5, v[20:21] op_sel_hi:[1,0,1]
	v_cvt_pk_bf16_f32 v4, v16, v17
	v_cvt_pk_bf16_f32 v5, v18, v19
	v_cvt_pk_bf16_f32 v6, v12, v13
	v_cvt_pk_bf16_f32 v7, v14, v15
	global_store_dwordx4 v[64:65], v[4:7], off
	v_pk_add_f32 v[24:25], v[8:9], v[20:21]
	v_pk_add_f32 v[26:27], v[10:11], v[22:23]
	v_cvt_pk_bf16_f32 v4, v8, v9
	v_cvt_pk_bf16_f32 v5, v10, v11
	v_cvt_pk_bf16_f32 v6, v20, v21
	v_cvt_pk_bf16_f32 v7, v22, v23
	global_store_dwordx4 v[64:65], v[4:7], off offset:64
	s_nop 1
	v_pk_add_f32 v[4:5], v[16:17], v[12:13]
	v_pk_add_f32 v[6:7], v[18:19], v[14:15]
	v_pk_mul_f32 v[14:15], v[14:15], v[14:15]
	v_pk_mul_f32 v[12:13], v[12:13], v[12:13]
	v_pk_fma_f32 v[14:15], v[18:19], v[18:19], v[14:15]
	v_pk_fma_f32 v[12:13], v[16:17], v[16:17], v[12:13]
	v_pk_mul_f32 v[16:17], v[22:23], v[22:23]
	v_pk_mul_f32 v[18:19], v[20:21], v[20:21]
	v_pk_add_f32 v[6:7], v[6:7], v[26:27]
	v_pk_add_f32 v[4:5], v[4:5], v[24:25]
	v_pk_fma_f32 v[8:9], v[8:9], v[8:9], v[18:19]
	v_pk_fma_f32 v[10:11], v[10:11], v[10:11], v[16:17]
	v_pk_add_f32 v[8:9], v[12:13], v[8:9]
	v_pk_add_f32 v[10:11], v[14:15], v[10:11]
	v_add_f32_e32 v4, v4, v5
	v_add_f32_e32 v5, v6, v7
	v_add_f32_e32 v4, v4, v5
	v_add_f32_e32 v5, v8, v9
	v_add_f32_e32 v6, v10, v11
	v_add_f32_e32 v5, v5, v6
	ds_bpermute_b32 v7, v156, v5
	ds_bpermute_b32 v6, v156, v4
	v_add_f32_e32 v9, v100, v101
	v_add_f32_e32 v8, v46, v47
	v_cndmask_b32_e64 v9, 0, v9, s[42:43]
	s_waitcnt lgkmcnt(1)
	v_add_f32_e32 v5, v5, v7
	ds_bpermute_b32 v7, v158, v5
	s_waitcnt lgkmcnt(1)
	v_add_f32_e32 v4, v4, v6
	ds_bpermute_b32 v6, v158, v4
	v_cndmask_b32_e64 v8, v9, v8, s[40:41]
	s_waitcnt lgkmcnt(1)
	v_add_f32_e32 v5, v5, v7
	v_add_f32_e32 v7, v30, v31
	v_cndmask_b32_e64 v7, v8, v7, s[38:39]
	v_cndmask_b32_e64 v10, v7, v5, s[36:37]
	v_add_f32_e32 v7, v66, v67
	s_waitcnt lgkmcnt(0)
	v_add_f32_e32 v4, v4, v6
	v_add_f32_e32 v6, v36, v37
	v_cndmask_b32_e64 v7, 0, v7, s[42:43]
	v_add_f32_e32 v5, v28, v29
	v_cndmask_b32_e64 v6, v7, v6, s[40:41]
	v_add_f32_e32 v7, v157, v159
	v_cndmask_b32_e64 v5, v6, v5, s[38:39]
	v_add_f32_e32 v6, v134, v135
	v_cndmask_b32_e64 v7, 0, v7, s[42:43]
	v_cndmask_b32_e64 v11, v5, v4, s[36:37]
	v_add_f32_e32 v5, v113, v136
	v_cndmask_b32_e64 v6, v7, v6, s[40:41]
	v_add_f32_e32 v7, v130, v131
	v_add_f32_e32 v4, v116, v117
	v_cndmask_b32_e64 v5, v6, v5, s[38:39]
	v_add_f32_e32 v6, v132, v133
	v_cndmask_b32_e64 v7, 0, v7, s[42:43]
	v_cndmask_b32_e64 v12, v5, v4, s[36:37]
	v_add_f32_e32 v5, v98, v99
	v_cndmask_b32_e64 v6, v7, v6, s[40:41]
	v_add_f32_e32 v4, v82, v83
	v_cndmask_b32_e64 v5, v6, v5, s[38:39]
	v_cndmask_b32_e64 v8, v5, v4, s[36:37]
	v_or_b32_e32 v4, v188, v243
	v_or_b32_e32 v6, v112, v243
	v_ashrrev_i32_e32 v5, 31, v4
	v_ashrrev_i32_e32 v7, 31, v6
	v_mul_f32_e32 v8, 0x4b800000, v8
	v_lshl_add_u64 v[4:5], v[4:5], 4, s[16:17]
	v_lshl_add_u64 v[6:7], v[6:7], 4, s[16:17]
	v_rndne_f32_e32 v8, v8
	s_mov_b32 s16, 0x2f800000
	v_mul_f32_e64 v9, |v8|, s16
	v_floor_f32_e32 v9, v9
	s_mov_b32 s17, 0xcf800000
	v_fma_f32 v13, v9, s17, |v8|
	v_cvt_u32_f32_e32 v13, v13
	v_cvt_u32_f32_e32 v9, v9
	v_ashrrev_i32_e32 v14, 31, v8
	v_xor_b32_e32 v8, v13, v14
	v_xor_b32_e32 v9, v9, v14
	v_sub_co_u32_e32 v8, vcc, v8, v14
	s_nop 1
	v_subb_co_u32_e32 v9, vcc, v9, v14, vcc
	global_atomic_add_x2 v[4:5], v[8:9], off
	v_mul_f32_e32 v8, 0x4b800000, v12
	v_rndne_f32_e32 v8, v8
	v_mul_f32_e64 v9, |v8|, s16
	v_floor_f32_e32 v9, v9
	v_fma_f32 v12, v9, s17, |v8|
	v_cvt_u32_f32_e32 v12, v12
	v_cvt_u32_f32_e32 v9, v9
	v_ashrrev_i32_e32 v13, 31, v8
	v_xor_b32_e32 v8, v12, v13
	v_xor_b32_e32 v9, v9, v13
	v_sub_co_u32_e32 v8, vcc, v8, v13
	s_nop 1
	v_subb_co_u32_e32 v9, vcc, v9, v13, vcc
	global_atomic_add_x2 v[4:5], v[8:9], off offset:8
	v_mul_f32_e32 v4, 0x4b800000, v11
	v_rndne_f32_e32 v4, v4
	v_mul_f32_e64 v5, |v4|, s16
	v_floor_f32_e32 v5, v5
	v_fma_f32 v8, v5, s17, |v4|
	v_cvt_u32_f32_e32 v8, v8
	v_cvt_u32_f32_e32 v5, v5
	v_ashrrev_i32_e32 v9, 31, v4
	v_xor_b32_e32 v4, v8, v9
	v_xor_b32_e32 v5, v5, v9
	v_sub_co_u32_e32 v4, vcc, v4, v9
	s_nop 1
	v_subb_co_u32_e32 v5, vcc, v5, v9, vcc
	global_atomic_add_x2 v[6:7], v[4:5], off
	v_mul_f32_e32 v4, 0x4b800000, v10
	v_rndne_f32_e32 v4, v4
	v_mul_f32_e64 v5, |v4|, s16
	v_floor_f32_e32 v5, v5
	v_fma_f32 v8, v5, s17, |v4|
	v_cvt_u32_f32_e32 v8, v8
	v_cvt_u32_f32_e32 v5, v5
	v_ashrrev_i32_e32 v9, 31, v4
	v_xor_b32_e32 v4, v8, v9
	v_xor_b32_e32 v5, v5, v9
	v_sub_co_u32_e32 v4, vcc, v4, v9
	s_nop 1
	v_subb_co_u32_e32 v5, vcc, v5, v9, vcc
	global_atomic_add_x2 v[6:7], v[4:5], off offset:8
	s_and_b64 vcc, exec, s[44:45]
	s_cbranch_vccnz .LBB0_1027
	v_readlane_b32 s16, v252, 2
	v_readlane_b32 s17, v252, 3
	s_andn2_b64 vcc, exec, s[16:17]
	s_cbranch_vccnz .LBB0_1026
	s_barrier
	s_branch .LBB0_1026
